# lever 9 loop-edge edit: K-loop counter/pointer/exit-test block moved in front of the loop-back barrier; in the peeled loops that barrier becomes the loop head and the exit path gets its own copy
# baseline (speedup 1.0000x reference)
; #define PG8_STAGE(bufoff, gbase, voff) do { _Pragma("unroll") for (int _i = 0; _i < 2; ++_i) \
;         __builtin_amdgcn_global_load_lds((const unsigned*)((const char*)(gbase) + (voff)[_i]), (LAS unsigned*)(lds + (bufoff) + ldsw + _i * 8192), 16, 0, 0); } while (0)
; #define PG8_LDA(dst, b, h) do { _Pragma("unroll") for (int m = 0; m < 4; ++m) _Pragma("unroll") for (int k = 0; k < 2; ++k) dst[m][k] = *(const LAS bf16x8*)(lds + PG8_SA(b, h) + aoff + m * 2048 + k * 1024); } while (0)
; #define PG8_LDB(dst, b, h) do { _Pragma("unroll") for (int n = 0; n < 2; ++n) _Pragma("unroll") for (int k = 0; k < 2; ++k) dst[n][k] = *(const LAS bf16x8*)(lds + PG8_SB(b, h) + boff + n * 2048 + k * 1024); } while (0)
; #define PG8_MMA(ai, bj, At, Bt) do { __builtin_amdgcn_s_setprio(1); _Pragma("unroll") for (int m = 0; m < 4; ++m) _Pragma("unroll") for (int n = 0; n < 2; ++n) _Pragma("unroll") for (int k = 0; k < 2; ++k) \
;         acc[ai][bj][m][n] = __builtin_amdgcn_mfma_f32_16x16x32_bf16(Bt[n][k], At[m][k], acc[ai][bj][m][n], 0, 0, 0); __builtin_amdgcn_s_setprio(0); } while (0)
; #define PG8_WAIT_V(n) asm volatile("s_waitcnt vmcnt(" #n ")" ::: "memory")
; #define PG8_WAIT_L(n) asm volatile("s_waitcnt lgkmcnt(" #n ")" ::: "memory")
; #define PG8_BAR __builtin_amdgcn_s_barrier()
; #define PG8_SCHED __builtin_amdgcn_sched_barrier(0)
; template <class Epi, class Sched>
; __device__ __forceinline__ void gemm_phase(LAS unsigned char* lds, const Gemm g, const Sched& S, const Epi& E) {
;     ...
;         const bool has_next = S.next(ui + 1, nxt);
;         const char* nA = has_next ? (const char*)g.A + (size_t)nxt.pm * tstepA + (size_t)nxt.pn * g.a_pn_off * 2 : cA; const char* nB = has_next ? (const char*)g.Bt + (size_t)nxt.pn * tstepB : cB;
;         for (int t = 0; t < nt; t += 2) {
;             const bool last = (t == nt - 2);
;             const char* a1 = cA + (size_t)(t + 1) * kstep;
;             const char* a2 = last ? nA : cA + (size_t)(t + 2) * kstep; const char* b2 = last ? nB : cB + (size_t)(t + 2) * kstep;
;             const char* a3 = a2 + kstep; const char* b3 = b2 + kstep;
;             PG8_LDB(B0, 0, 0); PG8_LDB(B1, 0, 1); PG8_SCHED; PG8_LDA(At, 0, 0); PG8_STAGE(PG8_SA(1, 1), a1 + hstepA, voffA);
;             PG8_WAIT_V(8); PG8_WAIT_L(0); PG8_BAR; PG8_MMA(0, 0, At, B0); PG8_MMA(0, 1, At, B1); PG8_BAR; PG8_SCHED;
.LBB0_231:
	s_ashr_i32 s83, s82, 31
	s_lshl_b64 s[36:37], s[82:83], 19
	s_add_u32 s84, s4, s36
	s_addc_u32 s85, s5, s37
	s_and_b64 s[36:37], s[70:71], exec
	s_cselect_b32 s43, s85, s19
	s_cselect_b32 s48, s84, s18
	s_ashr_i32 s81, s80, 31
	s_lshl_b64 s[36:37], s[80:81], 19
	v_readlane_b32 s12, v248, 5
	s_add_u32 s36, s12, s36
	v_readlane_b32 s12, v248, 6
	s_addc_u32 s37, s12, s37
	s_and_b64 s[86:87], s[70:71], exec
	s_cselect_b32 s49, s37, s21
	s_cselect_b32 s53, s36, s20
	s_add_u32 s18, s18, 0x40080
	s_addc_u32 s19, s19, 0
	s_add_u32 s54, s20, 0x100
	s_addc_u32 s81, s21, 0
	s_mov_b32 s83, -2
	s_add_u32 s20, s18, 0xfffc0080
	s_addc_u32 s21, s19, -1
	s_add_i32 s88, 0, 0x10000
	s_cmp_eq_u32 s83, 12
	s_cselect_b32 s21, s43, s21
	s_cselect_b32 s20, s48, s20
	s_cselect_b32 s87, s49, s81
	s_cselect_b32 s86, s53, s54
	s_add_i32 s90, 0, 0x14000
	s_add_u32 s100, s20, 0x80
	s_addc_u32 s101, s21, 0
	s_add_i32 m0, s9, 0xc000
	s_nop 0
	global_load_lds_dwordx4 v170, s[18:19]
	s_add_i32 m0, s9, 0xe000
	s_nop 0
	global_load_lds_dwordx4 v190, s[18:19]
	ds_read_b128 v[130:133], v246
	ds_read_b128 v[134:137], v246 offset:1024
	ds_read_b128 v[138:141], v246 offset:2048
	ds_read_b128 v[142:145], v246 offset:3072
	ds_read_b128 v[146:149], v246 offset:16384
	ds_read_b128 v[150:153], v246 offset:17408
	ds_read_b128 v[154:157], v246 offset:18432
	ds_read_b128 v[158:161], v246 offset:19456
	ds_read_b128 v[162:165], v222
	ds_read_b128 v[166:169], v222 offset:1024
	ds_read_b128 v[194:197], v222 offset:2048
	ds_read_b128 v[198:201], v222 offset:3072
	ds_read_b128 v[202:205], v222 offset:4096
	ds_read_b128 v[224:227], v222 offset:5120
	ds_read_b128 v[228:231], v222 offset:6144
	ds_read_b128 v[232:235], v222 offset:7168
	s_waitcnt vmcnt(8)
	s_waitcnt lgkmcnt(0)
	s_barrier
	s_waitcnt lgkmcnt(0)
	v_mfma_f32_16x16x32_bf16 v[126:129], v[130:133], v[162:165], 0
	v_mfma_f32_16x16x32_bf16 v[118:121], v[138:141], v[162:165], 0
	v_mfma_f32_16x16x32_bf16 v[110:113], v[130:133], v[194:197], 0
	v_mfma_f32_16x16x32_bf16 v[102:105], v[138:141], v[194:197], 0
	v_mfma_f32_16x16x32_bf16 v[94:97], v[130:133], v[202:205], 0
	v_mfma_f32_16x16x32_bf16 v[86:89], v[138:141], v[202:205], 0
	v_mfma_f32_16x16x32_bf16 v[78:81], v[130:133], v[228:231], 0
	v_mfma_f32_16x16x32_bf16 v[70:73], v[138:141], v[228:231], 0
	v_mfma_f32_16x16x32_bf16 v[126:129], v[134:137], v[166:169], v[126:129]
	v_mfma_f32_16x16x32_bf16 v[118:121], v[142:145], v[166:169], v[118:121]
	v_mfma_f32_16x16x32_bf16 v[110:113], v[134:137], v[198:201], v[110:113]
	v_mfma_f32_16x16x32_bf16 v[102:105], v[142:145], v[198:201], v[102:105]
	v_mfma_f32_16x16x32_bf16 v[94:97], v[134:137], v[224:227], v[94:97]
	v_mfma_f32_16x16x32_bf16 v[86:89], v[142:145], v[224:227], v[86:89]
	v_mfma_f32_16x16x32_bf16 v[78:81], v[134:137], v[232:235], v[78:81]
	v_mfma_f32_16x16x32_bf16 v[70:73], v[142:145], v[232:235], v[70:73]
	v_mfma_f32_16x16x32_bf16 v[122:125], v[146:149], v[162:165], 0
	v_mfma_f32_16x16x32_bf16 v[114:117], v[154:157], v[162:165], 0
	v_mfma_f32_16x16x32_bf16 v[106:109], v[146:149], v[194:197], 0
	v_mfma_f32_16x16x32_bf16 v[98:101], v[154:157], v[194:197], 0
	v_mfma_f32_16x16x32_bf16 v[90:93], v[146:149], v[202:205], 0
	v_mfma_f32_16x16x32_bf16 v[82:85], v[154:157], v[202:205], 0
	v_mfma_f32_16x16x32_bf16 v[74:77], v[146:149], v[228:231], 0
	v_mfma_f32_16x16x32_bf16 v[66:69], v[154:157], v[228:231], 0
	v_mfma_f32_16x16x32_bf16 v[122:125], v[150:153], v[166:169], v[122:125]
	v_mfma_f32_16x16x32_bf16 v[114:117], v[158:161], v[166:169], v[114:117]
	v_mfma_f32_16x16x32_bf16 v[106:109], v[150:153], v[198:201], v[106:109]
	v_mfma_f32_16x16x32_bf16 v[98:101], v[158:161], v[198:201], v[98:101]
	v_mfma_f32_16x16x32_bf16 v[90:93], v[150:153], v[224:227], v[90:93]
	v_mfma_f32_16x16x32_bf16 v[82:85], v[158:161], v[224:227], v[82:85]
	v_mfma_f32_16x16x32_bf16 v[74:77], v[150:153], v[232:235], v[74:77]
	v_mfma_f32_16x16x32_bf16 v[66:69], v[158:161], v[232:235], v[66:69]
	s_barrier
	s_add_i32 s88, s88, s8
	s_mov_b32 m0, s88
	s_nop 0
	global_load_lds_dwordx4 v172, s[86:87]
	s_add_i32 m0, s88, 0x2000
	s_add_u32 s88, s86, 0x40000
	s_addc_u32 s89, s87, 0
	s_add_i32 s90, s90, s8
	global_load_lds_dwordx4 v192, s[86:87]
	s_mov_b32 m0, s90
	s_nop 0
	global_load_lds_dwordx4 v172, s[88:89]
	s_add_i32 m0, s90, 0x2000
	s_nop 0
	global_load_lds_dwordx4 v192, s[88:89]
	s_mov_b32 m0, s9
	s_nop 0
	global_load_lds_dwordx4 v170, s[20:21]
	s_mov_b32 m0, s28
	s_nop 0
	global_load_lds_dwordx4 v190, s[20:21]
	ds_read_b128 v[162:165], v222 offset:16384
	ds_read_b128 v[166:169], v222 offset:17408
	ds_read_b128 v[194:197], v222 offset:18432
	ds_read_b128 v[198:201], v222 offset:19456
	ds_read_b128 v[202:205], v222 offset:20480
	ds_read_b128 v[224:227], v222 offset:21504
	ds_read_b128 v[228:231], v222 offset:22528
	ds_read_b128 v[232:235], v222 offset:23552
	s_waitcnt vmcnt(8)
	s_waitcnt lgkmcnt(0)
	s_barrier
; #define PG8_STAGE(bufoff, gbase, voff) do { _Pragma("unroll") for (int _i = 0; _i < 2; ++_i) \
;         __builtin_amdgcn_global_load_lds((const unsigned*)((const char*)(gbase) + (voff)[_i]), (LAS unsigned*)(lds + (bufoff) + ldsw + _i * 8192), 16, 0, 0); } while (0)
; #define PG8_LDA(dst, b, h) do { _Pragma("unroll") for (int m = 0; m < 4; ++m) _Pragma("unroll") for (int k = 0; k < 2; ++k) dst[m][k] = *(const LAS bf16x8*)(lds + PG8_SA(b, h) + aoff + m * 2048 + k * 1024); } while (0)
; #define PG8_LDB(dst, b, h) do { _Pragma("unroll") for (int n = 0; n < 2; ++n) _Pragma("unroll") for (int k = 0; k < 2; ++k) dst[n][k] = *(const LAS bf16x8*)(lds + PG8_SB(b, h) + boff + n * 2048 + k * 1024); } while (0)
; #define PG8_MMA(ai, bj, At, Bt) do { __builtin_amdgcn_s_setprio(1); _Pragma("unroll") for (int m = 0; m < 4; ++m) _Pragma("unroll") for (int n = 0; n < 2; ++n) _Pragma("unroll") for (int k = 0; k < 2; ++k) \
;         acc[ai][bj][m][n] = __builtin_amdgcn_mfma_f32_16x16x32_bf16(Bt[n][k], At[m][k], acc[ai][bj][m][n], 0, 0, 0); __builtin_amdgcn_s_setprio(0); } while (0)
; #define PG8_WAIT_V(n) asm volatile("s_waitcnt vmcnt(" #n ")" ::: "memory")
; #define PG8_WAIT_L(n) asm volatile("s_waitcnt lgkmcnt(" #n ")" ::: "memory")
; #define PG8_BAR __builtin_amdgcn_s_barrier()
; #define PG8_SCHED __builtin_amdgcn_sched_barrier(0)
; template <class Epi, class Sched>
; __device__ __forceinline__ void gemm_phase(LAS unsigned char* lds, const Gemm g, const Sched& S, const Epi& E) {
;     ...
;             PG8_WAIT_V(8); PG8_WAIT_L(0); PG8_BAR; PG8_MMA(1, 0, At, B0); PG8_MMA(1, 1, At, B1); PG8_BAR; PG8_SCHED;
;             PG8_LDB(B0, 1, 0); PG8_LDB(B1, 1, 1); PG8_SCHED; PG8_LDA(At, 1, 0); PG8_STAGE(PG8_SA(0, 1), a2 + hstepA, voffA);
;             PG8_WAIT_V(8); PG8_WAIT_L(0); PG8_BAR; PG8_MMA(0, 0, At, B0); PG8_MMA(0, 1, At, B1); PG8_BAR; PG8_SCHED;
	s_waitcnt lgkmcnt(0)
	v_mfma_f32_16x16x32_bf16 v[62:65], v[130:133], v[162:165], 0
	v_mfma_f32_16x16x32_bf16 v[54:57], v[138:141], v[162:165], 0
	v_mfma_f32_16x16x32_bf16 v[46:49], v[130:133], v[194:197], 0
	v_mfma_f32_16x16x32_bf16 v[38:41], v[138:141], v[194:197], 0
	v_mfma_f32_16x16x32_bf16 v[30:33], v[130:133], v[202:205], 0
	v_mfma_f32_16x16x32_bf16 v[22:25], v[138:141], v[202:205], 0
	v_mfma_f32_16x16x32_bf16 v[14:17], v[130:133], v[228:231], 0
	v_mfma_f32_16x16x32_bf16 v[6:9], v[138:141], v[228:231], 0
	v_mfma_f32_16x16x32_bf16 v[62:65], v[134:137], v[166:169], v[62:65]
	v_mfma_f32_16x16x32_bf16 v[54:57], v[142:145], v[166:169], v[54:57]
	v_mfma_f32_16x16x32_bf16 v[46:49], v[134:137], v[198:201], v[46:49]
	v_mfma_f32_16x16x32_bf16 v[38:41], v[142:145], v[198:201], v[38:41]
	v_mfma_f32_16x16x32_bf16 v[30:33], v[134:137], v[224:227], v[30:33]
	v_mfma_f32_16x16x32_bf16 v[22:25], v[142:145], v[224:227], v[22:25]
	v_mfma_f32_16x16x32_bf16 v[14:17], v[134:137], v[232:235], v[14:17]
	v_mfma_f32_16x16x32_bf16 v[6:9], v[142:145], v[232:235], v[6:9]
	v_mfma_f32_16x16x32_bf16 v[58:61], v[146:149], v[162:165], 0
	v_mfma_f32_16x16x32_bf16 v[50:53], v[154:157], v[162:165], 0
	v_mfma_f32_16x16x32_bf16 v[42:45], v[146:149], v[194:197], 0
	v_mfma_f32_16x16x32_bf16 v[34:37], v[154:157], v[194:197], 0
	v_mfma_f32_16x16x32_bf16 v[26:29], v[146:149], v[202:205], 0
	v_mfma_f32_16x16x32_bf16 v[18:21], v[154:157], v[202:205], 0
	v_mfma_f32_16x16x32_bf16 v[10:13], v[146:149], v[228:231], 0
	v_mfma_f32_16x16x32_bf16 v[2:5], v[154:157], v[228:231], 0
	v_mfma_f32_16x16x32_bf16 v[58:61], v[150:153], v[166:169], v[58:61]
	v_mfma_f32_16x16x32_bf16 v[50:53], v[158:161], v[166:169], v[50:53]
	v_mfma_f32_16x16x32_bf16 v[42:45], v[150:153], v[198:201], v[42:45]
	v_mfma_f32_16x16x32_bf16 v[34:37], v[158:161], v[198:201], v[34:37]
	v_mfma_f32_16x16x32_bf16 v[26:29], v[150:153], v[224:227], v[26:29]
	v_mfma_f32_16x16x32_bf16 v[18:21], v[158:161], v[224:227], v[18:21]
	v_mfma_f32_16x16x32_bf16 v[10:13], v[150:153], v[232:235], v[10:13]
	v_mfma_f32_16x16x32_bf16 v[2:5], v[158:161], v[232:235], v[2:5]
	s_barrier
	s_add_i32 s88, 0, 0x18000
	s_add_i32 s89, 0, 0x1c000
	s_add_u32 s20, s20, 0x40000
	s_addc_u32 s21, s21, 0
	s_mov_b32 m0, s29
	s_nop 0
	global_load_lds_dwordx4 v170, s[20:21]
	s_mov_b32 m0, s30
	s_nop 0
	global_load_lds_dwordx4 v190, s[20:21]
	ds_read_b128 v[130:133], v246 offset:32768
	ds_read_b128 v[134:137], v246 offset:33792
	ds_read_b128 v[138:141], v246 offset:34816
	ds_read_b128 v[142:145], v246 offset:35840
	ds_read_b128 v[146:149], v246 offset:49152
	ds_read_b128 v[150:153], v246 offset:50176
	ds_read_b128 v[154:157], v246 offset:51200
	ds_read_b128 v[158:161], v246 offset:52224
	ds_read_b128 v[162:165], v222 offset:32768
	ds_read_b128 v[166:169], v222 offset:33792
	ds_read_b128 v[194:197], v222 offset:34816
	ds_read_b128 v[198:201], v222 offset:35840
	ds_read_b128 v[202:205], v222 offset:36864
	ds_read_b128 v[224:227], v222 offset:37888
	ds_read_b128 v[228:231], v222 offset:38912
	ds_read_b128 v[232:235], v222 offset:39936
	s_waitcnt vmcnt(8)
	s_waitcnt lgkmcnt(0)
	s_barrier
	s_waitcnt lgkmcnt(0)
	v_mfma_f32_16x16x32_bf16 v[126:129], v[130:133], v[162:165], v[126:129]
	v_mfma_f32_16x16x32_bf16 v[118:121], v[138:141], v[162:165], v[118:121]
	v_mfma_f32_16x16x32_bf16 v[110:113], v[130:133], v[194:197], v[110:113]
	v_mfma_f32_16x16x32_bf16 v[102:105], v[138:141], v[194:197], v[102:105]
	v_mfma_f32_16x16x32_bf16 v[94:97], v[130:133], v[202:205], v[94:97]
	v_mfma_f32_16x16x32_bf16 v[86:89], v[138:141], v[202:205], v[86:89]
	v_mfma_f32_16x16x32_bf16 v[78:81], v[130:133], v[228:231], v[78:81]
	v_mfma_f32_16x16x32_bf16 v[70:73], v[138:141], v[228:231], v[70:73]
	v_mfma_f32_16x16x32_bf16 v[126:129], v[134:137], v[166:169], v[126:129]
	v_mfma_f32_16x16x32_bf16 v[118:121], v[142:145], v[166:169], v[118:121]
	v_mfma_f32_16x16x32_bf16 v[110:113], v[134:137], v[198:201], v[110:113]
	v_mfma_f32_16x16x32_bf16 v[102:105], v[142:145], v[198:201], v[102:105]
	v_mfma_f32_16x16x32_bf16 v[94:97], v[134:137], v[224:227], v[94:97]
	v_mfma_f32_16x16x32_bf16 v[86:89], v[142:145], v[224:227], v[86:89]
	v_mfma_f32_16x16x32_bf16 v[78:81], v[134:137], v[232:235], v[78:81]
	v_mfma_f32_16x16x32_bf16 v[70:73], v[142:145], v[232:235], v[70:73]
	v_mfma_f32_16x16x32_bf16 v[122:125], v[146:149], v[162:165], v[122:125]
	v_mfma_f32_16x16x32_bf16 v[114:117], v[154:157], v[162:165], v[114:117]
	v_mfma_f32_16x16x32_bf16 v[106:109], v[146:149], v[194:197], v[106:109]
	v_mfma_f32_16x16x32_bf16 v[98:101], v[154:157], v[194:197], v[98:101]
	v_mfma_f32_16x16x32_bf16 v[90:93], v[146:149], v[202:205], v[90:93]
	v_mfma_f32_16x16x32_bf16 v[82:85], v[154:157], v[202:205], v[82:85]
	v_mfma_f32_16x16x32_bf16 v[74:77], v[146:149], v[228:231], v[74:77]
	v_mfma_f32_16x16x32_bf16 v[66:69], v[154:157], v[228:231], v[66:69]
	v_mfma_f32_16x16x32_bf16 v[122:125], v[150:153], v[166:169], v[122:125]
	v_mfma_f32_16x16x32_bf16 v[114:117], v[158:161], v[166:169], v[114:117]
	v_mfma_f32_16x16x32_bf16 v[106:109], v[150:153], v[198:201], v[106:109]
	v_mfma_f32_16x16x32_bf16 v[98:101], v[158:161], v[198:201], v[98:101]
	v_mfma_f32_16x16x32_bf16 v[90:93], v[150:153], v[224:227], v[90:93]
	v_mfma_f32_16x16x32_bf16 v[82:85], v[158:161], v[224:227], v[82:85]
	v_mfma_f32_16x16x32_bf16 v[74:77], v[150:153], v[232:235], v[74:77]
	v_mfma_f32_16x16x32_bf16 v[66:69], v[158:161], v[232:235], v[66:69]
	s_barrier
; #define PG8_STAGE(bufoff, gbase, voff) do { _Pragma("unroll") for (int _i = 0; _i < 2; ++_i) \
;         __builtin_amdgcn_global_load_lds((const unsigned*)((const char*)(gbase) + (voff)[_i]), (LAS unsigned*)(lds + (bufoff) + ldsw + _i * 8192), 16, 0, 0); } while (0)
; #define PG8_LDA(dst, b, h) do { _Pragma("unroll") for (int m = 0; m < 4; ++m) _Pragma("unroll") for (int k = 0; k < 2; ++k) dst[m][k] = *(const LAS bf16x8*)(lds + PG8_SA(b, h) + aoff + m * 2048 + k * 1024); } while (0)
; #define PG8_LDB(dst, b, h) do { _Pragma("unroll") for (int n = 0; n < 2; ++n) _Pragma("unroll") for (int k = 0; k < 2; ++k) dst[n][k] = *(const LAS bf16x8*)(lds + PG8_SB(b, h) + boff + n * 2048 + k * 1024); } while (0)
; #define PG8_WAIT_V(n) asm volatile("s_waitcnt vmcnt(" #n ")" ::: "memory")
; #define PG8_BAR __builtin_amdgcn_s_barrier()
; template <class Epi, class Sched>
; __device__ __forceinline__ void gemm_phase(LAS unsigned char* lds, const Gemm g, const Sched& S, const Epi& E) {
;     ...
;         for (int t = 0; t < nt; t += 2) {
;             const bool last = (t == nt - 2);
;             const char* a1 = cA + (size_t)(t + 1) * kstep;
;             const char* a2 = last ? nA : cA + (size_t)(t + 2) * kstep; const char* b2 = last ? nB : cB + (size_t)(t + 2) * kstep;
;             const char* a3 = a2 + kstep; const char* b3 = b2 + kstep;
;             PG8_LDB(B0, 0, 0); PG8_LDB(B1, 0, 1); PG8_SCHED; PG8_LDA(At, 0, 0); PG8_STAGE(PG8_SA(1, 1), a1 + hstepA, voffA);
;             PG8_WAIT_V(8); PG8_WAIT_L(0); PG8_BAR; PG8_MMA(0, 0, At, B0); PG8_MMA(0, 1, At, B1); PG8_BAR; PG8_SCHED;
;             PG8_LDA(At, 0, 1); PG8_STAGE(PG8_SB(0, 0), b2, voffB); PG8_STAGE(PG8_SB(0, 1), b2 + hstepB, voffB); PG8_STAGE(PG8_SA(0, 0), a2, voffA);
;             PG8_WAIT_V(8); PG8_WAIT_L(0); PG8_BAR; PG8_MMA(1, 0, At, B0); PG8_MMA(1, 1, At, B1); PG8_BAR; PG8_SCHED;
;             PG8_LDB(B0, 1, 0); PG8_LDB(B1, 1, 1); PG8_SCHED; PG8_LDA(At, 1, 0); PG8_STAGE(PG8_SA(0, 1), a2 + hstepA, voffA);
;             PG8_WAIT_V(8); PG8_WAIT_L(0); PG8_BAR; PG8_MMA(0, 0, At, B0); PG8_MMA(0, 1, At, B1); PG8_BAR; PG8_SCHED;
;             PG8_LDA(At, 1, 1); PG8_STAGE(PG8_SB(1, 0), b3, voffB); PG8_STAGE(PG8_SB(1, 1), b3 + hstepB, voffB); PG8_STAGE(PG8_SA(1, 0), a3, voffA);
;             PG8_WAIT_V(8); PG8_WAIT_L(0); PG8_BAR; PG8_MMA(1, 0, At, B0); PG8_MMA(1, 1, At, B1); PG8_BAR; PG8_SCHED;
	s_add_i32 s20, s8, 0x18000
	s_add_u32 s88, s86, 0x80
	s_addc_u32 s89, s87, 0
	s_mov_b32 m0, s20
	s_nop 0
	global_load_lds_dwordx4 v172, s[88:89]
	s_add_i32 m0, s20, 0x2000
	s_add_u32 s20, s86, 0x40080
	s_addc_u32 s21, s87, 0
	s_add_i32 s12, s8, 0x1c000
	global_load_lds_dwordx4 v192, s[88:89]
	s_mov_b32 m0, s12
	s_nop 0
	global_load_lds_dwordx4 v172, s[20:21]
	s_add_i32 m0, s12, 0x2000
	s_nop 0
	global_load_lds_dwordx4 v192, s[20:21]
	s_mov_b32 m0, s31
	s_nop 0
	global_load_lds_dwordx4 v170, s[100:101]
	s_mov_b32 m0, s34
	s_nop 0
	global_load_lds_dwordx4 v190, s[100:101]
	ds_read_b128 v[162:165], v222 offset:49152
	ds_read_b128 v[166:169], v222 offset:50176
	ds_read_b128 v[194:197], v222 offset:51200
	ds_read_b128 v[198:201], v222 offset:52224
	ds_read_b128 v[202:205], v222 offset:53248
	ds_read_b128 v[224:227], v222 offset:54272
	ds_read_b128 v[228:231], v222 offset:55296
	ds_read_b128 v[232:235], v222 offset:56320
	s_waitcnt vmcnt(8)
	s_waitcnt lgkmcnt(0)
	s_barrier
	s_waitcnt lgkmcnt(0)
	v_mfma_f32_16x16x32_bf16 v[62:65], v[130:133], v[162:165], v[62:65]
	v_mfma_f32_16x16x32_bf16 v[54:57], v[138:141], v[162:165], v[54:57]
	v_mfma_f32_16x16x32_bf16 v[46:49], v[130:133], v[194:197], v[46:49]
	v_mfma_f32_16x16x32_bf16 v[38:41], v[138:141], v[194:197], v[38:41]
	v_mfma_f32_16x16x32_bf16 v[30:33], v[130:133], v[202:205], v[30:33]
	v_mfma_f32_16x16x32_bf16 v[22:25], v[138:141], v[202:205], v[22:25]
	v_mfma_f32_16x16x32_bf16 v[14:17], v[130:133], v[228:231], v[14:17]
	v_mfma_f32_16x16x32_bf16 v[6:9], v[138:141], v[228:231], v[6:9]
	v_mfma_f32_16x16x32_bf16 v[62:65], v[134:137], v[166:169], v[62:65]
	v_mfma_f32_16x16x32_bf16 v[54:57], v[142:145], v[166:169], v[54:57]
	v_mfma_f32_16x16x32_bf16 v[46:49], v[134:137], v[198:201], v[46:49]
	v_mfma_f32_16x16x32_bf16 v[38:41], v[142:145], v[198:201], v[38:41]
	v_mfma_f32_16x16x32_bf16 v[30:33], v[134:137], v[224:227], v[30:33]
	v_mfma_f32_16x16x32_bf16 v[22:25], v[142:145], v[224:227], v[22:25]
	v_mfma_f32_16x16x32_bf16 v[14:17], v[134:137], v[232:235], v[14:17]
	v_mfma_f32_16x16x32_bf16 v[6:9], v[142:145], v[232:235], v[6:9]
	v_mfma_f32_16x16x32_bf16 v[58:61], v[146:149], v[162:165], v[58:61]
	v_mfma_f32_16x16x32_bf16 v[50:53], v[154:157], v[162:165], v[50:53]
	v_mfma_f32_16x16x32_bf16 v[42:45], v[146:149], v[194:197], v[42:45]
	v_mfma_f32_16x16x32_bf16 v[34:37], v[154:157], v[194:197], v[34:37]
	v_mfma_f32_16x16x32_bf16 v[26:29], v[146:149], v[202:205], v[26:29]
	v_mfma_f32_16x16x32_bf16 v[18:21], v[154:157], v[202:205], v[18:21]
	v_mfma_f32_16x16x32_bf16 v[10:13], v[146:149], v[228:231], v[10:13]
	v_mfma_f32_16x16x32_bf16 v[2:5], v[154:157], v[228:231], v[2:5]
	v_mfma_f32_16x16x32_bf16 v[58:61], v[150:153], v[166:169], v[58:61]
	v_mfma_f32_16x16x32_bf16 v[50:53], v[158:161], v[166:169], v[50:53]
	v_mfma_f32_16x16x32_bf16 v[42:45], v[150:153], v[198:201], v[42:45]
	v_mfma_f32_16x16x32_bf16 v[34:37], v[158:161], v[198:201], v[34:37]
	v_mfma_f32_16x16x32_bf16 v[26:29], v[150:153], v[224:227], v[26:29]
	v_mfma_f32_16x16x32_bf16 v[18:21], v[158:161], v[224:227], v[18:21]
	v_mfma_f32_16x16x32_bf16 v[10:13], v[150:153], v[232:235], v[10:13]
	v_mfma_f32_16x16x32_bf16 v[2:5], v[158:161], v[232:235], v[2:5]
	s_add_i32 s83, s83, 2
	s_add_u32 s18, s18, 0x100
	s_addc_u32 s19, s19, 0
	s_add_u32 s54, s54, 0x100
	s_addc_u32 s81, s81, 0
	s_cmp_gt_u32 s83, 13
.LBB0_232:
	s_barrier
	s_add_u32 s20, s18, 0xfffc0080
	s_addc_u32 s21, s19, -1
	s_add_i32 s88, 0, 0x10000
	s_cmp_eq_u32 s83, 12
	s_cselect_b32 s21, s43, s21
	s_cselect_b32 s20, s48, s20
	s_cselect_b32 s87, s49, s81
	s_cselect_b32 s86, s53, s54
	s_add_i32 s90, 0, 0x14000
	s_add_u32 s100, s20, 0x80
	s_addc_u32 s101, s21, 0
	s_add_i32 m0, s9, 0xc000
	s_nop 0
	global_load_lds_dwordx4 v170, s[18:19]
	s_add_i32 m0, s9, 0xe000
	s_nop 0
	global_load_lds_dwordx4 v190, s[18:19]
	ds_read_b128 v[130:133], v246
	ds_read_b128 v[134:137], v246 offset:1024
	ds_read_b128 v[138:141], v246 offset:2048
	ds_read_b128 v[142:145], v246 offset:3072
	ds_read_b128 v[146:149], v246 offset:16384
	ds_read_b128 v[150:153], v246 offset:17408
	ds_read_b128 v[154:157], v246 offset:18432
	ds_read_b128 v[158:161], v246 offset:19456
	ds_read_b128 v[162:165], v222
	ds_read_b128 v[166:169], v222 offset:1024
	ds_read_b128 v[194:197], v222 offset:2048
	ds_read_b128 v[198:201], v222 offset:3072
	ds_read_b128 v[202:205], v222 offset:4096
	ds_read_b128 v[224:227], v222 offset:5120
	ds_read_b128 v[228:231], v222 offset:6144
	ds_read_b128 v[232:235], v222 offset:7168
	s_waitcnt vmcnt(8)
	s_waitcnt lgkmcnt(0)
	s_barrier
; #define PG8_STAGE(bufoff, gbase, voff) do { _Pragma("unroll") for (int _i = 0; _i < 2; ++_i) \
;         __builtin_amdgcn_global_load_lds((const unsigned*)((const char*)(gbase) + (voff)[_i]), (LAS unsigned*)(lds + (bufoff) + ldsw + _i * 8192), 16, 0, 0); } while (0)
; #define PG8_LDA(dst, b, h) do { _Pragma("unroll") for (int m = 0; m < 4; ++m) _Pragma("unroll") for (int k = 0; k < 2; ++k) dst[m][k] = *(const LAS bf16x8*)(lds + PG8_SA(b, h) + aoff + m * 2048 + k * 1024); } while (0)
; #define PG8_LDB(dst, b, h) do { _Pragma("unroll") for (int n = 0; n < 2; ++n) _Pragma("unroll") for (int k = 0; k < 2; ++k) dst[n][k] = *(const LAS bf16x8*)(lds + PG8_SB(b, h) + boff + n * 2048 + k * 1024); } while (0)
; #define PG8_MMA(ai, bj, At, Bt) do { __builtin_amdgcn_s_setprio(1); _Pragma("unroll") for (int m = 0; m < 4; ++m) _Pragma("unroll") for (int n = 0; n < 2; ++n) _Pragma("unroll") for (int k = 0; k < 2; ++k) \
;         acc[ai][bj][m][n] = __builtin_amdgcn_mfma_f32_16x16x32_bf16(Bt[n][k], At[m][k], acc[ai][bj][m][n], 0, 0, 0); __builtin_amdgcn_s_setprio(0); } while (0)
; #define PG8_WAIT_V(n) asm volatile("s_waitcnt vmcnt(" #n ")" ::: "memory")
; #define PG8_WAIT_L(n) asm volatile("s_waitcnt lgkmcnt(" #n ")" ::: "memory")
; #define PG8_BAR __builtin_amdgcn_s_barrier()
; #define PG8_SCHED __builtin_amdgcn_sched_barrier(0)
; template <class Epi, class Sched>
; __device__ __forceinline__ void gemm_phase(LAS unsigned char* lds, const Gemm g, const Sched& S, const Epi& E) {
;     ...
;             PG8_WAIT_V(8); PG8_WAIT_L(0); PG8_BAR; PG8_MMA(0, 0, At, B0); PG8_MMA(0, 1, At, B1); PG8_BAR; PG8_SCHED;
;             PG8_LDA(At, 0, 1); PG8_STAGE(PG8_SB(0, 0), b2, voffB); PG8_STAGE(PG8_SB(0, 1), b2 + hstepB, voffB); PG8_STAGE(PG8_SA(0, 0), a2, voffA);
;             PG8_WAIT_V(8); PG8_WAIT_L(0); PG8_BAR; PG8_MMA(1, 0, At, B0); PG8_MMA(1, 1, At, B1); PG8_BAR; PG8_SCHED;
;             PG8_LDB(B0, 1, 0); PG8_LDB(B1, 1, 1); PG8_SCHED; PG8_LDA(At, 1, 0); PG8_STAGE(PG8_SA(0, 1), a2 + hstepA, voffA);
;             PG8_WAIT_V(8); PG8_WAIT_L(0); PG8_BAR; PG8_MMA(0, 0, At, B0); PG8_MMA(0, 1, At, B1); PG8_BAR; PG8_SCHED;
	s_waitcnt lgkmcnt(0)
	v_mfma_f32_16x16x32_bf16 v[126:129], v[130:133], v[162:165], v[126:129]
	v_mfma_f32_16x16x32_bf16 v[118:121], v[138:141], v[162:165], v[118:121]
	v_mfma_f32_16x16x32_bf16 v[110:113], v[130:133], v[194:197], v[110:113]
	v_mfma_f32_16x16x32_bf16 v[102:105], v[138:141], v[194:197], v[102:105]
	v_mfma_f32_16x16x32_bf16 v[94:97], v[130:133], v[202:205], v[94:97]
	v_mfma_f32_16x16x32_bf16 v[86:89], v[138:141], v[202:205], v[86:89]
	v_mfma_f32_16x16x32_bf16 v[78:81], v[130:133], v[228:231], v[78:81]
	v_mfma_f32_16x16x32_bf16 v[70:73], v[138:141], v[228:231], v[70:73]
	v_mfma_f32_16x16x32_bf16 v[126:129], v[134:137], v[166:169], v[126:129]
	v_mfma_f32_16x16x32_bf16 v[118:121], v[142:145], v[166:169], v[118:121]
	v_mfma_f32_16x16x32_bf16 v[110:113], v[134:137], v[198:201], v[110:113]
	v_mfma_f32_16x16x32_bf16 v[102:105], v[142:145], v[198:201], v[102:105]
	v_mfma_f32_16x16x32_bf16 v[94:97], v[134:137], v[224:227], v[94:97]
	v_mfma_f32_16x16x32_bf16 v[86:89], v[142:145], v[224:227], v[86:89]
	v_mfma_f32_16x16x32_bf16 v[78:81], v[134:137], v[232:235], v[78:81]
	v_mfma_f32_16x16x32_bf16 v[70:73], v[142:145], v[232:235], v[70:73]
	v_mfma_f32_16x16x32_bf16 v[122:125], v[146:149], v[162:165], v[122:125]
	v_mfma_f32_16x16x32_bf16 v[114:117], v[154:157], v[162:165], v[114:117]
	v_mfma_f32_16x16x32_bf16 v[106:109], v[146:149], v[194:197], v[106:109]
	v_mfma_f32_16x16x32_bf16 v[98:101], v[154:157], v[194:197], v[98:101]
	v_mfma_f32_16x16x32_bf16 v[90:93], v[146:149], v[202:205], v[90:93]
	v_mfma_f32_16x16x32_bf16 v[82:85], v[154:157], v[202:205], v[82:85]
	v_mfma_f32_16x16x32_bf16 v[74:77], v[146:149], v[228:231], v[74:77]
	v_mfma_f32_16x16x32_bf16 v[66:69], v[154:157], v[228:231], v[66:69]
	v_mfma_f32_16x16x32_bf16 v[122:125], v[150:153], v[166:169], v[122:125]
	v_mfma_f32_16x16x32_bf16 v[114:117], v[158:161], v[166:169], v[114:117]
	v_mfma_f32_16x16x32_bf16 v[106:109], v[150:153], v[198:201], v[106:109]
	v_mfma_f32_16x16x32_bf16 v[98:101], v[158:161], v[198:201], v[98:101]
	v_mfma_f32_16x16x32_bf16 v[90:93], v[150:153], v[224:227], v[90:93]
	v_mfma_f32_16x16x32_bf16 v[82:85], v[158:161], v[224:227], v[82:85]
	v_mfma_f32_16x16x32_bf16 v[74:77], v[150:153], v[232:235], v[74:77]
	v_mfma_f32_16x16x32_bf16 v[66:69], v[158:161], v[232:235], v[66:69]
	s_barrier
	s_add_i32 s88, s88, s8
	s_mov_b32 m0, s88
	s_nop 0
	global_load_lds_dwordx4 v172, s[86:87]
	s_add_i32 m0, s88, 0x2000
	s_add_u32 s88, s86, 0x40000
	s_addc_u32 s89, s87, 0
	s_add_i32 s90, s90, s8
	global_load_lds_dwordx4 v192, s[86:87]
	s_mov_b32 m0, s90
	s_nop 0
	global_load_lds_dwordx4 v172, s[88:89]
	s_add_i32 m0, s90, 0x2000
	s_nop 0
	global_load_lds_dwordx4 v192, s[88:89]
	s_mov_b32 m0, s9
	s_nop 0
	global_load_lds_dwordx4 v170, s[20:21]
	s_mov_b32 m0, s28
	s_nop 0
	global_load_lds_dwordx4 v190, s[20:21]
	ds_read_b128 v[162:165], v222 offset:16384
	ds_read_b128 v[166:169], v222 offset:17408
	ds_read_b128 v[194:197], v222 offset:18432
	ds_read_b128 v[198:201], v222 offset:19456
	ds_read_b128 v[202:205], v222 offset:20480
	ds_read_b128 v[224:227], v222 offset:21504
	ds_read_b128 v[228:231], v222 offset:22528
	ds_read_b128 v[232:235], v222 offset:23552
	s_waitcnt vmcnt(8)
	s_waitcnt lgkmcnt(0)
	s_barrier
	s_waitcnt lgkmcnt(0)
	v_mfma_f32_16x16x32_bf16 v[62:65], v[130:133], v[162:165], v[62:65]
	v_mfma_f32_16x16x32_bf16 v[54:57], v[138:141], v[162:165], v[54:57]
	v_mfma_f32_16x16x32_bf16 v[46:49], v[130:133], v[194:197], v[46:49]
	v_mfma_f32_16x16x32_bf16 v[38:41], v[138:141], v[194:197], v[38:41]
	v_mfma_f32_16x16x32_bf16 v[30:33], v[130:133], v[202:205], v[30:33]
	v_mfma_f32_16x16x32_bf16 v[22:25], v[138:141], v[202:205], v[22:25]
	v_mfma_f32_16x16x32_bf16 v[14:17], v[130:133], v[228:231], v[14:17]
	v_mfma_f32_16x16x32_bf16 v[6:9], v[138:141], v[228:231], v[6:9]
	v_mfma_f32_16x16x32_bf16 v[62:65], v[134:137], v[166:169], v[62:65]
	v_mfma_f32_16x16x32_bf16 v[54:57], v[142:145], v[166:169], v[54:57]
	v_mfma_f32_16x16x32_bf16 v[46:49], v[134:137], v[198:201], v[46:49]
	v_mfma_f32_16x16x32_bf16 v[38:41], v[142:145], v[198:201], v[38:41]
	v_mfma_f32_16x16x32_bf16 v[30:33], v[134:137], v[224:227], v[30:33]
	v_mfma_f32_16x16x32_bf16 v[22:25], v[142:145], v[224:227], v[22:25]
	v_mfma_f32_16x16x32_bf16 v[14:17], v[134:137], v[232:235], v[14:17]
	v_mfma_f32_16x16x32_bf16 v[6:9], v[142:145], v[232:235], v[6:9]
	v_mfma_f32_16x16x32_bf16 v[58:61], v[146:149], v[162:165], v[58:61]
	v_mfma_f32_16x16x32_bf16 v[50:53], v[154:157], v[162:165], v[50:53]
	v_mfma_f32_16x16x32_bf16 v[42:45], v[146:149], v[194:197], v[42:45]
	v_mfma_f32_16x16x32_bf16 v[34:37], v[154:157], v[194:197], v[34:37]
	v_mfma_f32_16x16x32_bf16 v[26:29], v[146:149], v[202:205], v[26:29]
	v_mfma_f32_16x16x32_bf16 v[18:21], v[154:157], v[202:205], v[18:21]
	v_mfma_f32_16x16x32_bf16 v[10:13], v[146:149], v[228:231], v[10:13]
	v_mfma_f32_16x16x32_bf16 v[2:5], v[154:157], v[228:231], v[2:5]
	v_mfma_f32_16x16x32_bf16 v[58:61], v[150:153], v[166:169], v[58:61]
	v_mfma_f32_16x16x32_bf16 v[50:53], v[158:161], v[166:169], v[50:53]
	v_mfma_f32_16x16x32_bf16 v[42:45], v[150:153], v[198:201], v[42:45]
	v_mfma_f32_16x16x32_bf16 v[34:37], v[158:161], v[198:201], v[34:37]
	v_mfma_f32_16x16x32_bf16 v[26:29], v[150:153], v[224:227], v[26:29]
	v_mfma_f32_16x16x32_bf16 v[18:21], v[158:161], v[224:227], v[18:21]
	v_mfma_f32_16x16x32_bf16 v[10:13], v[150:153], v[232:235], v[10:13]
	v_mfma_f32_16x16x32_bf16 v[2:5], v[158:161], v[232:235], v[2:5]
	s_barrier
; #define PG8_STAGE(bufoff, gbase, voff) do { _Pragma("unroll") for (int _i = 0; _i < 2; ++_i) \
;         __builtin_amdgcn_global_load_lds((const unsigned*)((const char*)(gbase) + (voff)[_i]), (LAS unsigned*)(lds + (bufoff) + ldsw + _i * 8192), 16, 0, 0); } while (0)
; #define PG8_LDA(dst, b, h) do { _Pragma("unroll") for (int m = 0; m < 4; ++m) _Pragma("unroll") for (int k = 0; k < 2; ++k) dst[m][k] = *(const LAS bf16x8*)(lds + PG8_SA(b, h) + aoff + m * 2048 + k * 1024); } while (0)
; #define PG8_LDB(dst, b, h) do { _Pragma("unroll") for (int n = 0; n < 2; ++n) _Pragma("unroll") for (int k = 0; k < 2; ++k) dst[n][k] = *(const LAS bf16x8*)(lds + PG8_SB(b, h) + boff + n * 2048 + k * 1024); } while (0)
; #define PG8_MMA(ai, bj, At, Bt) do { __builtin_amdgcn_s_setprio(1); _Pragma("unroll") for (int m = 0; m < 4; ++m) _Pragma("unroll") for (int n = 0; n < 2; ++n) _Pragma("unroll") for (int k = 0; k < 2; ++k) \
;         acc[ai][bj][m][n] = __builtin_amdgcn_mfma_f32_16x16x32_bf16(Bt[n][k], At[m][k], acc[ai][bj][m][n], 0, 0, 0); __builtin_amdgcn_s_setprio(0); } while (0)
; #define PG8_WAIT_V(n) asm volatile("s_waitcnt vmcnt(" #n ")" ::: "memory")
; #define PG8_WAIT_L(n) asm volatile("s_waitcnt lgkmcnt(" #n ")" ::: "memory")
; #define PG8_BAR __builtin_amdgcn_s_barrier()
; #define PG8_SCHED __builtin_amdgcn_sched_barrier(0)
; template <class Epi, class Sched>
; __device__ __forceinline__ void gemm_phase(LAS unsigned char* lds, const Gemm g, const Sched& S, const Epi& E) {
;     ...
;             PG8_LDB(B0, 1, 0); PG8_LDB(B1, 1, 1); PG8_SCHED; PG8_LDA(At, 1, 0); PG8_STAGE(PG8_SA(0, 1), a2 + hstepA, voffA);
;             PG8_WAIT_V(8); PG8_WAIT_L(0); PG8_BAR; PG8_MMA(0, 0, At, B0); PG8_MMA(0, 1, At, B1); PG8_BAR; PG8_SCHED;
;             PG8_LDA(At, 1, 1); PG8_STAGE(PG8_SB(1, 0), b3, voffB); PG8_STAGE(PG8_SB(1, 1), b3 + hstepB, voffB); PG8_STAGE(PG8_SA(1, 0), a3, voffA);
;             PG8_WAIT_V(8); PG8_WAIT_L(0); PG8_BAR; PG8_MMA(1, 0, At, B0); PG8_MMA(1, 1, At, B1); PG8_BAR; PG8_SCHED;
;         }
;         if (wr == 0) PG8_BAR;
	s_add_i32 s88, 0, 0x18000
	s_add_i32 s89, 0, 0x1c000
	s_add_u32 s20, s20, 0x40000
	s_addc_u32 s21, s21, 0
	s_mov_b32 m0, s29
	s_nop 0
	global_load_lds_dwordx4 v170, s[20:21]
	s_mov_b32 m0, s30
	s_nop 0
	global_load_lds_dwordx4 v190, s[20:21]
	ds_read_b128 v[130:133], v246 offset:32768
	ds_read_b128 v[134:137], v246 offset:33792
	ds_read_b128 v[138:141], v246 offset:34816
	ds_read_b128 v[142:145], v246 offset:35840
	ds_read_b128 v[146:149], v246 offset:49152
	ds_read_b128 v[150:153], v246 offset:50176
	ds_read_b128 v[154:157], v246 offset:51200
	ds_read_b128 v[158:161], v246 offset:52224
	ds_read_b128 v[162:165], v222 offset:32768
	ds_read_b128 v[166:169], v222 offset:33792
	ds_read_b128 v[194:197], v222 offset:34816
	ds_read_b128 v[198:201], v222 offset:35840
	ds_read_b128 v[202:205], v222 offset:36864
	ds_read_b128 v[224:227], v222 offset:37888
	ds_read_b128 v[228:231], v222 offset:38912
	ds_read_b128 v[232:235], v222 offset:39936
	s_waitcnt vmcnt(8)
	s_waitcnt lgkmcnt(0)
	s_barrier
	s_waitcnt lgkmcnt(0)
	v_mfma_f32_16x16x32_bf16 v[126:129], v[130:133], v[162:165], v[126:129]
	v_mfma_f32_16x16x32_bf16 v[118:121], v[138:141], v[162:165], v[118:121]
	v_mfma_f32_16x16x32_bf16 v[110:113], v[130:133], v[194:197], v[110:113]
	v_mfma_f32_16x16x32_bf16 v[102:105], v[138:141], v[194:197], v[102:105]
	v_mfma_f32_16x16x32_bf16 v[94:97], v[130:133], v[202:205], v[94:97]
	v_mfma_f32_16x16x32_bf16 v[86:89], v[138:141], v[202:205], v[86:89]
	v_mfma_f32_16x16x32_bf16 v[78:81], v[130:133], v[228:231], v[78:81]
	v_mfma_f32_16x16x32_bf16 v[70:73], v[138:141], v[228:231], v[70:73]
	v_mfma_f32_16x16x32_bf16 v[126:129], v[134:137], v[166:169], v[126:129]
	v_mfma_f32_16x16x32_bf16 v[118:121], v[142:145], v[166:169], v[118:121]
	v_mfma_f32_16x16x32_bf16 v[110:113], v[134:137], v[198:201], v[110:113]
	v_mfma_f32_16x16x32_bf16 v[102:105], v[142:145], v[198:201], v[102:105]
	v_mfma_f32_16x16x32_bf16 v[94:97], v[134:137], v[224:227], v[94:97]
	v_mfma_f32_16x16x32_bf16 v[86:89], v[142:145], v[224:227], v[86:89]
	v_mfma_f32_16x16x32_bf16 v[78:81], v[134:137], v[232:235], v[78:81]
	v_mfma_f32_16x16x32_bf16 v[70:73], v[142:145], v[232:235], v[70:73]
	v_mfma_f32_16x16x32_bf16 v[122:125], v[146:149], v[162:165], v[122:125]
	v_mfma_f32_16x16x32_bf16 v[114:117], v[154:157], v[162:165], v[114:117]
	v_mfma_f32_16x16x32_bf16 v[106:109], v[146:149], v[194:197], v[106:109]
	v_mfma_f32_16x16x32_bf16 v[98:101], v[154:157], v[194:197], v[98:101]
	v_mfma_f32_16x16x32_bf16 v[90:93], v[146:149], v[202:205], v[90:93]
	v_mfma_f32_16x16x32_bf16 v[82:85], v[154:157], v[202:205], v[82:85]
	v_mfma_f32_16x16x32_bf16 v[74:77], v[146:149], v[228:231], v[74:77]
	v_mfma_f32_16x16x32_bf16 v[66:69], v[154:157], v[228:231], v[66:69]
	v_mfma_f32_16x16x32_bf16 v[122:125], v[150:153], v[166:169], v[122:125]
	v_mfma_f32_16x16x32_bf16 v[114:117], v[158:161], v[166:169], v[114:117]
	v_mfma_f32_16x16x32_bf16 v[106:109], v[150:153], v[198:201], v[106:109]
	v_mfma_f32_16x16x32_bf16 v[98:101], v[158:161], v[198:201], v[98:101]
	v_mfma_f32_16x16x32_bf16 v[90:93], v[150:153], v[224:227], v[90:93]
	v_mfma_f32_16x16x32_bf16 v[82:85], v[158:161], v[224:227], v[82:85]
	v_mfma_f32_16x16x32_bf16 v[74:77], v[150:153], v[232:235], v[74:77]
	v_mfma_f32_16x16x32_bf16 v[66:69], v[158:161], v[232:235], v[66:69]
	s_barrier
	s_add_i32 s20, s8, 0x18000
	s_add_u32 s88, s86, 0x80
	s_addc_u32 s89, s87, 0
	s_mov_b32 m0, s20
	s_nop 0
	global_load_lds_dwordx4 v172, s[88:89]
	s_add_i32 m0, s20, 0x2000
	s_add_u32 s20, s86, 0x40080
	s_addc_u32 s21, s87, 0
	s_add_i32 s12, s8, 0x1c000
	global_load_lds_dwordx4 v192, s[88:89]
	s_mov_b32 m0, s12
	s_nop 0
	global_load_lds_dwordx4 v172, s[20:21]
	s_add_i32 m0, s12, 0x2000
	s_nop 0
	global_load_lds_dwordx4 v192, s[20:21]
	s_mov_b32 m0, s31
	s_nop 0
	global_load_lds_dwordx4 v170, s[100:101]
	s_mov_b32 m0, s34
	s_nop 0
	global_load_lds_dwordx4 v190, s[100:101]
	ds_read_b128 v[162:165], v222 offset:49152
	ds_read_b128 v[166:169], v222 offset:50176
	ds_read_b128 v[194:197], v222 offset:51200
	ds_read_b128 v[198:201], v222 offset:52224
	ds_read_b128 v[202:205], v222 offset:53248
	ds_read_b128 v[224:227], v222 offset:54272
	ds_read_b128 v[228:231], v222 offset:55296
	ds_read_b128 v[232:235], v222 offset:56320
	s_waitcnt vmcnt(8)
	s_waitcnt lgkmcnt(0)
	s_barrier
	s_waitcnt lgkmcnt(0)
	v_mfma_f32_16x16x32_bf16 v[62:65], v[130:133], v[162:165], v[62:65]
	v_mfma_f32_16x16x32_bf16 v[54:57], v[138:141], v[162:165], v[54:57]
	v_mfma_f32_16x16x32_bf16 v[46:49], v[130:133], v[194:197], v[46:49]
	v_mfma_f32_16x16x32_bf16 v[38:41], v[138:141], v[194:197], v[38:41]
	v_mfma_f32_16x16x32_bf16 v[30:33], v[130:133], v[202:205], v[30:33]
	v_mfma_f32_16x16x32_bf16 v[22:25], v[138:141], v[202:205], v[22:25]
	v_mfma_f32_16x16x32_bf16 v[14:17], v[130:133], v[228:231], v[14:17]
	v_mfma_f32_16x16x32_bf16 v[6:9], v[138:141], v[228:231], v[6:9]
	v_mfma_f32_16x16x32_bf16 v[62:65], v[134:137], v[166:169], v[62:65]
	v_mfma_f32_16x16x32_bf16 v[54:57], v[142:145], v[166:169], v[54:57]
	v_mfma_f32_16x16x32_bf16 v[46:49], v[134:137], v[198:201], v[46:49]
	v_mfma_f32_16x16x32_bf16 v[38:41], v[142:145], v[198:201], v[38:41]
	v_mfma_f32_16x16x32_bf16 v[30:33], v[134:137], v[224:227], v[30:33]
	v_mfma_f32_16x16x32_bf16 v[22:25], v[142:145], v[224:227], v[22:25]
	v_mfma_f32_16x16x32_bf16 v[14:17], v[134:137], v[232:235], v[14:17]
	v_mfma_f32_16x16x32_bf16 v[6:9], v[142:145], v[232:235], v[6:9]
	v_mfma_f32_16x16x32_bf16 v[58:61], v[146:149], v[162:165], v[58:61]
	v_mfma_f32_16x16x32_bf16 v[50:53], v[154:157], v[162:165], v[50:53]
	v_mfma_f32_16x16x32_bf16 v[42:45], v[146:149], v[194:197], v[42:45]
	v_mfma_f32_16x16x32_bf16 v[34:37], v[154:157], v[194:197], v[34:37]
	v_mfma_f32_16x16x32_bf16 v[26:29], v[146:149], v[202:205], v[26:29]
	v_mfma_f32_16x16x32_bf16 v[18:21], v[154:157], v[202:205], v[18:21]
	v_mfma_f32_16x16x32_bf16 v[10:13], v[146:149], v[228:231], v[10:13]
	v_mfma_f32_16x16x32_bf16 v[2:5], v[154:157], v[228:231], v[2:5]
	v_mfma_f32_16x16x32_bf16 v[58:61], v[150:153], v[166:169], v[58:61]
	v_mfma_f32_16x16x32_bf16 v[50:53], v[158:161], v[166:169], v[50:53]
	v_mfma_f32_16x16x32_bf16 v[42:45], v[150:153], v[198:201], v[42:45]
	v_mfma_f32_16x16x32_bf16 v[34:37], v[158:161], v[198:201], v[34:37]
	v_mfma_f32_16x16x32_bf16 v[26:29], v[150:153], v[224:227], v[26:29]
	v_mfma_f32_16x16x32_bf16 v[18:21], v[158:161], v[224:227], v[18:21]
	v_mfma_f32_16x16x32_bf16 v[10:13], v[150:153], v[232:235], v[10:13]
	v_mfma_f32_16x16x32_bf16 v[2:5], v[158:161], v[232:235], v[2:5]
	s_add_i32 s83, s83, 2
	s_add_u32 s18, s18, 0x100
	s_addc_u32 s19, s19, 0
	s_add_u32 s54, s54, 0x100
	s_addc_u32 s81, s81, 0
	s_cmp_gt_u32 s83, 13
	s_cbranch_scc0 .LBB0_232
	s_barrier
	s_and_b64 vcc, exec, s[72:73]
	s_cbranch_vccz .LBB0_235
	s_barrier

; #define PG8_STAGE(bufoff, gbase, voff) do { _Pragma("unroll") for (int _i = 0; _i < 2; ++_i) \
;         __builtin_amdgcn_global_load_lds((const unsigned*)((const char*)(gbase) + (voff)[_i]), (LAS unsigned*)(lds + (bufoff) + ldsw + _i * 8192), 16, 0, 0); } while (0)
; #define PG8_LDA(dst, b, h) do { _Pragma("unroll") for (int m = 0; m < 4; ++m) _Pragma("unroll") for (int k = 0; k < 2; ++k) dst[m][k] = *(const LAS bf16x8*)(lds + PG8_SA(b, h) + aoff + m * 2048 + k * 1024); } while (0)
; #define PG8_LDB(dst, b, h) do { _Pragma("unroll") for (int n = 0; n < 2; ++n) _Pragma("unroll") for (int k = 0; k < 2; ++k) dst[n][k] = *(const LAS bf16x8*)(lds + PG8_SB(b, h) + boff + n * 2048 + k * 1024); } while (0)
; #define PG8_MMA(ai, bj, At, Bt) do { __builtin_amdgcn_s_setprio(1); _Pragma("unroll") for (int m = 0; m < 4; ++m) _Pragma("unroll") for (int n = 0; n < 2; ++n) _Pragma("unroll") for (int k = 0; k < 2; ++k) \
;         acc[ai][bj][m][n] = __builtin_amdgcn_mfma_f32_16x16x32_bf16(Bt[n][k], At[m][k], acc[ai][bj][m][n], 0, 0, 0); __builtin_amdgcn_s_setprio(0); } while (0)
; #define PG8_WAIT_V(n) asm volatile("s_waitcnt vmcnt(" #n ")" ::: "memory")
; #define PG8_WAIT_L(n) asm volatile("s_waitcnt lgkmcnt(" #n ")" ::: "memory")
; template <class Epi, class Sched>
; __device__ __forceinline__ void gemm_phase(LAS unsigned char* lds, const Gemm g, const Sched& S, const Epi& E) {
;     ...
;         const bool has_next = S.next(ui + 1, nxt);
;         const char* nA = has_next ? (const char*)g.A + (size_t)nxt.pm * tstepA + (size_t)nxt.pn * g.a_pn_off * 2 : cA; const char* nB = has_next ? (const char*)g.Bt + (size_t)nxt.pn * tstepB : cB;
;         for (int t = 0; t < nt; t += 2) {
;             const bool last = (t == nt - 2);
;             const char* a1 = cA + (size_t)(t + 1) * kstep;
;             const char* a2 = last ? nA : cA + (size_t)(t + 2) * kstep; const char* b2 = last ? nB : cB + (size_t)(t + 2) * kstep;
;             const char* a3 = a2 + kstep; const char* b3 = b2 + kstep;
;             PG8_LDB(B0, 0, 0); PG8_LDB(B1, 0, 1); PG8_SCHED; PG8_LDA(At, 0, 0); PG8_STAGE(PG8_SA(1, 1), a1 + hstepA, voffA);
;             PG8_WAIT_V(8); PG8_WAIT_L(0); PG8_BAR; PG8_MMA(0, 0, At, B0); PG8_MMA(0, 1, At, B1); PG8_BAR; PG8_SCHED;
;             PG8_LDA(At, 0, 1); PG8_STAGE(PG8_SB(0, 0), b2, voffB); PG8_STAGE(PG8_SB(0, 1), b2 + hstepB, voffB); PG8_STAGE(PG8_SA(0, 0), a2, voffA);
.LBB0_348:
	s_ashr_i32 s71, s70, 31
	s_lshl_b64 s[48:49], s[70:71], 19
	s_add_u32 s72, s4, s48
	s_addc_u32 s73, s5, s49
	s_and_b64 s[48:49], s[66:67], exec
	s_cselect_b32 s48, s73, s19
	s_cselect_b32 s49, s72, s18
	s_ashr_i32 s69, s68, 31
	s_lshl_b64 s[74:75], s[68:69], 19
	v_readlane_b32 s12, v248, 13
	s_add_u32 s74, s12, s74
	v_readlane_b32 s12, v248, 14
	s_addc_u32 s75, s12, s75
	s_and_b64 s[76:77], s[66:67], exec
	s_cselect_b32 s53, s75, s21
	s_cselect_b32 s54, s74, s20
	s_add_u32 s18, s18, 0x40080
	s_addc_u32 s19, s19, 0
	s_add_u32 s69, s20, 0x100
	s_addc_u32 s71, s21, 0
	s_mov_b32 s78, -2
	s_waitcnt vmcnt(0)
	v_add_u32_e32 v255, 0x10000, v139
	s_add_u32 s20, s18, 0xfffc0080
	s_addc_u32 s21, s19, -1
	s_add_i32 s79, 0, 0x10000
	s_cmp_eq_u32 s78, 12
	s_cselect_b32 s21, s48, s21
	s_cselect_b32 s20, s49, s20
	s_cselect_b32 s77, s53, s71
	s_cselect_b32 s76, s54, s69
	s_add_u32 s100, s20, 0x80
	s_addc_u32 s101, s21, 0
	s_add_i32 s82, 0, 0x14000
	s_add_i32 m0, s9, 0xc000
	s_nop 0
	global_load_lds_dwordx4 v130, s[18:19]
	s_add_i32 m0, s9, 0xe000
	s_nop 0
	global_load_lds_dwordx4 v134, s[18:19]
	ds_read_b128 v[150:153], v255
	ds_read_b128 v[154:157], v255 offset:1024
	ds_read_b128 v[158:161], v255 offset:2048
	ds_read_b128 v[162:165], v255 offset:3072
	ds_read_b128 v[166:169], v255 offset:16384
	ds_read_b128 v[170:173], v255 offset:17408
	ds_read_b128 v[190:193], v255 offset:18432
	ds_read_b128 v[194:197], v255 offset:19456
	ds_read_b128 v[198:201], v148
	ds_read_b128 v[202:205], v148 offset:1024
	ds_read_b128 v[206:209], v148 offset:2048
	ds_read_b128 v[218:221], v148 offset:3072
	ds_read_b128 v[222:225], v148 offset:4096
	ds_read_b128 v[226:229], v148 offset:5120
	ds_read_b128 v[230:233], v148 offset:6144
	ds_read_b128 v[234:237], v148 offset:7168
	s_waitcnt vmcnt(8)
	s_waitcnt lgkmcnt(0)
	s_barrier
	s_waitcnt lgkmcnt(0)
	v_mfma_f32_16x16x32_bf16 v[126:129], v[150:153], v[198:201], 0
	v_mfma_f32_16x16x32_bf16 v[122:125], v[158:161], v[198:201], 0
	v_mfma_f32_16x16x32_bf16 v[110:113], v[150:153], v[206:209], 0
	v_mfma_f32_16x16x32_bf16 v[106:109], v[158:161], v[206:209], 0
	v_mfma_f32_16x16x32_bf16 v[94:97], v[150:153], v[222:225], 0
	v_mfma_f32_16x16x32_bf16 v[90:93], v[158:161], v[222:225], 0
	v_mfma_f32_16x16x32_bf16 v[82:85], v[150:153], v[230:233], 0
	v_mfma_f32_16x16x32_bf16 v[74:77], v[158:161], v[230:233], 0
	v_mfma_f32_16x16x32_bf16 v[126:129], v[154:157], v[202:205], v[126:129]
	v_mfma_f32_16x16x32_bf16 v[122:125], v[162:165], v[202:205], v[122:125]
	v_mfma_f32_16x16x32_bf16 v[110:113], v[154:157], v[218:221], v[110:113]
	v_mfma_f32_16x16x32_bf16 v[106:109], v[162:165], v[218:221], v[106:109]
	v_mfma_f32_16x16x32_bf16 v[94:97], v[154:157], v[226:229], v[94:97]
	v_mfma_f32_16x16x32_bf16 v[90:93], v[162:165], v[226:229], v[90:93]
	v_mfma_f32_16x16x32_bf16 v[82:85], v[154:157], v[234:237], v[82:85]
	v_mfma_f32_16x16x32_bf16 v[74:77], v[162:165], v[234:237], v[74:77]
	v_mfma_f32_16x16x32_bf16 v[118:121], v[166:169], v[198:201], 0
	v_mfma_f32_16x16x32_bf16 v[114:117], v[190:193], v[198:201], 0
	v_mfma_f32_16x16x32_bf16 v[102:105], v[166:169], v[206:209], 0
	v_mfma_f32_16x16x32_bf16 v[98:101], v[190:193], v[206:209], 0
	v_mfma_f32_16x16x32_bf16 v[86:89], v[166:169], v[222:225], 0
	v_mfma_f32_16x16x32_bf16 v[78:81], v[190:193], v[222:225], 0
	v_mfma_f32_16x16x32_bf16 v[70:73], v[166:169], v[230:233], 0
	v_mfma_f32_16x16x32_bf16 v[66:69], v[190:193], v[230:233], 0
	v_mfma_f32_16x16x32_bf16 v[118:121], v[170:173], v[202:205], v[118:121]
	v_mfma_f32_16x16x32_bf16 v[114:117], v[194:197], v[202:205], v[114:117]
	v_mfma_f32_16x16x32_bf16 v[102:105], v[170:173], v[218:221], v[102:105]
	v_mfma_f32_16x16x32_bf16 v[98:101], v[194:197], v[218:221], v[98:101]
	v_mfma_f32_16x16x32_bf16 v[86:89], v[170:173], v[226:229], v[86:89]
	v_mfma_f32_16x16x32_bf16 v[78:81], v[194:197], v[226:229], v[78:81]
	v_mfma_f32_16x16x32_bf16 v[70:73], v[170:173], v[234:237], v[70:73]
	v_mfma_f32_16x16x32_bf16 v[66:69], v[194:197], v[234:237], v[66:69]
	s_barrier
	s_add_i32 s79, s79, s8
	s_mov_b32 m0, s79
	s_nop 0
	global_load_lds_dwordx4 v132, s[76:77]
	s_add_i32 m0, s79, 0x2000
	s_add_u32 s80, s76, 0x40000
	s_addc_u32 s81, s77, 0
	s_add_i32 s79, s82, s8
	global_load_lds_dwordx4 v136, s[76:77]
	s_mov_b32 m0, s79
	s_nop 0
	global_load_lds_dwordx4 v132, s[80:81]
	s_add_i32 m0, s79, 0x2000
	s_nop 0
	global_load_lds_dwordx4 v136, s[80:81]
	s_mov_b32 m0, s9
	s_nop 0
	global_load_lds_dwordx4 v130, s[20:21]
	s_mov_b32 m0, s28
	s_nop 0
	global_load_lds_dwordx4 v134, s[20:21]
	ds_read_b128 v[198:201], v148 offset:16384
	ds_read_b128 v[202:205], v148 offset:17408
	ds_read_b128 v[206:209], v148 offset:18432
	ds_read_b128 v[218:221], v148 offset:19456
	ds_read_b128 v[222:225], v148 offset:20480
	ds_read_b128 v[226:229], v148 offset:21504
	ds_read_b128 v[230:233], v148 offset:22528
	ds_read_b128 v[234:237], v148 offset:23552
	s_waitcnt vmcnt(8)
	s_waitcnt lgkmcnt(0)
	s_barrier
; #define PG8_STAGE(bufoff, gbase, voff) do { _Pragma("unroll") for (int _i = 0; _i < 2; ++_i) \
;         __builtin_amdgcn_global_load_lds((const unsigned*)((const char*)(gbase) + (voff)[_i]), (LAS unsigned*)(lds + (bufoff) + ldsw + _i * 8192), 16, 0, 0); } while (0)
; #define PG8_LDA(dst, b, h) do { _Pragma("unroll") for (int m = 0; m < 4; ++m) _Pragma("unroll") for (int k = 0; k < 2; ++k) dst[m][k] = *(const LAS bf16x8*)(lds + PG8_SA(b, h) + aoff + m * 2048 + k * 1024); } while (0)
; #define PG8_LDB(dst, b, h) do { _Pragma("unroll") for (int n = 0; n < 2; ++n) _Pragma("unroll") for (int k = 0; k < 2; ++k) dst[n][k] = *(const LAS bf16x8*)(lds + PG8_SB(b, h) + boff + n * 2048 + k * 1024); } while (0)
; #define PG8_MMA(ai, bj, At, Bt) do { __builtin_amdgcn_s_setprio(1); _Pragma("unroll") for (int m = 0; m < 4; ++m) _Pragma("unroll") for (int n = 0; n < 2; ++n) _Pragma("unroll") for (int k = 0; k < 2; ++k) \
;         acc[ai][bj][m][n] = __builtin_amdgcn_mfma_f32_16x16x32_bf16(Bt[n][k], At[m][k], acc[ai][bj][m][n], 0, 0, 0); __builtin_amdgcn_s_setprio(0); } while (0)
; #define PG8_WAIT_V(n) asm volatile("s_waitcnt vmcnt(" #n ")" ::: "memory")
; #define PG8_WAIT_L(n) asm volatile("s_waitcnt lgkmcnt(" #n ")" ::: "memory")
; #define PG8_BAR __builtin_amdgcn_s_barrier()
; #define PG8_SCHED __builtin_amdgcn_sched_barrier(0)
; template <class Epi, class Sched>
; __device__ __forceinline__ void gemm_phase(LAS unsigned char* lds, const Gemm g, const Sched& S, const Epi& E) {
;     ...
;             PG8_WAIT_V(8); PG8_WAIT_L(0); PG8_BAR; PG8_MMA(1, 0, At, B0); PG8_MMA(1, 1, At, B1); PG8_BAR; PG8_SCHED;
;             PG8_LDB(B0, 1, 0); PG8_LDB(B1, 1, 1); PG8_SCHED; PG8_LDA(At, 1, 0); PG8_STAGE(PG8_SA(0, 1), a2 + hstepA, voffA);
;             PG8_WAIT_V(8); PG8_WAIT_L(0); PG8_BAR; PG8_MMA(0, 0, At, B0); PG8_MMA(0, 1, At, B1); PG8_BAR; PG8_SCHED;
	s_waitcnt lgkmcnt(0)
	v_mfma_f32_16x16x32_bf16 v[62:65], v[150:153], v[198:201], 0
	v_mfma_f32_16x16x32_bf16 v[58:61], v[158:161], v[198:201], 0
	v_mfma_f32_16x16x32_bf16 v[50:53], v[150:153], v[206:209], 0
	v_mfma_f32_16x16x32_bf16 v[42:45], v[158:161], v[206:209], 0
	v_mfma_f32_16x16x32_bf16 v[30:33], v[150:153], v[222:225], 0
	v_mfma_f32_16x16x32_bf16 v[26:29], v[158:161], v[222:225], 0
	v_mfma_f32_16x16x32_bf16 v[18:21], v[150:153], v[230:233], 0
	v_mfma_f32_16x16x32_bf16 v[10:13], v[158:161], v[230:233], 0
	v_mfma_f32_16x16x32_bf16 v[62:65], v[154:157], v[202:205], v[62:65]
	v_mfma_f32_16x16x32_bf16 v[58:61], v[162:165], v[202:205], v[58:61]
	v_mfma_f32_16x16x32_bf16 v[50:53], v[154:157], v[218:221], v[50:53]
	v_mfma_f32_16x16x32_bf16 v[42:45], v[162:165], v[218:221], v[42:45]
	v_mfma_f32_16x16x32_bf16 v[30:33], v[154:157], v[226:229], v[30:33]
	v_mfma_f32_16x16x32_bf16 v[26:29], v[162:165], v[226:229], v[26:29]
	v_mfma_f32_16x16x32_bf16 v[18:21], v[154:157], v[234:237], v[18:21]
	v_mfma_f32_16x16x32_bf16 v[10:13], v[162:165], v[234:237], v[10:13]
	v_mfma_f32_16x16x32_bf16 v[54:57], v[166:169], v[198:201], 0
	v_mfma_f32_16x16x32_bf16 v[46:49], v[190:193], v[198:201], 0
	v_mfma_f32_16x16x32_bf16 v[38:41], v[166:169], v[206:209], 0
	v_mfma_f32_16x16x32_bf16 v[34:37], v[190:193], v[206:209], 0
	v_mfma_f32_16x16x32_bf16 v[22:25], v[166:169], v[222:225], 0
	v_mfma_f32_16x16x32_bf16 v[14:17], v[190:193], v[222:225], 0
	v_mfma_f32_16x16x32_bf16 v[6:9], v[166:169], v[230:233], 0
	v_mfma_f32_16x16x32_bf16 v[2:5], v[190:193], v[230:233], 0
	v_mfma_f32_16x16x32_bf16 v[54:57], v[170:173], v[202:205], v[54:57]
	v_mfma_f32_16x16x32_bf16 v[46:49], v[194:197], v[202:205], v[46:49]
	v_mfma_f32_16x16x32_bf16 v[38:41], v[170:173], v[218:221], v[38:41]
	v_mfma_f32_16x16x32_bf16 v[34:37], v[194:197], v[218:221], v[34:37]
	v_mfma_f32_16x16x32_bf16 v[22:25], v[170:173], v[226:229], v[22:25]
	v_mfma_f32_16x16x32_bf16 v[14:17], v[194:197], v[226:229], v[14:17]
	v_mfma_f32_16x16x32_bf16 v[6:9], v[170:173], v[234:237], v[6:9]
	v_mfma_f32_16x16x32_bf16 v[2:5], v[194:197], v[234:237], v[2:5]
	s_barrier
	s_add_i32 s79, 0, 0x18000
	s_add_i32 s80, 0, 0x1c000
	s_add_u32 s20, s20, 0x40000
	s_addc_u32 s21, s21, 0
	s_mov_b32 m0, s29
	s_nop 0
	global_load_lds_dwordx4 v130, s[20:21]
	s_mov_b32 m0, s30
	s_nop 0
	global_load_lds_dwordx4 v134, s[20:21]
	ds_read_b128 v[150:153], v255 offset:32768
	ds_read_b128 v[154:157], v255 offset:33792
	ds_read_b128 v[158:161], v255 offset:34816
	ds_read_b128 v[162:165], v255 offset:35840
	ds_read_b128 v[166:169], v255 offset:49152
	ds_read_b128 v[170:173], v255 offset:50176
	ds_read_b128 v[190:193], v255 offset:51200
	ds_read_b128 v[194:197], v255 offset:52224
	ds_read_b128 v[198:201], v148 offset:32768
	ds_read_b128 v[202:205], v148 offset:33792
	ds_read_b128 v[206:209], v148 offset:34816
	ds_read_b128 v[218:221], v148 offset:35840
	ds_read_b128 v[222:225], v148 offset:36864
	ds_read_b128 v[226:229], v148 offset:37888
	ds_read_b128 v[230:233], v148 offset:38912
	ds_read_b128 v[234:237], v148 offset:39936
	s_waitcnt vmcnt(8)
	s_waitcnt lgkmcnt(0)
	s_barrier
	s_waitcnt lgkmcnt(0)
	v_mfma_f32_16x16x32_bf16 v[126:129], v[150:153], v[198:201], v[126:129]
	v_mfma_f32_16x16x32_bf16 v[122:125], v[158:161], v[198:201], v[122:125]
	v_mfma_f32_16x16x32_bf16 v[110:113], v[150:153], v[206:209], v[110:113]
	v_mfma_f32_16x16x32_bf16 v[106:109], v[158:161], v[206:209], v[106:109]
	v_mfma_f32_16x16x32_bf16 v[94:97], v[150:153], v[222:225], v[94:97]
	v_mfma_f32_16x16x32_bf16 v[90:93], v[158:161], v[222:225], v[90:93]
	v_mfma_f32_16x16x32_bf16 v[82:85], v[150:153], v[230:233], v[82:85]
	v_mfma_f32_16x16x32_bf16 v[74:77], v[158:161], v[230:233], v[74:77]
	v_mfma_f32_16x16x32_bf16 v[126:129], v[154:157], v[202:205], v[126:129]
	v_mfma_f32_16x16x32_bf16 v[122:125], v[162:165], v[202:205], v[122:125]
	v_mfma_f32_16x16x32_bf16 v[110:113], v[154:157], v[218:221], v[110:113]
	v_mfma_f32_16x16x32_bf16 v[106:109], v[162:165], v[218:221], v[106:109]
	v_mfma_f32_16x16x32_bf16 v[94:97], v[154:157], v[226:229], v[94:97]
	v_mfma_f32_16x16x32_bf16 v[90:93], v[162:165], v[226:229], v[90:93]
	v_mfma_f32_16x16x32_bf16 v[82:85], v[154:157], v[234:237], v[82:85]
	v_mfma_f32_16x16x32_bf16 v[74:77], v[162:165], v[234:237], v[74:77]
	v_mfma_f32_16x16x32_bf16 v[118:121], v[166:169], v[198:201], v[118:121]
	v_mfma_f32_16x16x32_bf16 v[114:117], v[190:193], v[198:201], v[114:117]
	v_mfma_f32_16x16x32_bf16 v[102:105], v[166:169], v[206:209], v[102:105]
	v_mfma_f32_16x16x32_bf16 v[98:101], v[190:193], v[206:209], v[98:101]
	v_mfma_f32_16x16x32_bf16 v[86:89], v[166:169], v[222:225], v[86:89]
	v_mfma_f32_16x16x32_bf16 v[78:81], v[190:193], v[222:225], v[78:81]
	v_mfma_f32_16x16x32_bf16 v[70:73], v[166:169], v[230:233], v[70:73]
	v_mfma_f32_16x16x32_bf16 v[66:69], v[190:193], v[230:233], v[66:69]
	v_mfma_f32_16x16x32_bf16 v[118:121], v[170:173], v[202:205], v[118:121]
	v_mfma_f32_16x16x32_bf16 v[114:117], v[194:197], v[202:205], v[114:117]
	v_mfma_f32_16x16x32_bf16 v[102:105], v[170:173], v[218:221], v[102:105]
	v_mfma_f32_16x16x32_bf16 v[98:101], v[194:197], v[218:221], v[98:101]
	v_mfma_f32_16x16x32_bf16 v[86:89], v[170:173], v[226:229], v[86:89]
	v_mfma_f32_16x16x32_bf16 v[78:81], v[194:197], v[226:229], v[78:81]
	v_mfma_f32_16x16x32_bf16 v[70:73], v[170:173], v[234:237], v[70:73]
	v_mfma_f32_16x16x32_bf16 v[66:69], v[194:197], v[234:237], v[66:69]
	s_barrier
; #define PG8_STAGE(bufoff, gbase, voff) do { _Pragma("unroll") for (int _i = 0; _i < 2; ++_i) \
;         __builtin_amdgcn_global_load_lds((const unsigned*)((const char*)(gbase) + (voff)[_i]), (LAS unsigned*)(lds + (bufoff) + ldsw + _i * 8192), 16, 0, 0); } while (0)
; #define PG8_LDA(dst, b, h) do { _Pragma("unroll") for (int m = 0; m < 4; ++m) _Pragma("unroll") for (int k = 0; k < 2; ++k) dst[m][k] = *(const LAS bf16x8*)(lds + PG8_SA(b, h) + aoff + m * 2048 + k * 1024); } while (0)
; #define PG8_LDB(dst, b, h) do { _Pragma("unroll") for (int n = 0; n < 2; ++n) _Pragma("unroll") for (int k = 0; k < 2; ++k) dst[n][k] = *(const LAS bf16x8*)(lds + PG8_SB(b, h) + boff + n * 2048 + k * 1024); } while (0)
; #define PG8_WAIT_V(n) asm volatile("s_waitcnt vmcnt(" #n ")" ::: "memory")
; #define PG8_BAR __builtin_amdgcn_s_barrier()
; template <class Epi, class Sched>
; __device__ __forceinline__ void gemm_phase(LAS unsigned char* lds, const Gemm g, const Sched& S, const Epi& E) {
;     ...
;         for (int t = 0; t < nt; t += 2) {
;             const bool last = (t == nt - 2);
;             const char* a1 = cA + (size_t)(t + 1) * kstep;
;             const char* a2 = last ? nA : cA + (size_t)(t + 2) * kstep; const char* b2 = last ? nB : cB + (size_t)(t + 2) * kstep;
;             const char* a3 = a2 + kstep; const char* b3 = b2 + kstep;
;             PG8_LDB(B0, 0, 0); PG8_LDB(B1, 0, 1); PG8_SCHED; PG8_LDA(At, 0, 0); PG8_STAGE(PG8_SA(1, 1), a1 + hstepA, voffA);
;             PG8_WAIT_V(8); PG8_WAIT_L(0); PG8_BAR; PG8_MMA(0, 0, At, B0); PG8_MMA(0, 1, At, B1); PG8_BAR; PG8_SCHED;
;             PG8_LDA(At, 0, 1); PG8_STAGE(PG8_SB(0, 0), b2, voffB); PG8_STAGE(PG8_SB(0, 1), b2 + hstepB, voffB); PG8_STAGE(PG8_SA(0, 0), a2, voffA);
;             PG8_WAIT_V(8); PG8_WAIT_L(0); PG8_BAR; PG8_MMA(1, 0, At, B0); PG8_MMA(1, 1, At, B1); PG8_BAR; PG8_SCHED;
;             PG8_LDB(B0, 1, 0); PG8_LDB(B1, 1, 1); PG8_SCHED; PG8_LDA(At, 1, 0); PG8_STAGE(PG8_SA(0, 1), a2 + hstepA, voffA);
;             PG8_WAIT_V(8); PG8_WAIT_L(0); PG8_BAR; PG8_MMA(0, 0, At, B0); PG8_MMA(0, 1, At, B1); PG8_BAR; PG8_SCHED;
;             PG8_LDA(At, 1, 1); PG8_STAGE(PG8_SB(1, 0), b3, voffB); PG8_STAGE(PG8_SB(1, 1), b3 + hstepB, voffB); PG8_STAGE(PG8_SA(1, 0), a3, voffA);
;             PG8_WAIT_V(8); PG8_WAIT_L(0); PG8_BAR; PG8_MMA(1, 0, At, B0); PG8_MMA(1, 1, At, B1); PG8_BAR; PG8_SCHED;
	s_add_i32 s20, s8, 0x18000
	s_add_u32 s80, s76, 0x80
	s_addc_u32 s81, s77, 0
	s_mov_b32 m0, s20
	s_nop 0
	global_load_lds_dwordx4 v132, s[80:81]
	s_add_i32 m0, s20, 0x2000
	s_add_u32 s20, s76, 0x40080
	s_addc_u32 s21, s77, 0
	s_add_i32 s12, s8, 0x1c000
	global_load_lds_dwordx4 v136, s[80:81]
	s_mov_b32 m0, s12
	s_nop 0
	global_load_lds_dwordx4 v132, s[20:21]
	s_add_i32 m0, s12, 0x2000
	s_nop 0
	global_load_lds_dwordx4 v136, s[20:21]
	s_mov_b32 m0, s31
	s_nop 0
	global_load_lds_dwordx4 v130, s[100:101]
	s_mov_b32 m0, s34
	s_nop 0
	global_load_lds_dwordx4 v134, s[100:101]
	ds_read_b128 v[198:201], v148 offset:49152
	ds_read_b128 v[202:205], v148 offset:50176
	ds_read_b128 v[206:209], v148 offset:51200
	ds_read_b128 v[218:221], v148 offset:52224
	ds_read_b128 v[222:225], v148 offset:53248
	ds_read_b128 v[226:229], v148 offset:54272
	ds_read_b128 v[230:233], v148 offset:55296
	ds_read_b128 v[234:237], v148 offset:56320
	s_waitcnt vmcnt(8)
	s_waitcnt lgkmcnt(0)
	s_barrier
	s_waitcnt lgkmcnt(0)
	v_mfma_f32_16x16x32_bf16 v[62:65], v[150:153], v[198:201], v[62:65]
	v_mfma_f32_16x16x32_bf16 v[58:61], v[158:161], v[198:201], v[58:61]
	v_mfma_f32_16x16x32_bf16 v[50:53], v[150:153], v[206:209], v[50:53]
	v_mfma_f32_16x16x32_bf16 v[42:45], v[158:161], v[206:209], v[42:45]
	v_mfma_f32_16x16x32_bf16 v[30:33], v[150:153], v[222:225], v[30:33]
	v_mfma_f32_16x16x32_bf16 v[26:29], v[158:161], v[222:225], v[26:29]
	v_mfma_f32_16x16x32_bf16 v[18:21], v[150:153], v[230:233], v[18:21]
	v_mfma_f32_16x16x32_bf16 v[10:13], v[158:161], v[230:233], v[10:13]
	v_mfma_f32_16x16x32_bf16 v[62:65], v[154:157], v[202:205], v[62:65]
	v_mfma_f32_16x16x32_bf16 v[58:61], v[162:165], v[202:205], v[58:61]
	v_mfma_f32_16x16x32_bf16 v[50:53], v[154:157], v[218:221], v[50:53]
	v_mfma_f32_16x16x32_bf16 v[42:45], v[162:165], v[218:221], v[42:45]
	v_mfma_f32_16x16x32_bf16 v[30:33], v[154:157], v[226:229], v[30:33]
	v_mfma_f32_16x16x32_bf16 v[26:29], v[162:165], v[226:229], v[26:29]
	v_mfma_f32_16x16x32_bf16 v[18:21], v[154:157], v[234:237], v[18:21]
	v_mfma_f32_16x16x32_bf16 v[10:13], v[162:165], v[234:237], v[10:13]
	v_mfma_f32_16x16x32_bf16 v[54:57], v[166:169], v[198:201], v[54:57]
	v_mfma_f32_16x16x32_bf16 v[46:49], v[190:193], v[198:201], v[46:49]
	v_mfma_f32_16x16x32_bf16 v[38:41], v[166:169], v[206:209], v[38:41]
	v_mfma_f32_16x16x32_bf16 v[34:37], v[190:193], v[206:209], v[34:37]
	v_mfma_f32_16x16x32_bf16 v[22:25], v[166:169], v[222:225], v[22:25]
	v_mfma_f32_16x16x32_bf16 v[14:17], v[190:193], v[222:225], v[14:17]
	v_mfma_f32_16x16x32_bf16 v[6:9], v[166:169], v[230:233], v[6:9]
	v_mfma_f32_16x16x32_bf16 v[2:5], v[190:193], v[230:233], v[2:5]
	v_mfma_f32_16x16x32_bf16 v[54:57], v[170:173], v[202:205], v[54:57]
	v_mfma_f32_16x16x32_bf16 v[46:49], v[194:197], v[202:205], v[46:49]
	v_mfma_f32_16x16x32_bf16 v[38:41], v[170:173], v[218:221], v[38:41]
	v_mfma_f32_16x16x32_bf16 v[34:37], v[194:197], v[218:221], v[34:37]
	v_mfma_f32_16x16x32_bf16 v[22:25], v[170:173], v[226:229], v[22:25]
	v_mfma_f32_16x16x32_bf16 v[14:17], v[194:197], v[226:229], v[14:17]
	v_mfma_f32_16x16x32_bf16 v[6:9], v[170:173], v[234:237], v[6:9]
	v_mfma_f32_16x16x32_bf16 v[2:5], v[194:197], v[234:237], v[2:5]
	s_add_i32 s78, s78, 2
	s_add_u32 s18, s18, 0x100
	s_addc_u32 s19, s19, 0
	s_add_u32 s69, s69, 0x100
	s_addc_u32 s71, s71, 0
	s_cmp_gt_u32 s78, 13
.LBB0_349:
	s_barrier
	s_add_u32 s20, s18, 0xfffc0080
	s_addc_u32 s21, s19, -1
	s_add_i32 s79, 0, 0x10000
	s_cmp_eq_u32 s78, 12
	s_cselect_b32 s21, s48, s21
	s_cselect_b32 s20, s49, s20
	s_cselect_b32 s77, s53, s71
	s_cselect_b32 s76, s54, s69
	s_add_u32 s100, s20, 0x80
	s_addc_u32 s101, s21, 0
	s_add_i32 s82, 0, 0x14000
	s_add_i32 m0, s9, 0xc000
	s_nop 0
	global_load_lds_dwordx4 v130, s[18:19]
	s_add_i32 m0, s9, 0xe000
	s_nop 0
	global_load_lds_dwordx4 v134, s[18:19]
	ds_read_b128 v[150:153], v255
	ds_read_b128 v[154:157], v255 offset:1024
	ds_read_b128 v[158:161], v255 offset:2048
	ds_read_b128 v[162:165], v255 offset:3072
	ds_read_b128 v[166:169], v255 offset:16384
	ds_read_b128 v[170:173], v255 offset:17408
	ds_read_b128 v[190:193], v255 offset:18432
	ds_read_b128 v[194:197], v255 offset:19456
	ds_read_b128 v[198:201], v148
	ds_read_b128 v[202:205], v148 offset:1024
	ds_read_b128 v[206:209], v148 offset:2048
	ds_read_b128 v[218:221], v148 offset:3072
	ds_read_b128 v[222:225], v148 offset:4096
	ds_read_b128 v[226:229], v148 offset:5120
	ds_read_b128 v[230:233], v148 offset:6144
	ds_read_b128 v[234:237], v148 offset:7168
	s_waitcnt vmcnt(8)
	s_waitcnt lgkmcnt(0)
	s_barrier
; #define PG8_STAGE(bufoff, gbase, voff) do { _Pragma("unroll") for (int _i = 0; _i < 2; ++_i) \
;         __builtin_amdgcn_global_load_lds((const unsigned*)((const char*)(gbase) + (voff)[_i]), (LAS unsigned*)(lds + (bufoff) + ldsw + _i * 8192), 16, 0, 0); } while (0)
; #define PG8_LDA(dst, b, h) do { _Pragma("unroll") for (int m = 0; m < 4; ++m) _Pragma("unroll") for (int k = 0; k < 2; ++k) dst[m][k] = *(const LAS bf16x8*)(lds + PG8_SA(b, h) + aoff + m * 2048 + k * 1024); } while (0)
; #define PG8_LDB(dst, b, h) do { _Pragma("unroll") for (int n = 0; n < 2; ++n) _Pragma("unroll") for (int k = 0; k < 2; ++k) dst[n][k] = *(const LAS bf16x8*)(lds + PG8_SB(b, h) + boff + n * 2048 + k * 1024); } while (0)
; #define PG8_MMA(ai, bj, At, Bt) do { __builtin_amdgcn_s_setprio(1); _Pragma("unroll") for (int m = 0; m < 4; ++m) _Pragma("unroll") for (int n = 0; n < 2; ++n) _Pragma("unroll") for (int k = 0; k < 2; ++k) \
;         acc[ai][bj][m][n] = __builtin_amdgcn_mfma_f32_16x16x32_bf16(Bt[n][k], At[m][k], acc[ai][bj][m][n], 0, 0, 0); __builtin_amdgcn_s_setprio(0); } while (0)
; #define PG8_WAIT_V(n) asm volatile("s_waitcnt vmcnt(" #n ")" ::: "memory")
; #define PG8_WAIT_L(n) asm volatile("s_waitcnt lgkmcnt(" #n ")" ::: "memory")
; #define PG8_BAR __builtin_amdgcn_s_barrier()
; #define PG8_SCHED __builtin_amdgcn_sched_barrier(0)
; template <class Epi, class Sched>
; __device__ __forceinline__ void gemm_phase(LAS unsigned char* lds, const Gemm g, const Sched& S, const Epi& E) {
;     ...
;             PG8_WAIT_V(8); PG8_WAIT_L(0); PG8_BAR; PG8_MMA(0, 0, At, B0); PG8_MMA(0, 1, At, B1); PG8_BAR; PG8_SCHED;
;             PG8_LDA(At, 0, 1); PG8_STAGE(PG8_SB(0, 0), b2, voffB); PG8_STAGE(PG8_SB(0, 1), b2 + hstepB, voffB); PG8_STAGE(PG8_SA(0, 0), a2, voffA);
;             PG8_WAIT_V(8); PG8_WAIT_L(0); PG8_BAR; PG8_MMA(1, 0, At, B0); PG8_MMA(1, 1, At, B1); PG8_BAR; PG8_SCHED;
;             PG8_LDB(B0, 1, 0); PG8_LDB(B1, 1, 1); PG8_SCHED; PG8_LDA(At, 1, 0); PG8_STAGE(PG8_SA(0, 1), a2 + hstepA, voffA);
;             PG8_WAIT_V(8); PG8_WAIT_L(0); PG8_BAR; PG8_MMA(0, 0, At, B0); PG8_MMA(0, 1, At, B1); PG8_BAR; PG8_SCHED;
	s_waitcnt lgkmcnt(0)
	v_mfma_f32_16x16x32_bf16 v[126:129], v[150:153], v[198:201], v[126:129]
	v_mfma_f32_16x16x32_bf16 v[122:125], v[158:161], v[198:201], v[122:125]
	v_mfma_f32_16x16x32_bf16 v[110:113], v[150:153], v[206:209], v[110:113]
	v_mfma_f32_16x16x32_bf16 v[106:109], v[158:161], v[206:209], v[106:109]
	v_mfma_f32_16x16x32_bf16 v[94:97], v[150:153], v[222:225], v[94:97]
	v_mfma_f32_16x16x32_bf16 v[90:93], v[158:161], v[222:225], v[90:93]
	v_mfma_f32_16x16x32_bf16 v[82:85], v[150:153], v[230:233], v[82:85]
	v_mfma_f32_16x16x32_bf16 v[74:77], v[158:161], v[230:233], v[74:77]
	v_mfma_f32_16x16x32_bf16 v[126:129], v[154:157], v[202:205], v[126:129]
	v_mfma_f32_16x16x32_bf16 v[122:125], v[162:165], v[202:205], v[122:125]
	v_mfma_f32_16x16x32_bf16 v[110:113], v[154:157], v[218:221], v[110:113]
	v_mfma_f32_16x16x32_bf16 v[106:109], v[162:165], v[218:221], v[106:109]
	v_mfma_f32_16x16x32_bf16 v[94:97], v[154:157], v[226:229], v[94:97]
	v_mfma_f32_16x16x32_bf16 v[90:93], v[162:165], v[226:229], v[90:93]
	v_mfma_f32_16x16x32_bf16 v[82:85], v[154:157], v[234:237], v[82:85]
	v_mfma_f32_16x16x32_bf16 v[74:77], v[162:165], v[234:237], v[74:77]
	v_mfma_f32_16x16x32_bf16 v[118:121], v[166:169], v[198:201], v[118:121]
	v_mfma_f32_16x16x32_bf16 v[114:117], v[190:193], v[198:201], v[114:117]
	v_mfma_f32_16x16x32_bf16 v[102:105], v[166:169], v[206:209], v[102:105]
	v_mfma_f32_16x16x32_bf16 v[98:101], v[190:193], v[206:209], v[98:101]
	v_mfma_f32_16x16x32_bf16 v[86:89], v[166:169], v[222:225], v[86:89]
	v_mfma_f32_16x16x32_bf16 v[78:81], v[190:193], v[222:225], v[78:81]
	v_mfma_f32_16x16x32_bf16 v[70:73], v[166:169], v[230:233], v[70:73]
	v_mfma_f32_16x16x32_bf16 v[66:69], v[190:193], v[230:233], v[66:69]
	v_mfma_f32_16x16x32_bf16 v[118:121], v[170:173], v[202:205], v[118:121]
	v_mfma_f32_16x16x32_bf16 v[114:117], v[194:197], v[202:205], v[114:117]
	v_mfma_f32_16x16x32_bf16 v[102:105], v[170:173], v[218:221], v[102:105]
	v_mfma_f32_16x16x32_bf16 v[98:101], v[194:197], v[218:221], v[98:101]
	v_mfma_f32_16x16x32_bf16 v[86:89], v[170:173], v[226:229], v[86:89]
	v_mfma_f32_16x16x32_bf16 v[78:81], v[194:197], v[226:229], v[78:81]
	v_mfma_f32_16x16x32_bf16 v[70:73], v[170:173], v[234:237], v[70:73]
	v_mfma_f32_16x16x32_bf16 v[66:69], v[194:197], v[234:237], v[66:69]
	s_barrier
	s_add_i32 s79, s79, s8
	s_mov_b32 m0, s79
	s_nop 0
	global_load_lds_dwordx4 v132, s[76:77]
	s_add_i32 m0, s79, 0x2000
	s_add_u32 s80, s76, 0x40000
	s_addc_u32 s81, s77, 0
	s_add_i32 s79, s82, s8
	global_load_lds_dwordx4 v136, s[76:77]
	s_mov_b32 m0, s79
	s_nop 0
	global_load_lds_dwordx4 v132, s[80:81]
	s_add_i32 m0, s79, 0x2000
	s_nop 0
	global_load_lds_dwordx4 v136, s[80:81]
	s_mov_b32 m0, s9
	s_nop 0
	global_load_lds_dwordx4 v130, s[20:21]
	s_mov_b32 m0, s28
	s_nop 0
	global_load_lds_dwordx4 v134, s[20:21]
	ds_read_b128 v[198:201], v148 offset:16384
	ds_read_b128 v[202:205], v148 offset:17408
	ds_read_b128 v[206:209], v148 offset:18432
	ds_read_b128 v[218:221], v148 offset:19456
	ds_read_b128 v[222:225], v148 offset:20480
	ds_read_b128 v[226:229], v148 offset:21504
	ds_read_b128 v[230:233], v148 offset:22528
	ds_read_b128 v[234:237], v148 offset:23552
	s_waitcnt vmcnt(8)
	s_waitcnt lgkmcnt(0)
	s_barrier
	s_waitcnt lgkmcnt(0)
	v_mfma_f32_16x16x32_bf16 v[62:65], v[150:153], v[198:201], v[62:65]
	v_mfma_f32_16x16x32_bf16 v[58:61], v[158:161], v[198:201], v[58:61]
	v_mfma_f32_16x16x32_bf16 v[50:53], v[150:153], v[206:209], v[50:53]
	v_mfma_f32_16x16x32_bf16 v[42:45], v[158:161], v[206:209], v[42:45]
	v_mfma_f32_16x16x32_bf16 v[30:33], v[150:153], v[222:225], v[30:33]
	v_mfma_f32_16x16x32_bf16 v[26:29], v[158:161], v[222:225], v[26:29]
	v_mfma_f32_16x16x32_bf16 v[18:21], v[150:153], v[230:233], v[18:21]
	v_mfma_f32_16x16x32_bf16 v[10:13], v[158:161], v[230:233], v[10:13]
	v_mfma_f32_16x16x32_bf16 v[62:65], v[154:157], v[202:205], v[62:65]
	v_mfma_f32_16x16x32_bf16 v[58:61], v[162:165], v[202:205], v[58:61]
	v_mfma_f32_16x16x32_bf16 v[50:53], v[154:157], v[218:221], v[50:53]
	v_mfma_f32_16x16x32_bf16 v[42:45], v[162:165], v[218:221], v[42:45]
	v_mfma_f32_16x16x32_bf16 v[30:33], v[154:157], v[226:229], v[30:33]
	v_mfma_f32_16x16x32_bf16 v[26:29], v[162:165], v[226:229], v[26:29]
	v_mfma_f32_16x16x32_bf16 v[18:21], v[154:157], v[234:237], v[18:21]
	v_mfma_f32_16x16x32_bf16 v[10:13], v[162:165], v[234:237], v[10:13]
	v_mfma_f32_16x16x32_bf16 v[54:57], v[166:169], v[198:201], v[54:57]
	v_mfma_f32_16x16x32_bf16 v[46:49], v[190:193], v[198:201], v[46:49]
	v_mfma_f32_16x16x32_bf16 v[38:41], v[166:169], v[206:209], v[38:41]
	v_mfma_f32_16x16x32_bf16 v[34:37], v[190:193], v[206:209], v[34:37]
	v_mfma_f32_16x16x32_bf16 v[22:25], v[166:169], v[222:225], v[22:25]
	v_mfma_f32_16x16x32_bf16 v[14:17], v[190:193], v[222:225], v[14:17]
	v_mfma_f32_16x16x32_bf16 v[6:9], v[166:169], v[230:233], v[6:9]
	v_mfma_f32_16x16x32_bf16 v[2:5], v[190:193], v[230:233], v[2:5]
	v_mfma_f32_16x16x32_bf16 v[54:57], v[170:173], v[202:205], v[54:57]
	v_mfma_f32_16x16x32_bf16 v[46:49], v[194:197], v[202:205], v[46:49]
	v_mfma_f32_16x16x32_bf16 v[38:41], v[170:173], v[218:221], v[38:41]
	v_mfma_f32_16x16x32_bf16 v[34:37], v[194:197], v[218:221], v[34:37]
	v_mfma_f32_16x16x32_bf16 v[22:25], v[170:173], v[226:229], v[22:25]
	v_mfma_f32_16x16x32_bf16 v[14:17], v[194:197], v[226:229], v[14:17]
	v_mfma_f32_16x16x32_bf16 v[6:9], v[170:173], v[234:237], v[6:9]
	v_mfma_f32_16x16x32_bf16 v[2:5], v[194:197], v[234:237], v[2:5]
	s_barrier
; #define PG8_STAGE(bufoff, gbase, voff) do { _Pragma("unroll") for (int _i = 0; _i < 2; ++_i) \
;         __builtin_amdgcn_global_load_lds((const unsigned*)((const char*)(gbase) + (voff)[_i]), (LAS unsigned*)(lds + (bufoff) + ldsw + _i * 8192), 16, 0, 0); } while (0)
; #define PG8_LDA(dst, b, h) do { _Pragma("unroll") for (int m = 0; m < 4; ++m) _Pragma("unroll") for (int k = 0; k < 2; ++k) dst[m][k] = *(const LAS bf16x8*)(lds + PG8_SA(b, h) + aoff + m * 2048 + k * 1024); } while (0)
; #define PG8_LDB(dst, b, h) do { _Pragma("unroll") for (int n = 0; n < 2; ++n) _Pragma("unroll") for (int k = 0; k < 2; ++k) dst[n][k] = *(const LAS bf16x8*)(lds + PG8_SB(b, h) + boff + n * 2048 + k * 1024); } while (0)
; #define PG8_MMA(ai, bj, At, Bt) do { __builtin_amdgcn_s_setprio(1); _Pragma("unroll") for (int m = 0; m < 4; ++m) _Pragma("unroll") for (int n = 0; n < 2; ++n) _Pragma("unroll") for (int k = 0; k < 2; ++k) \
;         acc[ai][bj][m][n] = __builtin_amdgcn_mfma_f32_16x16x32_bf16(Bt[n][k], At[m][k], acc[ai][bj][m][n], 0, 0, 0); __builtin_amdgcn_s_setprio(0); } while (0)
; #define PG8_WAIT_V(n) asm volatile("s_waitcnt vmcnt(" #n ")" ::: "memory")
; #define PG8_WAIT_L(n) asm volatile("s_waitcnt lgkmcnt(" #n ")" ::: "memory")
; #define PG8_BAR __builtin_amdgcn_s_barrier()
; #define PG8_SCHED __builtin_amdgcn_sched_barrier(0)
; template <class Epi, class Sched>
; __device__ __forceinline__ void gemm_phase(LAS unsigned char* lds, const Gemm g, const Sched& S, const Epi& E) {
;     ...
;             PG8_LDB(B0, 1, 0); PG8_LDB(B1, 1, 1); PG8_SCHED; PG8_LDA(At, 1, 0); PG8_STAGE(PG8_SA(0, 1), a2 + hstepA, voffA);
;             PG8_WAIT_V(8); PG8_WAIT_L(0); PG8_BAR; PG8_MMA(0, 0, At, B0); PG8_MMA(0, 1, At, B1); PG8_BAR; PG8_SCHED;
;             PG8_LDA(At, 1, 1); PG8_STAGE(PG8_SB(1, 0), b3, voffB); PG8_STAGE(PG8_SB(1, 1), b3 + hstepB, voffB); PG8_STAGE(PG8_SA(1, 0), a3, voffA);
;             PG8_WAIT_V(8); PG8_WAIT_L(0); PG8_BAR; PG8_MMA(1, 0, At, B0); PG8_MMA(1, 1, At, B1); PG8_BAR; PG8_SCHED;
;         }
;         if (wr == 0) PG8_BAR;
	s_add_i32 s79, 0, 0x18000
	s_add_i32 s80, 0, 0x1c000
	s_add_u32 s20, s20, 0x40000
	s_addc_u32 s21, s21, 0
	s_mov_b32 m0, s29
	s_nop 0
	global_load_lds_dwordx4 v130, s[20:21]
	s_mov_b32 m0, s30
	s_nop 0
	global_load_lds_dwordx4 v134, s[20:21]
	ds_read_b128 v[150:153], v255 offset:32768
	ds_read_b128 v[154:157], v255 offset:33792
	ds_read_b128 v[158:161], v255 offset:34816
	ds_read_b128 v[162:165], v255 offset:35840
	ds_read_b128 v[166:169], v255 offset:49152
	ds_read_b128 v[170:173], v255 offset:50176
	ds_read_b128 v[190:193], v255 offset:51200
	ds_read_b128 v[194:197], v255 offset:52224
	ds_read_b128 v[198:201], v148 offset:32768
	ds_read_b128 v[202:205], v148 offset:33792
	ds_read_b128 v[206:209], v148 offset:34816
	ds_read_b128 v[218:221], v148 offset:35840
	ds_read_b128 v[222:225], v148 offset:36864
	ds_read_b128 v[226:229], v148 offset:37888
	ds_read_b128 v[230:233], v148 offset:38912
	ds_read_b128 v[234:237], v148 offset:39936
	s_waitcnt vmcnt(8)
	s_waitcnt lgkmcnt(0)
	s_barrier
	s_waitcnt lgkmcnt(0)
	v_mfma_f32_16x16x32_bf16 v[126:129], v[150:153], v[198:201], v[126:129]
	v_mfma_f32_16x16x32_bf16 v[122:125], v[158:161], v[198:201], v[122:125]
	v_mfma_f32_16x16x32_bf16 v[110:113], v[150:153], v[206:209], v[110:113]
	v_mfma_f32_16x16x32_bf16 v[106:109], v[158:161], v[206:209], v[106:109]
	v_mfma_f32_16x16x32_bf16 v[94:97], v[150:153], v[222:225], v[94:97]
	v_mfma_f32_16x16x32_bf16 v[90:93], v[158:161], v[222:225], v[90:93]
	v_mfma_f32_16x16x32_bf16 v[82:85], v[150:153], v[230:233], v[82:85]
	v_mfma_f32_16x16x32_bf16 v[74:77], v[158:161], v[230:233], v[74:77]
	v_mfma_f32_16x16x32_bf16 v[126:129], v[154:157], v[202:205], v[126:129]
	v_mfma_f32_16x16x32_bf16 v[122:125], v[162:165], v[202:205], v[122:125]
	v_mfma_f32_16x16x32_bf16 v[110:113], v[154:157], v[218:221], v[110:113]
	v_mfma_f32_16x16x32_bf16 v[106:109], v[162:165], v[218:221], v[106:109]
	v_mfma_f32_16x16x32_bf16 v[94:97], v[154:157], v[226:229], v[94:97]
	v_mfma_f32_16x16x32_bf16 v[90:93], v[162:165], v[226:229], v[90:93]
	v_mfma_f32_16x16x32_bf16 v[82:85], v[154:157], v[234:237], v[82:85]
	v_mfma_f32_16x16x32_bf16 v[74:77], v[162:165], v[234:237], v[74:77]
	v_mfma_f32_16x16x32_bf16 v[118:121], v[166:169], v[198:201], v[118:121]
	v_mfma_f32_16x16x32_bf16 v[114:117], v[190:193], v[198:201], v[114:117]
	v_mfma_f32_16x16x32_bf16 v[102:105], v[166:169], v[206:209], v[102:105]
	v_mfma_f32_16x16x32_bf16 v[98:101], v[190:193], v[206:209], v[98:101]
	v_mfma_f32_16x16x32_bf16 v[86:89], v[166:169], v[222:225], v[86:89]
	v_mfma_f32_16x16x32_bf16 v[78:81], v[190:193], v[222:225], v[78:81]
	v_mfma_f32_16x16x32_bf16 v[70:73], v[166:169], v[230:233], v[70:73]
	v_mfma_f32_16x16x32_bf16 v[66:69], v[190:193], v[230:233], v[66:69]
	v_mfma_f32_16x16x32_bf16 v[118:121], v[170:173], v[202:205], v[118:121]
	v_mfma_f32_16x16x32_bf16 v[114:117], v[194:197], v[202:205], v[114:117]
	v_mfma_f32_16x16x32_bf16 v[102:105], v[170:173], v[218:221], v[102:105]
	v_mfma_f32_16x16x32_bf16 v[98:101], v[194:197], v[218:221], v[98:101]
	v_mfma_f32_16x16x32_bf16 v[86:89], v[170:173], v[226:229], v[86:89]
	v_mfma_f32_16x16x32_bf16 v[78:81], v[194:197], v[226:229], v[78:81]
	v_mfma_f32_16x16x32_bf16 v[70:73], v[170:173], v[234:237], v[70:73]
	v_mfma_f32_16x16x32_bf16 v[66:69], v[194:197], v[234:237], v[66:69]
	s_barrier
	s_add_i32 s20, s8, 0x18000
	s_add_u32 s80, s76, 0x80
	s_addc_u32 s81, s77, 0
	s_mov_b32 m0, s20
	s_nop 0
	global_load_lds_dwordx4 v132, s[80:81]
	s_add_i32 m0, s20, 0x2000
	s_add_u32 s20, s76, 0x40080
	s_addc_u32 s21, s77, 0
	s_add_i32 s12, s8, 0x1c000
	global_load_lds_dwordx4 v136, s[80:81]
	s_mov_b32 m0, s12
	s_nop 0
	global_load_lds_dwordx4 v132, s[20:21]
	s_add_i32 m0, s12, 0x2000
	s_nop 0
	global_load_lds_dwordx4 v136, s[20:21]
	s_mov_b32 m0, s31
	s_nop 0
	global_load_lds_dwordx4 v130, s[100:101]
	s_mov_b32 m0, s34
	s_nop 0
	global_load_lds_dwordx4 v134, s[100:101]
	ds_read_b128 v[198:201], v148 offset:49152
	ds_read_b128 v[202:205], v148 offset:50176
	ds_read_b128 v[206:209], v148 offset:51200
	ds_read_b128 v[218:221], v148 offset:52224
	ds_read_b128 v[222:225], v148 offset:53248
	ds_read_b128 v[226:229], v148 offset:54272
	ds_read_b128 v[230:233], v148 offset:55296
	ds_read_b128 v[234:237], v148 offset:56320
	s_waitcnt vmcnt(8)
	s_waitcnt lgkmcnt(0)
	s_barrier
	s_waitcnt lgkmcnt(0)
	v_mfma_f32_16x16x32_bf16 v[62:65], v[150:153], v[198:201], v[62:65]
	v_mfma_f32_16x16x32_bf16 v[58:61], v[158:161], v[198:201], v[58:61]
	v_mfma_f32_16x16x32_bf16 v[50:53], v[150:153], v[206:209], v[50:53]
	v_mfma_f32_16x16x32_bf16 v[42:45], v[158:161], v[206:209], v[42:45]
	v_mfma_f32_16x16x32_bf16 v[30:33], v[150:153], v[222:225], v[30:33]
	v_mfma_f32_16x16x32_bf16 v[26:29], v[158:161], v[222:225], v[26:29]
	v_mfma_f32_16x16x32_bf16 v[18:21], v[150:153], v[230:233], v[18:21]
	v_mfma_f32_16x16x32_bf16 v[10:13], v[158:161], v[230:233], v[10:13]
	v_mfma_f32_16x16x32_bf16 v[62:65], v[154:157], v[202:205], v[62:65]
	v_mfma_f32_16x16x32_bf16 v[58:61], v[162:165], v[202:205], v[58:61]
	v_mfma_f32_16x16x32_bf16 v[50:53], v[154:157], v[218:221], v[50:53]
	v_mfma_f32_16x16x32_bf16 v[42:45], v[162:165], v[218:221], v[42:45]
	v_mfma_f32_16x16x32_bf16 v[30:33], v[154:157], v[226:229], v[30:33]
	v_mfma_f32_16x16x32_bf16 v[26:29], v[162:165], v[226:229], v[26:29]
	v_mfma_f32_16x16x32_bf16 v[18:21], v[154:157], v[234:237], v[18:21]
	v_mfma_f32_16x16x32_bf16 v[10:13], v[162:165], v[234:237], v[10:13]
	v_mfma_f32_16x16x32_bf16 v[54:57], v[166:169], v[198:201], v[54:57]
	v_mfma_f32_16x16x32_bf16 v[46:49], v[190:193], v[198:201], v[46:49]
	v_mfma_f32_16x16x32_bf16 v[38:41], v[166:169], v[206:209], v[38:41]
	v_mfma_f32_16x16x32_bf16 v[34:37], v[190:193], v[206:209], v[34:37]
	v_mfma_f32_16x16x32_bf16 v[22:25], v[166:169], v[222:225], v[22:25]
	v_mfma_f32_16x16x32_bf16 v[14:17], v[190:193], v[222:225], v[14:17]
	v_mfma_f32_16x16x32_bf16 v[6:9], v[166:169], v[230:233], v[6:9]
	v_mfma_f32_16x16x32_bf16 v[2:5], v[190:193], v[230:233], v[2:5]
	v_mfma_f32_16x16x32_bf16 v[54:57], v[170:173], v[202:205], v[54:57]
	v_mfma_f32_16x16x32_bf16 v[46:49], v[194:197], v[202:205], v[46:49]
	v_mfma_f32_16x16x32_bf16 v[38:41], v[170:173], v[218:221], v[38:41]
	v_mfma_f32_16x16x32_bf16 v[34:37], v[194:197], v[218:221], v[34:37]
	v_mfma_f32_16x16x32_bf16 v[22:25], v[170:173], v[226:229], v[22:25]
	v_mfma_f32_16x16x32_bf16 v[14:17], v[194:197], v[226:229], v[14:17]
	v_mfma_f32_16x16x32_bf16 v[6:9], v[170:173], v[234:237], v[6:9]
	v_mfma_f32_16x16x32_bf16 v[2:5], v[194:197], v[234:237], v[2:5]
	s_add_i32 s78, s78, 2
	s_add_u32 s18, s18, 0x100
	s_addc_u32 s19, s19, 0
	s_add_u32 s69, s69, 0x100
	s_addc_u32 s71, s71, 0
	s_cmp_gt_u32 s78, 13
	s_cbranch_scc0 .LBB0_349
	s_barrier
	s_and_b64 vcc, exec, s[36:37]
	s_cbranch_vccz .LBB0_352
	s_barrier

; #define PG8_STAGE(bufoff, gbase, voff) do { _Pragma("unroll") for (int _i = 0; _i < 2; ++_i) \
;         __builtin_amdgcn_global_load_lds((const unsigned*)((const char*)(gbase) + (voff)[_i]), (LAS unsigned*)(lds + (bufoff) + ldsw + _i * 8192), 16, 0, 0); } while (0)
; #define PG8_LDA(dst, b, h) do { _Pragma("unroll") for (int m = 0; m < 4; ++m) _Pragma("unroll") for (int k = 0; k < 2; ++k) dst[m][k] = *(const LAS bf16x8*)(lds + PG8_SA(b, h) + aoff + m * 2048 + k * 1024); } while (0)
; #define PG8_LDB(dst, b, h) do { _Pragma("unroll") for (int n = 0; n < 2; ++n) _Pragma("unroll") for (int k = 0; k < 2; ++k) dst[n][k] = *(const LAS bf16x8*)(lds + PG8_SB(b, h) + boff + n * 2048 + k * 1024); } while (0)
; #define PG8_MMA(ai, bj, At, Bt) do { __builtin_amdgcn_s_setprio(1); _Pragma("unroll") for (int m = 0; m < 4; ++m) _Pragma("unroll") for (int n = 0; n < 2; ++n) _Pragma("unroll") for (int k = 0; k < 2; ++k) \
;         acc[ai][bj][m][n] = __builtin_amdgcn_mfma_f32_16x16x32_bf16(Bt[n][k], At[m][k], acc[ai][bj][m][n], 0, 0, 0); __builtin_amdgcn_s_setprio(0); } while (0)
; #define PG8_WAIT_V(n) asm volatile("s_waitcnt vmcnt(" #n ")" ::: "memory")
; #define PG8_WAIT_L(n) asm volatile("s_waitcnt lgkmcnt(" #n ")" ::: "memory")
; template <class Epi, class Sched>
; __device__ __forceinline__ void gemm_phase(LAS unsigned char* lds, const Gemm g, const Sched& S, const Epi& E) {
;     ...
;         const bool has_next = S.next(ui + 1, nxt);
;         const char* nA = has_next ? (const char*)g.A + (size_t)nxt.pm * tstepA + (size_t)nxt.pn * g.a_pn_off * 2 : cA; const char* nB = has_next ? (const char*)g.Bt + (size_t)nxt.pn * tstepB : cB;
;         for (int t = 0; t < nt; t += 2) {
;             const bool last = (t == nt - 2);
;             const char* a1 = cA + (size_t)(t + 1) * kstep;
;             const char* a2 = last ? nA : cA + (size_t)(t + 2) * kstep; const char* b2 = last ? nB : cB + (size_t)(t + 2) * kstep;
;             const char* a3 = a2 + kstep; const char* b3 = b2 + kstep;
;             PG8_LDB(B0, 0, 0); PG8_LDB(B1, 0, 1); PG8_SCHED; PG8_LDA(At, 0, 0); PG8_STAGE(PG8_SA(1, 1), a1 + hstepA, voffA);
;             PG8_WAIT_V(8); PG8_WAIT_L(0); PG8_BAR; PG8_MMA(0, 0, At, B0); PG8_MMA(0, 1, At, B1); PG8_BAR; PG8_SCHED;
;             PG8_LDA(At, 0, 1); PG8_STAGE(PG8_SB(0, 0), b2, voffB); PG8_STAGE(PG8_SB(0, 1), b2 + hstepB, voffB); PG8_STAGE(PG8_SA(0, 0), a2, voffA);
.LBB0_377:
	s_ashr_i32 s71, s70, 31
	s_lshl_b64 s[48:49], s[70:71], 19
	v_readlane_b32 s12, v248, 21
	s_add_u32 s72, s12, s48
	v_readlane_b32 s12, v248, 22
	s_addc_u32 s73, s12, s49
	s_and_b64 s[48:49], s[66:67], exec
	s_cselect_b32 s43, s73, s19
	s_cselect_b32 s48, s72, s18
	s_ashr_i32 s69, s68, 31
	s_lshl_b64 s[74:75], s[68:69], 19
	s_add_u32 s74, s4, s74
	s_addc_u32 s75, s5, s75
	s_and_b64 s[76:77], s[66:67], exec
	s_cselect_b32 s49, s75, s21
	s_cselect_b32 s53, s74, s20
	s_add_u32 s18, s18, 0x40080
	s_addc_u32 s19, s19, 0
	s_add_u32 s69, s20, 0x100
	s_addc_u32 s71, s21, 0
	s_mov_b32 s78, -2
	v_add_u32_e32 v255, 0x10000, v158
	s_add_u32 s20, s18, 0xfffc0080
	s_addc_u32 s21, s19, -1
	s_add_i32 s79, 0, 0x10000
	s_cmp_eq_u32 s78, 12
	s_cselect_b32 s21, s43, s21
	s_cselect_b32 s20, s48, s20
	s_cselect_b32 s77, s49, s71
	s_cselect_b32 s76, s53, s69
	s_add_u32 s100, s20, 0x80
	s_addc_u32 s101, s21, 0
	s_add_i32 s82, 0, 0x14000
	s_add_i32 m0, s9, 0xc000
	s_nop 0
	global_load_lds_dwordx4 v146, s[18:19]
	s_add_i32 m0, s9, 0xe000
	s_nop 0
	global_load_lds_dwordx4 v150, s[18:19]
	ds_read_b128 v[130:133], v255
	ds_read_b128 v[134:137], v255 offset:1024
	ds_read_b128 v[138:141], v255 offset:2048
	ds_read_b128 v[142:145], v255 offset:3072
	ds_read_b128 v[162:165], v255 offset:16384
	ds_read_b128 v[166:169], v255 offset:17408
	ds_read_b128 v[170:173], v255 offset:18432
	ds_read_b128 v[190:193], v255 offset:19456
	ds_read_b128 v[194:197], v160
	ds_read_b128 v[198:201], v160 offset:1024
	ds_read_b128 v[202:205], v160 offset:2048
	ds_read_b128 v[206:209], v160 offset:3072
	ds_read_b128 v[218:221], v160 offset:4096
	ds_read_b128 v[222:225], v160 offset:5120
	ds_read_b128 v[226:229], v160 offset:6144
	ds_read_b128 v[230:233], v160 offset:7168
	s_waitcnt vmcnt(8)
	s_waitcnt lgkmcnt(0)
	s_barrier
	s_waitcnt lgkmcnt(0)
	v_mfma_f32_16x16x32_bf16 v[126:129], v[130:133], v[194:197], 0
	v_mfma_f32_16x16x32_bf16 v[122:125], v[138:141], v[194:197], 0
	v_mfma_f32_16x16x32_bf16 v[118:121], v[130:133], v[202:205], 0
	v_mfma_f32_16x16x32_bf16 v[110:113], v[138:141], v[202:205], 0
	v_mfma_f32_16x16x32_bf16 v[102:105], v[130:133], v[218:221], 0
	v_mfma_f32_16x16x32_bf16 v[94:97], v[138:141], v[218:221], 0
	v_mfma_f32_16x16x32_bf16 v[86:89], v[130:133], v[226:229], 0
	v_mfma_f32_16x16x32_bf16 v[78:81], v[138:141], v[226:229], 0
	v_mfma_f32_16x16x32_bf16 v[126:129], v[134:137], v[198:201], v[126:129]
	v_mfma_f32_16x16x32_bf16 v[122:125], v[142:145], v[198:201], v[122:125]
	v_mfma_f32_16x16x32_bf16 v[118:121], v[134:137], v[206:209], v[118:121]
	v_mfma_f32_16x16x32_bf16 v[110:113], v[142:145], v[206:209], v[110:113]
	v_mfma_f32_16x16x32_bf16 v[102:105], v[134:137], v[222:225], v[102:105]
	v_mfma_f32_16x16x32_bf16 v[94:97], v[142:145], v[222:225], v[94:97]
	v_mfma_f32_16x16x32_bf16 v[86:89], v[134:137], v[230:233], v[86:89]
	v_mfma_f32_16x16x32_bf16 v[78:81], v[142:145], v[230:233], v[78:81]
	v_mfma_f32_16x16x32_bf16 v[114:117], v[162:165], v[194:197], 0
	v_mfma_f32_16x16x32_bf16 v[106:109], v[170:173], v[194:197], 0
	v_mfma_f32_16x16x32_bf16 v[98:101], v[162:165], v[202:205], 0
	v_mfma_f32_16x16x32_bf16 v[90:93], v[170:173], v[202:205], 0
	v_mfma_f32_16x16x32_bf16 v[82:85], v[162:165], v[218:221], 0
	v_mfma_f32_16x16x32_bf16 v[74:77], v[170:173], v[218:221], 0
	v_mfma_f32_16x16x32_bf16 v[70:73], v[162:165], v[226:229], 0
	v_mfma_f32_16x16x32_bf16 v[66:69], v[170:173], v[226:229], 0
	v_mfma_f32_16x16x32_bf16 v[114:117], v[166:169], v[198:201], v[114:117]
	v_mfma_f32_16x16x32_bf16 v[106:109], v[190:193], v[198:201], v[106:109]
	v_mfma_f32_16x16x32_bf16 v[98:101], v[166:169], v[206:209], v[98:101]
	v_mfma_f32_16x16x32_bf16 v[90:93], v[190:193], v[206:209], v[90:93]
	v_mfma_f32_16x16x32_bf16 v[82:85], v[166:169], v[222:225], v[82:85]
	v_mfma_f32_16x16x32_bf16 v[74:77], v[190:193], v[222:225], v[74:77]
	v_mfma_f32_16x16x32_bf16 v[70:73], v[166:169], v[230:233], v[70:73]
	v_mfma_f32_16x16x32_bf16 v[66:69], v[190:193], v[230:233], v[66:69]
	s_barrier
	s_add_i32 s79, s79, s8
	s_mov_b32 m0, s79
	s_nop 0
	global_load_lds_dwordx4 v148, s[76:77]
	s_add_i32 m0, s79, 0x2000
	s_add_u32 s80, s76, 0x40000
	s_addc_u32 s81, s77, 0
	s_add_i32 s79, s82, s8
	global_load_lds_dwordx4 v152, s[76:77]
	s_mov_b32 m0, s79
	s_nop 0
	global_load_lds_dwordx4 v148, s[80:81]
	s_add_i32 m0, s79, 0x2000
	s_nop 0
	global_load_lds_dwordx4 v152, s[80:81]
	s_mov_b32 m0, s9
	s_nop 0
	global_load_lds_dwordx4 v146, s[20:21]
	s_mov_b32 m0, s28
	s_nop 0
	global_load_lds_dwordx4 v150, s[20:21]
	ds_read_b128 v[194:197], v160 offset:16384
	ds_read_b128 v[198:201], v160 offset:17408
	ds_read_b128 v[202:205], v160 offset:18432
	ds_read_b128 v[206:209], v160 offset:19456
	ds_read_b128 v[218:221], v160 offset:20480
	ds_read_b128 v[222:225], v160 offset:21504
	ds_read_b128 v[226:229], v160 offset:22528
	ds_read_b128 v[230:233], v160 offset:23552
	s_waitcnt vmcnt(8)
	s_waitcnt lgkmcnt(0)
	s_barrier
; #define PG8_STAGE(bufoff, gbase, voff) do { _Pragma("unroll") for (int _i = 0; _i < 2; ++_i) \
;         __builtin_amdgcn_global_load_lds((const unsigned*)((const char*)(gbase) + (voff)[_i]), (LAS unsigned*)(lds + (bufoff) + ldsw + _i * 8192), 16, 0, 0); } while (0)
; #define PG8_LDA(dst, b, h) do { _Pragma("unroll") for (int m = 0; m < 4; ++m) _Pragma("unroll") for (int k = 0; k < 2; ++k) dst[m][k] = *(const LAS bf16x8*)(lds + PG8_SA(b, h) + aoff + m * 2048 + k * 1024); } while (0)
; #define PG8_LDB(dst, b, h) do { _Pragma("unroll") for (int n = 0; n < 2; ++n) _Pragma("unroll") for (int k = 0; k < 2; ++k) dst[n][k] = *(const LAS bf16x8*)(lds + PG8_SB(b, h) + boff + n * 2048 + k * 1024); } while (0)
; #define PG8_MMA(ai, bj, At, Bt) do { __builtin_amdgcn_s_setprio(1); _Pragma("unroll") for (int m = 0; m < 4; ++m) _Pragma("unroll") for (int n = 0; n < 2; ++n) _Pragma("unroll") for (int k = 0; k < 2; ++k) \
;         acc[ai][bj][m][n] = __builtin_amdgcn_mfma_f32_16x16x32_bf16(Bt[n][k], At[m][k], acc[ai][bj][m][n], 0, 0, 0); __builtin_amdgcn_s_setprio(0); } while (0)
; #define PG8_WAIT_V(n) asm volatile("s_waitcnt vmcnt(" #n ")" ::: "memory")
; #define PG8_WAIT_L(n) asm volatile("s_waitcnt lgkmcnt(" #n ")" ::: "memory")
; #define PG8_BAR __builtin_amdgcn_s_barrier()
; #define PG8_SCHED __builtin_amdgcn_sched_barrier(0)
; template <class Epi, class Sched>
; __device__ __forceinline__ void gemm_phase(LAS unsigned char* lds, const Gemm g, const Sched& S, const Epi& E) {
;     ...
;             PG8_WAIT_V(8); PG8_WAIT_L(0); PG8_BAR; PG8_MMA(1, 0, At, B0); PG8_MMA(1, 1, At, B1); PG8_BAR; PG8_SCHED;
;             PG8_LDB(B0, 1, 0); PG8_LDB(B1, 1, 1); PG8_SCHED; PG8_LDA(At, 1, 0); PG8_STAGE(PG8_SA(0, 1), a2 + hstepA, voffA);
;             PG8_WAIT_V(8); PG8_WAIT_L(0); PG8_BAR; PG8_MMA(0, 0, At, B0); PG8_MMA(0, 1, At, B1); PG8_BAR; PG8_SCHED;
	s_waitcnt lgkmcnt(0)
	v_mfma_f32_16x16x32_bf16 v[62:65], v[130:133], v[194:197], 0
	v_mfma_f32_16x16x32_bf16 v[58:61], v[138:141], v[194:197], 0
	v_mfma_f32_16x16x32_bf16 v[54:57], v[130:133], v[202:205], 0
	v_mfma_f32_16x16x32_bf16 v[46:49], v[138:141], v[202:205], 0
	v_mfma_f32_16x16x32_bf16 v[38:41], v[130:133], v[218:221], 0
	v_mfma_f32_16x16x32_bf16 v[30:33], v[138:141], v[218:221], 0
	v_mfma_f32_16x16x32_bf16 v[22:25], v[130:133], v[226:229], 0
	v_mfma_f32_16x16x32_bf16 v[14:17], v[138:141], v[226:229], 0
	v_mfma_f32_16x16x32_bf16 v[62:65], v[134:137], v[198:201], v[62:65]
	v_mfma_f32_16x16x32_bf16 v[58:61], v[142:145], v[198:201], v[58:61]
	v_mfma_f32_16x16x32_bf16 v[54:57], v[134:137], v[206:209], v[54:57]
	v_mfma_f32_16x16x32_bf16 v[46:49], v[142:145], v[206:209], v[46:49]
	v_mfma_f32_16x16x32_bf16 v[38:41], v[134:137], v[222:225], v[38:41]
	v_mfma_f32_16x16x32_bf16 v[30:33], v[142:145], v[222:225], v[30:33]
	v_mfma_f32_16x16x32_bf16 v[22:25], v[134:137], v[230:233], v[22:25]
	v_mfma_f32_16x16x32_bf16 v[14:17], v[142:145], v[230:233], v[14:17]
	v_mfma_f32_16x16x32_bf16 v[50:53], v[162:165], v[194:197], 0
	v_mfma_f32_16x16x32_bf16 v[42:45], v[170:173], v[194:197], 0
	v_mfma_f32_16x16x32_bf16 v[34:37], v[162:165], v[202:205], 0
	v_mfma_f32_16x16x32_bf16 v[26:29], v[170:173], v[202:205], 0
	v_mfma_f32_16x16x32_bf16 v[18:21], v[162:165], v[218:221], 0
	v_mfma_f32_16x16x32_bf16 v[10:13], v[170:173], v[218:221], 0
	v_mfma_f32_16x16x32_bf16 v[6:9], v[162:165], v[226:229], 0
	v_mfma_f32_16x16x32_bf16 v[2:5], v[170:173], v[226:229], 0
	v_mfma_f32_16x16x32_bf16 v[50:53], v[166:169], v[198:201], v[50:53]
	v_mfma_f32_16x16x32_bf16 v[42:45], v[190:193], v[198:201], v[42:45]
	v_mfma_f32_16x16x32_bf16 v[34:37], v[166:169], v[206:209], v[34:37]
	v_mfma_f32_16x16x32_bf16 v[26:29], v[190:193], v[206:209], v[26:29]
	v_mfma_f32_16x16x32_bf16 v[18:21], v[166:169], v[222:225], v[18:21]
	v_mfma_f32_16x16x32_bf16 v[10:13], v[190:193], v[222:225], v[10:13]
	v_mfma_f32_16x16x32_bf16 v[6:9], v[166:169], v[230:233], v[6:9]
	v_mfma_f32_16x16x32_bf16 v[2:5], v[190:193], v[230:233], v[2:5]
	s_barrier
	s_add_i32 s79, 0, 0x18000
	s_add_i32 s80, 0, 0x1c000
	s_add_u32 s20, s20, 0x40000
	s_addc_u32 s21, s21, 0
	s_mov_b32 m0, s29
	s_nop 0
	global_load_lds_dwordx4 v146, s[20:21]
	s_mov_b32 m0, s30
	s_nop 0
	global_load_lds_dwordx4 v150, s[20:21]
	ds_read_b128 v[130:133], v255 offset:32768
	ds_read_b128 v[134:137], v255 offset:33792
	ds_read_b128 v[138:141], v255 offset:34816
	ds_read_b128 v[142:145], v255 offset:35840
	ds_read_b128 v[162:165], v255 offset:49152
	ds_read_b128 v[166:169], v255 offset:50176
	ds_read_b128 v[170:173], v255 offset:51200
	ds_read_b128 v[190:193], v255 offset:52224
	ds_read_b128 v[194:197], v160 offset:32768
	ds_read_b128 v[198:201], v160 offset:33792
	ds_read_b128 v[202:205], v160 offset:34816
	ds_read_b128 v[206:209], v160 offset:35840
	ds_read_b128 v[218:221], v160 offset:36864
	ds_read_b128 v[222:225], v160 offset:37888
	ds_read_b128 v[226:229], v160 offset:38912
	ds_read_b128 v[230:233], v160 offset:39936
	s_waitcnt vmcnt(8)
	s_waitcnt lgkmcnt(0)
	s_barrier
	s_waitcnt lgkmcnt(0)
	v_mfma_f32_16x16x32_bf16 v[126:129], v[130:133], v[194:197], v[126:129]
	v_mfma_f32_16x16x32_bf16 v[122:125], v[138:141], v[194:197], v[122:125]
	v_mfma_f32_16x16x32_bf16 v[118:121], v[130:133], v[202:205], v[118:121]
	v_mfma_f32_16x16x32_bf16 v[110:113], v[138:141], v[202:205], v[110:113]
	v_mfma_f32_16x16x32_bf16 v[102:105], v[130:133], v[218:221], v[102:105]
	v_mfma_f32_16x16x32_bf16 v[94:97], v[138:141], v[218:221], v[94:97]
	v_mfma_f32_16x16x32_bf16 v[86:89], v[130:133], v[226:229], v[86:89]
	v_mfma_f32_16x16x32_bf16 v[78:81], v[138:141], v[226:229], v[78:81]
	v_mfma_f32_16x16x32_bf16 v[126:129], v[134:137], v[198:201], v[126:129]
	v_mfma_f32_16x16x32_bf16 v[122:125], v[142:145], v[198:201], v[122:125]
	v_mfma_f32_16x16x32_bf16 v[118:121], v[134:137], v[206:209], v[118:121]
	v_mfma_f32_16x16x32_bf16 v[110:113], v[142:145], v[206:209], v[110:113]
	v_mfma_f32_16x16x32_bf16 v[102:105], v[134:137], v[222:225], v[102:105]
	v_mfma_f32_16x16x32_bf16 v[94:97], v[142:145], v[222:225], v[94:97]
	v_mfma_f32_16x16x32_bf16 v[86:89], v[134:137], v[230:233], v[86:89]
	v_mfma_f32_16x16x32_bf16 v[78:81], v[142:145], v[230:233], v[78:81]
	v_mfma_f32_16x16x32_bf16 v[114:117], v[162:165], v[194:197], v[114:117]
	v_mfma_f32_16x16x32_bf16 v[106:109], v[170:173], v[194:197], v[106:109]
	v_mfma_f32_16x16x32_bf16 v[98:101], v[162:165], v[202:205], v[98:101]
	v_mfma_f32_16x16x32_bf16 v[90:93], v[170:173], v[202:205], v[90:93]
	v_mfma_f32_16x16x32_bf16 v[82:85], v[162:165], v[218:221], v[82:85]
	v_mfma_f32_16x16x32_bf16 v[74:77], v[170:173], v[218:221], v[74:77]
	v_mfma_f32_16x16x32_bf16 v[70:73], v[162:165], v[226:229], v[70:73]
	v_mfma_f32_16x16x32_bf16 v[66:69], v[170:173], v[226:229], v[66:69]
	v_mfma_f32_16x16x32_bf16 v[114:117], v[166:169], v[198:201], v[114:117]
	v_mfma_f32_16x16x32_bf16 v[106:109], v[190:193], v[198:201], v[106:109]
	v_mfma_f32_16x16x32_bf16 v[98:101], v[166:169], v[206:209], v[98:101]
	v_mfma_f32_16x16x32_bf16 v[90:93], v[190:193], v[206:209], v[90:93]
	v_mfma_f32_16x16x32_bf16 v[82:85], v[166:169], v[222:225], v[82:85]
	v_mfma_f32_16x16x32_bf16 v[74:77], v[190:193], v[222:225], v[74:77]
	v_mfma_f32_16x16x32_bf16 v[70:73], v[166:169], v[230:233], v[70:73]
	v_mfma_f32_16x16x32_bf16 v[66:69], v[190:193], v[230:233], v[66:69]
	s_barrier
; #define PG8_STAGE(bufoff, gbase, voff) do { _Pragma("unroll") for (int _i = 0; _i < 2; ++_i) \
;         __builtin_amdgcn_global_load_lds((const unsigned*)((const char*)(gbase) + (voff)[_i]), (LAS unsigned*)(lds + (bufoff) + ldsw + _i * 8192), 16, 0, 0); } while (0)
; #define PG8_LDA(dst, b, h) do { _Pragma("unroll") for (int m = 0; m < 4; ++m) _Pragma("unroll") for (int k = 0; k < 2; ++k) dst[m][k] = *(const LAS bf16x8*)(lds + PG8_SA(b, h) + aoff + m * 2048 + k * 1024); } while (0)
; #define PG8_LDB(dst, b, h) do { _Pragma("unroll") for (int n = 0; n < 2; ++n) _Pragma("unroll") for (int k = 0; k < 2; ++k) dst[n][k] = *(const LAS bf16x8*)(lds + PG8_SB(b, h) + boff + n * 2048 + k * 1024); } while (0)
; #define PG8_WAIT_V(n) asm volatile("s_waitcnt vmcnt(" #n ")" ::: "memory")
; #define PG8_BAR __builtin_amdgcn_s_barrier()
; template <class Epi, class Sched>
; __device__ __forceinline__ void gemm_phase(LAS unsigned char* lds, const Gemm g, const Sched& S, const Epi& E) {
;     ...
;         for (int t = 0; t < nt; t += 2) {
;             const bool last = (t == nt - 2);
;             const char* a1 = cA + (size_t)(t + 1) * kstep;
;             const char* a2 = last ? nA : cA + (size_t)(t + 2) * kstep; const char* b2 = last ? nB : cB + (size_t)(t + 2) * kstep;
;             const char* a3 = a2 + kstep; const char* b3 = b2 + kstep;
;             PG8_LDB(B0, 0, 0); PG8_LDB(B1, 0, 1); PG8_SCHED; PG8_LDA(At, 0, 0); PG8_STAGE(PG8_SA(1, 1), a1 + hstepA, voffA);
;             PG8_WAIT_V(8); PG8_WAIT_L(0); PG8_BAR; PG8_MMA(0, 0, At, B0); PG8_MMA(0, 1, At, B1); PG8_BAR; PG8_SCHED;
;             PG8_LDA(At, 0, 1); PG8_STAGE(PG8_SB(0, 0), b2, voffB); PG8_STAGE(PG8_SB(0, 1), b2 + hstepB, voffB); PG8_STAGE(PG8_SA(0, 0), a2, voffA);
;             PG8_WAIT_V(8); PG8_WAIT_L(0); PG8_BAR; PG8_MMA(1, 0, At, B0); PG8_MMA(1, 1, At, B1); PG8_BAR; PG8_SCHED;
;             PG8_LDB(B0, 1, 0); PG8_LDB(B1, 1, 1); PG8_SCHED; PG8_LDA(At, 1, 0); PG8_STAGE(PG8_SA(0, 1), a2 + hstepA, voffA);
;             PG8_WAIT_V(8); PG8_WAIT_L(0); PG8_BAR; PG8_MMA(0, 0, At, B0); PG8_MMA(0, 1, At, B1); PG8_BAR; PG8_SCHED;
;             PG8_LDA(At, 1, 1); PG8_STAGE(PG8_SB(1, 0), b3, voffB); PG8_STAGE(PG8_SB(1, 1), b3 + hstepB, voffB); PG8_STAGE(PG8_SA(1, 0), a3, voffA);
;             PG8_WAIT_V(8); PG8_WAIT_L(0); PG8_BAR; PG8_MMA(1, 0, At, B0); PG8_MMA(1, 1, At, B1); PG8_BAR; PG8_SCHED;
	s_add_i32 s20, s8, 0x18000
	s_add_u32 s80, s76, 0x80
	s_addc_u32 s81, s77, 0
	s_mov_b32 m0, s20
	s_nop 0
	global_load_lds_dwordx4 v148, s[80:81]
	s_add_i32 m0, s20, 0x2000
	s_add_u32 s20, s76, 0x40080
	s_addc_u32 s21, s77, 0
	s_add_i32 s12, s8, 0x1c000
	global_load_lds_dwordx4 v152, s[80:81]
	s_mov_b32 m0, s12
	s_nop 0
	global_load_lds_dwordx4 v148, s[20:21]
	s_add_i32 m0, s12, 0x2000
	s_nop 0
	global_load_lds_dwordx4 v152, s[20:21]
	s_mov_b32 m0, s31
	s_nop 0
	global_load_lds_dwordx4 v146, s[100:101]
	s_mov_b32 m0, s34
	s_nop 0
	global_load_lds_dwordx4 v150, s[100:101]
	ds_read_b128 v[194:197], v160 offset:49152
	ds_read_b128 v[198:201], v160 offset:50176
	ds_read_b128 v[202:205], v160 offset:51200
	ds_read_b128 v[206:209], v160 offset:52224
	ds_read_b128 v[218:221], v160 offset:53248
	ds_read_b128 v[222:225], v160 offset:54272
	ds_read_b128 v[226:229], v160 offset:55296
	ds_read_b128 v[230:233], v160 offset:56320
	s_waitcnt vmcnt(8)
	s_waitcnt lgkmcnt(0)
	s_barrier
	s_waitcnt lgkmcnt(0)
	v_mfma_f32_16x16x32_bf16 v[62:65], v[130:133], v[194:197], v[62:65]
	v_mfma_f32_16x16x32_bf16 v[58:61], v[138:141], v[194:197], v[58:61]
	v_mfma_f32_16x16x32_bf16 v[54:57], v[130:133], v[202:205], v[54:57]
	v_mfma_f32_16x16x32_bf16 v[46:49], v[138:141], v[202:205], v[46:49]
	v_mfma_f32_16x16x32_bf16 v[38:41], v[130:133], v[218:221], v[38:41]
	v_mfma_f32_16x16x32_bf16 v[30:33], v[138:141], v[218:221], v[30:33]
	v_mfma_f32_16x16x32_bf16 v[22:25], v[130:133], v[226:229], v[22:25]
	v_mfma_f32_16x16x32_bf16 v[14:17], v[138:141], v[226:229], v[14:17]
	v_mfma_f32_16x16x32_bf16 v[62:65], v[134:137], v[198:201], v[62:65]
	v_mfma_f32_16x16x32_bf16 v[58:61], v[142:145], v[198:201], v[58:61]
	v_mfma_f32_16x16x32_bf16 v[54:57], v[134:137], v[206:209], v[54:57]
	v_mfma_f32_16x16x32_bf16 v[46:49], v[142:145], v[206:209], v[46:49]
	v_mfma_f32_16x16x32_bf16 v[38:41], v[134:137], v[222:225], v[38:41]
	v_mfma_f32_16x16x32_bf16 v[30:33], v[142:145], v[222:225], v[30:33]
	v_mfma_f32_16x16x32_bf16 v[22:25], v[134:137], v[230:233], v[22:25]
	v_mfma_f32_16x16x32_bf16 v[14:17], v[142:145], v[230:233], v[14:17]
	v_mfma_f32_16x16x32_bf16 v[50:53], v[162:165], v[194:197], v[50:53]
	v_mfma_f32_16x16x32_bf16 v[42:45], v[170:173], v[194:197], v[42:45]
	v_mfma_f32_16x16x32_bf16 v[34:37], v[162:165], v[202:205], v[34:37]
	v_mfma_f32_16x16x32_bf16 v[26:29], v[170:173], v[202:205], v[26:29]
	v_mfma_f32_16x16x32_bf16 v[18:21], v[162:165], v[218:221], v[18:21]
	v_mfma_f32_16x16x32_bf16 v[10:13], v[170:173], v[218:221], v[10:13]
	v_mfma_f32_16x16x32_bf16 v[6:9], v[162:165], v[226:229], v[6:9]
	v_mfma_f32_16x16x32_bf16 v[2:5], v[170:173], v[226:229], v[2:5]
	v_mfma_f32_16x16x32_bf16 v[50:53], v[166:169], v[198:201], v[50:53]
	v_mfma_f32_16x16x32_bf16 v[42:45], v[190:193], v[198:201], v[42:45]
	v_mfma_f32_16x16x32_bf16 v[34:37], v[166:169], v[206:209], v[34:37]
	v_mfma_f32_16x16x32_bf16 v[26:29], v[190:193], v[206:209], v[26:29]
	v_mfma_f32_16x16x32_bf16 v[18:21], v[166:169], v[222:225], v[18:21]
	v_mfma_f32_16x16x32_bf16 v[10:13], v[190:193], v[222:225], v[10:13]
	v_mfma_f32_16x16x32_bf16 v[6:9], v[166:169], v[230:233], v[6:9]
	v_mfma_f32_16x16x32_bf16 v[2:5], v[190:193], v[230:233], v[2:5]
	s_add_i32 s78, s78, 2
	s_add_u32 s18, s18, 0x100
	s_addc_u32 s19, s19, 0
	s_add_u32 s69, s69, 0x100
	s_addc_u32 s71, s71, 0
	s_cmp_gt_u32 s78, 13
.LBB0_378:
	s_barrier
	s_add_u32 s20, s18, 0xfffc0080
	s_addc_u32 s21, s19, -1
	s_add_i32 s79, 0, 0x10000
	s_cmp_eq_u32 s78, 12
	s_cselect_b32 s21, s43, s21
	s_cselect_b32 s20, s48, s20
	s_cselect_b32 s77, s49, s71
	s_cselect_b32 s76, s53, s69
	s_add_u32 s100, s20, 0x80
	s_addc_u32 s101, s21, 0
	s_add_i32 s82, 0, 0x14000
	s_add_i32 m0, s9, 0xc000
	s_nop 0
	global_load_lds_dwordx4 v146, s[18:19]
	s_add_i32 m0, s9, 0xe000
	s_nop 0
	global_load_lds_dwordx4 v150, s[18:19]
	ds_read_b128 v[130:133], v255
	ds_read_b128 v[134:137], v255 offset:1024
	ds_read_b128 v[138:141], v255 offset:2048
	ds_read_b128 v[142:145], v255 offset:3072
	ds_read_b128 v[162:165], v255 offset:16384
	ds_read_b128 v[166:169], v255 offset:17408
	ds_read_b128 v[170:173], v255 offset:18432
	ds_read_b128 v[190:193], v255 offset:19456
	ds_read_b128 v[194:197], v160
	ds_read_b128 v[198:201], v160 offset:1024
	ds_read_b128 v[202:205], v160 offset:2048
	ds_read_b128 v[206:209], v160 offset:3072
	ds_read_b128 v[218:221], v160 offset:4096
	ds_read_b128 v[222:225], v160 offset:5120
	ds_read_b128 v[226:229], v160 offset:6144
	ds_read_b128 v[230:233], v160 offset:7168
	s_waitcnt vmcnt(8)
	s_waitcnt lgkmcnt(0)
	s_barrier
; #define PG8_STAGE(bufoff, gbase, voff) do { _Pragma("unroll") for (int _i = 0; _i < 2; ++_i) \
;         __builtin_amdgcn_global_load_lds((const unsigned*)((const char*)(gbase) + (voff)[_i]), (LAS unsigned*)(lds + (bufoff) + ldsw + _i * 8192), 16, 0, 0); } while (0)
; #define PG8_LDA(dst, b, h) do { _Pragma("unroll") for (int m = 0; m < 4; ++m) _Pragma("unroll") for (int k = 0; k < 2; ++k) dst[m][k] = *(const LAS bf16x8*)(lds + PG8_SA(b, h) + aoff + m * 2048 + k * 1024); } while (0)
; #define PG8_LDB(dst, b, h) do { _Pragma("unroll") for (int n = 0; n < 2; ++n) _Pragma("unroll") for (int k = 0; k < 2; ++k) dst[n][k] = *(const LAS bf16x8*)(lds + PG8_SB(b, h) + boff + n * 2048 + k * 1024); } while (0)
; #define PG8_MMA(ai, bj, At, Bt) do { __builtin_amdgcn_s_setprio(1); _Pragma("unroll") for (int m = 0; m < 4; ++m) _Pragma("unroll") for (int n = 0; n < 2; ++n) _Pragma("unroll") for (int k = 0; k < 2; ++k) \
;         acc[ai][bj][m][n] = __builtin_amdgcn_mfma_f32_16x16x32_bf16(Bt[n][k], At[m][k], acc[ai][bj][m][n], 0, 0, 0); __builtin_amdgcn_s_setprio(0); } while (0)
; #define PG8_WAIT_V(n) asm volatile("s_waitcnt vmcnt(" #n ")" ::: "memory")
; #define PG8_WAIT_L(n) asm volatile("s_waitcnt lgkmcnt(" #n ")" ::: "memory")
; #define PG8_BAR __builtin_amdgcn_s_barrier()
; #define PG8_SCHED __builtin_amdgcn_sched_barrier(0)
; template <class Epi, class Sched>
; __device__ __forceinline__ void gemm_phase(LAS unsigned char* lds, const Gemm g, const Sched& S, const Epi& E) {
;     ...
;             PG8_WAIT_V(8); PG8_WAIT_L(0); PG8_BAR; PG8_MMA(0, 0, At, B0); PG8_MMA(0, 1, At, B1); PG8_BAR; PG8_SCHED;
;             PG8_LDA(At, 0, 1); PG8_STAGE(PG8_SB(0, 0), b2, voffB); PG8_STAGE(PG8_SB(0, 1), b2 + hstepB, voffB); PG8_STAGE(PG8_SA(0, 0), a2, voffA);
;             PG8_WAIT_V(8); PG8_WAIT_L(0); PG8_BAR; PG8_MMA(1, 0, At, B0); PG8_MMA(1, 1, At, B1); PG8_BAR; PG8_SCHED;
;             PG8_LDB(B0, 1, 0); PG8_LDB(B1, 1, 1); PG8_SCHED; PG8_LDA(At, 1, 0); PG8_STAGE(PG8_SA(0, 1), a2 + hstepA, voffA);
;             PG8_WAIT_V(8); PG8_WAIT_L(0); PG8_BAR; PG8_MMA(0, 0, At, B0); PG8_MMA(0, 1, At, B1); PG8_BAR; PG8_SCHED;
	s_waitcnt lgkmcnt(0)
	v_mfma_f32_16x16x32_bf16 v[126:129], v[130:133], v[194:197], v[126:129]
	v_mfma_f32_16x16x32_bf16 v[122:125], v[138:141], v[194:197], v[122:125]
	v_mfma_f32_16x16x32_bf16 v[118:121], v[130:133], v[202:205], v[118:121]
	v_mfma_f32_16x16x32_bf16 v[110:113], v[138:141], v[202:205], v[110:113]
	v_mfma_f32_16x16x32_bf16 v[102:105], v[130:133], v[218:221], v[102:105]
	v_mfma_f32_16x16x32_bf16 v[94:97], v[138:141], v[218:221], v[94:97]
	v_mfma_f32_16x16x32_bf16 v[86:89], v[130:133], v[226:229], v[86:89]
	v_mfma_f32_16x16x32_bf16 v[78:81], v[138:141], v[226:229], v[78:81]
	v_mfma_f32_16x16x32_bf16 v[126:129], v[134:137], v[198:201], v[126:129]
	v_mfma_f32_16x16x32_bf16 v[122:125], v[142:145], v[198:201], v[122:125]
	v_mfma_f32_16x16x32_bf16 v[118:121], v[134:137], v[206:209], v[118:121]
	v_mfma_f32_16x16x32_bf16 v[110:113], v[142:145], v[206:209], v[110:113]
	v_mfma_f32_16x16x32_bf16 v[102:105], v[134:137], v[222:225], v[102:105]
	v_mfma_f32_16x16x32_bf16 v[94:97], v[142:145], v[222:225], v[94:97]
	v_mfma_f32_16x16x32_bf16 v[86:89], v[134:137], v[230:233], v[86:89]
	v_mfma_f32_16x16x32_bf16 v[78:81], v[142:145], v[230:233], v[78:81]
	v_mfma_f32_16x16x32_bf16 v[114:117], v[162:165], v[194:197], v[114:117]
	v_mfma_f32_16x16x32_bf16 v[106:109], v[170:173], v[194:197], v[106:109]
	v_mfma_f32_16x16x32_bf16 v[98:101], v[162:165], v[202:205], v[98:101]
	v_mfma_f32_16x16x32_bf16 v[90:93], v[170:173], v[202:205], v[90:93]
	v_mfma_f32_16x16x32_bf16 v[82:85], v[162:165], v[218:221], v[82:85]
	v_mfma_f32_16x16x32_bf16 v[74:77], v[170:173], v[218:221], v[74:77]
	v_mfma_f32_16x16x32_bf16 v[70:73], v[162:165], v[226:229], v[70:73]
	v_mfma_f32_16x16x32_bf16 v[66:69], v[170:173], v[226:229], v[66:69]
	v_mfma_f32_16x16x32_bf16 v[114:117], v[166:169], v[198:201], v[114:117]
	v_mfma_f32_16x16x32_bf16 v[106:109], v[190:193], v[198:201], v[106:109]
	v_mfma_f32_16x16x32_bf16 v[98:101], v[166:169], v[206:209], v[98:101]
	v_mfma_f32_16x16x32_bf16 v[90:93], v[190:193], v[206:209], v[90:93]
	v_mfma_f32_16x16x32_bf16 v[82:85], v[166:169], v[222:225], v[82:85]
	v_mfma_f32_16x16x32_bf16 v[74:77], v[190:193], v[222:225], v[74:77]
	v_mfma_f32_16x16x32_bf16 v[70:73], v[166:169], v[230:233], v[70:73]
	v_mfma_f32_16x16x32_bf16 v[66:69], v[190:193], v[230:233], v[66:69]
	s_barrier
	s_add_i32 s79, s79, s8
	s_mov_b32 m0, s79
	s_nop 0
	global_load_lds_dwordx4 v148, s[76:77]
	s_add_i32 m0, s79, 0x2000
	s_add_u32 s80, s76, 0x40000
	s_addc_u32 s81, s77, 0
	s_add_i32 s79, s82, s8
	global_load_lds_dwordx4 v152, s[76:77]
	s_mov_b32 m0, s79
	s_nop 0
	global_load_lds_dwordx4 v148, s[80:81]
	s_add_i32 m0, s79, 0x2000
	s_nop 0
	global_load_lds_dwordx4 v152, s[80:81]
	s_mov_b32 m0, s9
	s_nop 0
	global_load_lds_dwordx4 v146, s[20:21]
	s_mov_b32 m0, s28
	s_nop 0
	global_load_lds_dwordx4 v150, s[20:21]
	ds_read_b128 v[194:197], v160 offset:16384
	ds_read_b128 v[198:201], v160 offset:17408
	ds_read_b128 v[202:205], v160 offset:18432
	ds_read_b128 v[206:209], v160 offset:19456
	ds_read_b128 v[218:221], v160 offset:20480
	ds_read_b128 v[222:225], v160 offset:21504
	ds_read_b128 v[226:229], v160 offset:22528
	ds_read_b128 v[230:233], v160 offset:23552
	s_waitcnt vmcnt(8)
	s_waitcnt lgkmcnt(0)
	s_barrier
	s_waitcnt lgkmcnt(0)
	v_mfma_f32_16x16x32_bf16 v[62:65], v[130:133], v[194:197], v[62:65]
	v_mfma_f32_16x16x32_bf16 v[58:61], v[138:141], v[194:197], v[58:61]
	v_mfma_f32_16x16x32_bf16 v[54:57], v[130:133], v[202:205], v[54:57]
	v_mfma_f32_16x16x32_bf16 v[46:49], v[138:141], v[202:205], v[46:49]
	v_mfma_f32_16x16x32_bf16 v[38:41], v[130:133], v[218:221], v[38:41]
	v_mfma_f32_16x16x32_bf16 v[30:33], v[138:141], v[218:221], v[30:33]
	v_mfma_f32_16x16x32_bf16 v[22:25], v[130:133], v[226:229], v[22:25]
	v_mfma_f32_16x16x32_bf16 v[14:17], v[138:141], v[226:229], v[14:17]
	v_mfma_f32_16x16x32_bf16 v[62:65], v[134:137], v[198:201], v[62:65]
	v_mfma_f32_16x16x32_bf16 v[58:61], v[142:145], v[198:201], v[58:61]
	v_mfma_f32_16x16x32_bf16 v[54:57], v[134:137], v[206:209], v[54:57]
	v_mfma_f32_16x16x32_bf16 v[46:49], v[142:145], v[206:209], v[46:49]
	v_mfma_f32_16x16x32_bf16 v[38:41], v[134:137], v[222:225], v[38:41]
	v_mfma_f32_16x16x32_bf16 v[30:33], v[142:145], v[222:225], v[30:33]
	v_mfma_f32_16x16x32_bf16 v[22:25], v[134:137], v[230:233], v[22:25]
	v_mfma_f32_16x16x32_bf16 v[14:17], v[142:145], v[230:233], v[14:17]
	v_mfma_f32_16x16x32_bf16 v[50:53], v[162:165], v[194:197], v[50:53]
	v_mfma_f32_16x16x32_bf16 v[42:45], v[170:173], v[194:197], v[42:45]
	v_mfma_f32_16x16x32_bf16 v[34:37], v[162:165], v[202:205], v[34:37]
	v_mfma_f32_16x16x32_bf16 v[26:29], v[170:173], v[202:205], v[26:29]
	v_mfma_f32_16x16x32_bf16 v[18:21], v[162:165], v[218:221], v[18:21]
	v_mfma_f32_16x16x32_bf16 v[10:13], v[170:173], v[218:221], v[10:13]
	v_mfma_f32_16x16x32_bf16 v[6:9], v[162:165], v[226:229], v[6:9]
	v_mfma_f32_16x16x32_bf16 v[2:5], v[170:173], v[226:229], v[2:5]
	v_mfma_f32_16x16x32_bf16 v[50:53], v[166:169], v[198:201], v[50:53]
	v_mfma_f32_16x16x32_bf16 v[42:45], v[190:193], v[198:201], v[42:45]
	v_mfma_f32_16x16x32_bf16 v[34:37], v[166:169], v[206:209], v[34:37]
	v_mfma_f32_16x16x32_bf16 v[26:29], v[190:193], v[206:209], v[26:29]
	v_mfma_f32_16x16x32_bf16 v[18:21], v[166:169], v[222:225], v[18:21]
	v_mfma_f32_16x16x32_bf16 v[10:13], v[190:193], v[222:225], v[10:13]
	v_mfma_f32_16x16x32_bf16 v[6:9], v[166:169], v[230:233], v[6:9]
	v_mfma_f32_16x16x32_bf16 v[2:5], v[190:193], v[230:233], v[2:5]
	s_barrier
; #define PG8_STAGE(bufoff, gbase, voff) do { _Pragma("unroll") for (int _i = 0; _i < 2; ++_i) \
;         __builtin_amdgcn_global_load_lds((const unsigned*)((const char*)(gbase) + (voff)[_i]), (LAS unsigned*)(lds + (bufoff) + ldsw + _i * 8192), 16, 0, 0); } while (0)
; #define PG8_LDA(dst, b, h) do { _Pragma("unroll") for (int m = 0; m < 4; ++m) _Pragma("unroll") for (int k = 0; k < 2; ++k) dst[m][k] = *(const LAS bf16x8*)(lds + PG8_SA(b, h) + aoff + m * 2048 + k * 1024); } while (0)
; #define PG8_LDB(dst, b, h) do { _Pragma("unroll") for (int n = 0; n < 2; ++n) _Pragma("unroll") for (int k = 0; k < 2; ++k) dst[n][k] = *(const LAS bf16x8*)(lds + PG8_SB(b, h) + boff + n * 2048 + k * 1024); } while (0)
; #define PG8_MMA(ai, bj, At, Bt) do { __builtin_amdgcn_s_setprio(1); _Pragma("unroll") for (int m = 0; m < 4; ++m) _Pragma("unroll") for (int n = 0; n < 2; ++n) _Pragma("unroll") for (int k = 0; k < 2; ++k) \
;         acc[ai][bj][m][n] = __builtin_amdgcn_mfma_f32_16x16x32_bf16(Bt[n][k], At[m][k], acc[ai][bj][m][n], 0, 0, 0); __builtin_amdgcn_s_setprio(0); } while (0)
; #define PG8_WAIT_V(n) asm volatile("s_waitcnt vmcnt(" #n ")" ::: "memory")
; #define PG8_WAIT_L(n) asm volatile("s_waitcnt lgkmcnt(" #n ")" ::: "memory")
; #define PG8_BAR __builtin_amdgcn_s_barrier()
; #define PG8_SCHED __builtin_amdgcn_sched_barrier(0)
; template <class Epi, class Sched>
; __device__ __forceinline__ void gemm_phase(LAS unsigned char* lds, const Gemm g, const Sched& S, const Epi& E) {
;     ...
;             PG8_LDB(B0, 1, 0); PG8_LDB(B1, 1, 1); PG8_SCHED; PG8_LDA(At, 1, 0); PG8_STAGE(PG8_SA(0, 1), a2 + hstepA, voffA);
;             PG8_WAIT_V(8); PG8_WAIT_L(0); PG8_BAR; PG8_MMA(0, 0, At, B0); PG8_MMA(0, 1, At, B1); PG8_BAR; PG8_SCHED;
;             PG8_LDA(At, 1, 1); PG8_STAGE(PG8_SB(1, 0), b3, voffB); PG8_STAGE(PG8_SB(1, 1), b3 + hstepB, voffB); PG8_STAGE(PG8_SA(1, 0), a3, voffA);
;             PG8_WAIT_V(8); PG8_WAIT_L(0); PG8_BAR; PG8_MMA(1, 0, At, B0); PG8_MMA(1, 1, At, B1); PG8_BAR; PG8_SCHED;
;         }
;         if (wr == 0) PG8_BAR;
	s_add_i32 s79, 0, 0x18000
	s_add_i32 s80, 0, 0x1c000
	s_add_u32 s20, s20, 0x40000
	s_addc_u32 s21, s21, 0
	s_mov_b32 m0, s29
	s_nop 0
	global_load_lds_dwordx4 v146, s[20:21]
	s_mov_b32 m0, s30
	s_nop 0
	global_load_lds_dwordx4 v150, s[20:21]
	ds_read_b128 v[130:133], v255 offset:32768
	ds_read_b128 v[134:137], v255 offset:33792
	ds_read_b128 v[138:141], v255 offset:34816
	ds_read_b128 v[142:145], v255 offset:35840
	ds_read_b128 v[162:165], v255 offset:49152
	ds_read_b128 v[166:169], v255 offset:50176
	ds_read_b128 v[170:173], v255 offset:51200
	ds_read_b128 v[190:193], v255 offset:52224
	ds_read_b128 v[194:197], v160 offset:32768
	ds_read_b128 v[198:201], v160 offset:33792
	ds_read_b128 v[202:205], v160 offset:34816
	ds_read_b128 v[206:209], v160 offset:35840
	ds_read_b128 v[218:221], v160 offset:36864
	ds_read_b128 v[222:225], v160 offset:37888
	ds_read_b128 v[226:229], v160 offset:38912
	ds_read_b128 v[230:233], v160 offset:39936
	s_waitcnt vmcnt(8)
	s_waitcnt lgkmcnt(0)
	s_barrier
	s_waitcnt lgkmcnt(0)
	v_mfma_f32_16x16x32_bf16 v[126:129], v[130:133], v[194:197], v[126:129]
	v_mfma_f32_16x16x32_bf16 v[122:125], v[138:141], v[194:197], v[122:125]
	v_mfma_f32_16x16x32_bf16 v[118:121], v[130:133], v[202:205], v[118:121]
	v_mfma_f32_16x16x32_bf16 v[110:113], v[138:141], v[202:205], v[110:113]
	v_mfma_f32_16x16x32_bf16 v[102:105], v[130:133], v[218:221], v[102:105]
	v_mfma_f32_16x16x32_bf16 v[94:97], v[138:141], v[218:221], v[94:97]
	v_mfma_f32_16x16x32_bf16 v[86:89], v[130:133], v[226:229], v[86:89]
	v_mfma_f32_16x16x32_bf16 v[78:81], v[138:141], v[226:229], v[78:81]
	v_mfma_f32_16x16x32_bf16 v[126:129], v[134:137], v[198:201], v[126:129]
	v_mfma_f32_16x16x32_bf16 v[122:125], v[142:145], v[198:201], v[122:125]
	v_mfma_f32_16x16x32_bf16 v[118:121], v[134:137], v[206:209], v[118:121]
	v_mfma_f32_16x16x32_bf16 v[110:113], v[142:145], v[206:209], v[110:113]
	v_mfma_f32_16x16x32_bf16 v[102:105], v[134:137], v[222:225], v[102:105]
	v_mfma_f32_16x16x32_bf16 v[94:97], v[142:145], v[222:225], v[94:97]
	v_mfma_f32_16x16x32_bf16 v[86:89], v[134:137], v[230:233], v[86:89]
	v_mfma_f32_16x16x32_bf16 v[78:81], v[142:145], v[230:233], v[78:81]
	v_mfma_f32_16x16x32_bf16 v[114:117], v[162:165], v[194:197], v[114:117]
	v_mfma_f32_16x16x32_bf16 v[106:109], v[170:173], v[194:197], v[106:109]
	v_mfma_f32_16x16x32_bf16 v[98:101], v[162:165], v[202:205], v[98:101]
	v_mfma_f32_16x16x32_bf16 v[90:93], v[170:173], v[202:205], v[90:93]
	v_mfma_f32_16x16x32_bf16 v[82:85], v[162:165], v[218:221], v[82:85]
	v_mfma_f32_16x16x32_bf16 v[74:77], v[170:173], v[218:221], v[74:77]
	v_mfma_f32_16x16x32_bf16 v[70:73], v[162:165], v[226:229], v[70:73]
	v_mfma_f32_16x16x32_bf16 v[66:69], v[170:173], v[226:229], v[66:69]
	v_mfma_f32_16x16x32_bf16 v[114:117], v[166:169], v[198:201], v[114:117]
	v_mfma_f32_16x16x32_bf16 v[106:109], v[190:193], v[198:201], v[106:109]
	v_mfma_f32_16x16x32_bf16 v[98:101], v[166:169], v[206:209], v[98:101]
	v_mfma_f32_16x16x32_bf16 v[90:93], v[190:193], v[206:209], v[90:93]
	v_mfma_f32_16x16x32_bf16 v[82:85], v[166:169], v[222:225], v[82:85]
	v_mfma_f32_16x16x32_bf16 v[74:77], v[190:193], v[222:225], v[74:77]
	v_mfma_f32_16x16x32_bf16 v[70:73], v[166:169], v[230:233], v[70:73]
	v_mfma_f32_16x16x32_bf16 v[66:69], v[190:193], v[230:233], v[66:69]
	s_barrier
	s_add_i32 s20, s8, 0x18000
	s_add_u32 s80, s76, 0x80
	s_addc_u32 s81, s77, 0
	s_mov_b32 m0, s20
	s_nop 0
	global_load_lds_dwordx4 v148, s[80:81]
	s_add_i32 m0, s20, 0x2000
	s_add_u32 s20, s76, 0x40080
	s_addc_u32 s21, s77, 0
	s_add_i32 s12, s8, 0x1c000
	global_load_lds_dwordx4 v152, s[80:81]
	s_mov_b32 m0, s12
	s_nop 0
	global_load_lds_dwordx4 v148, s[20:21]
	s_add_i32 m0, s12, 0x2000
	s_nop 0
	global_load_lds_dwordx4 v152, s[20:21]
	s_mov_b32 m0, s31
	s_nop 0
	global_load_lds_dwordx4 v146, s[100:101]
	s_mov_b32 m0, s34
	s_nop 0
	global_load_lds_dwordx4 v150, s[100:101]
	ds_read_b128 v[194:197], v160 offset:49152
	ds_read_b128 v[198:201], v160 offset:50176
	ds_read_b128 v[202:205], v160 offset:51200
	ds_read_b128 v[206:209], v160 offset:52224
	ds_read_b128 v[218:221], v160 offset:53248
	ds_read_b128 v[222:225], v160 offset:54272
	ds_read_b128 v[226:229], v160 offset:55296
	ds_read_b128 v[230:233], v160 offset:56320
	s_waitcnt vmcnt(8)
	s_waitcnt lgkmcnt(0)
	s_barrier
	s_waitcnt lgkmcnt(0)
	v_mfma_f32_16x16x32_bf16 v[62:65], v[130:133], v[194:197], v[62:65]
	v_mfma_f32_16x16x32_bf16 v[58:61], v[138:141], v[194:197], v[58:61]
	v_mfma_f32_16x16x32_bf16 v[54:57], v[130:133], v[202:205], v[54:57]
	v_mfma_f32_16x16x32_bf16 v[46:49], v[138:141], v[202:205], v[46:49]
	v_mfma_f32_16x16x32_bf16 v[38:41], v[130:133], v[218:221], v[38:41]
	v_mfma_f32_16x16x32_bf16 v[30:33], v[138:141], v[218:221], v[30:33]
	v_mfma_f32_16x16x32_bf16 v[22:25], v[130:133], v[226:229], v[22:25]
	v_mfma_f32_16x16x32_bf16 v[14:17], v[138:141], v[226:229], v[14:17]
	v_mfma_f32_16x16x32_bf16 v[62:65], v[134:137], v[198:201], v[62:65]
	v_mfma_f32_16x16x32_bf16 v[58:61], v[142:145], v[198:201], v[58:61]
	v_mfma_f32_16x16x32_bf16 v[54:57], v[134:137], v[206:209], v[54:57]
	v_mfma_f32_16x16x32_bf16 v[46:49], v[142:145], v[206:209], v[46:49]
	v_mfma_f32_16x16x32_bf16 v[38:41], v[134:137], v[222:225], v[38:41]
	v_mfma_f32_16x16x32_bf16 v[30:33], v[142:145], v[222:225], v[30:33]
	v_mfma_f32_16x16x32_bf16 v[22:25], v[134:137], v[230:233], v[22:25]
	v_mfma_f32_16x16x32_bf16 v[14:17], v[142:145], v[230:233], v[14:17]
	v_mfma_f32_16x16x32_bf16 v[50:53], v[162:165], v[194:197], v[50:53]
	v_mfma_f32_16x16x32_bf16 v[42:45], v[170:173], v[194:197], v[42:45]
	v_mfma_f32_16x16x32_bf16 v[34:37], v[162:165], v[202:205], v[34:37]
	v_mfma_f32_16x16x32_bf16 v[26:29], v[170:173], v[202:205], v[26:29]
	v_mfma_f32_16x16x32_bf16 v[18:21], v[162:165], v[218:221], v[18:21]
	v_mfma_f32_16x16x32_bf16 v[10:13], v[170:173], v[218:221], v[10:13]
	v_mfma_f32_16x16x32_bf16 v[6:9], v[162:165], v[226:229], v[6:9]
	v_mfma_f32_16x16x32_bf16 v[2:5], v[170:173], v[226:229], v[2:5]
	v_mfma_f32_16x16x32_bf16 v[50:53], v[166:169], v[198:201], v[50:53]
	v_mfma_f32_16x16x32_bf16 v[42:45], v[190:193], v[198:201], v[42:45]
	v_mfma_f32_16x16x32_bf16 v[34:37], v[166:169], v[206:209], v[34:37]
	v_mfma_f32_16x16x32_bf16 v[26:29], v[190:193], v[206:209], v[26:29]
	v_mfma_f32_16x16x32_bf16 v[18:21], v[166:169], v[222:225], v[18:21]
	v_mfma_f32_16x16x32_bf16 v[10:13], v[190:193], v[222:225], v[10:13]
	v_mfma_f32_16x16x32_bf16 v[6:9], v[166:169], v[230:233], v[6:9]
	v_mfma_f32_16x16x32_bf16 v[2:5], v[190:193], v[230:233], v[2:5]
	s_add_i32 s78, s78, 2
	s_add_u32 s18, s18, 0x100
	s_addc_u32 s19, s19, 0
	s_add_u32 s69, s69, 0x100
	s_addc_u32 s71, s71, 0
	s_cmp_gt_u32 s78, 13
	s_cbranch_scc0 .LBB0_378
	s_barrier
	s_and_b64 vcc, exec, s[36:37]
	s_cbranch_vccz .LBB0_381
	s_barrier

; #define PG8_STAGE(bufoff, gbase, voff) do { _Pragma("unroll") for (int _i = 0; _i < 2; ++_i) \
;         __builtin_amdgcn_global_load_lds((const unsigned*)((const char*)(gbase) + (voff)[_i]), (LAS unsigned*)(lds + (bufoff) + ldsw + _i * 8192), 16, 0, 0); } while (0)
; #define PG8_LDA(dst, b, h) do { _Pragma("unroll") for (int m = 0; m < 4; ++m) _Pragma("unroll") for (int k = 0; k < 2; ++k) dst[m][k] = *(const LAS bf16x8*)(lds + PG8_SA(b, h) + aoff + m * 2048 + k * 1024); } while (0)
; #define PG8_LDB(dst, b, h) do { _Pragma("unroll") for (int n = 0; n < 2; ++n) _Pragma("unroll") for (int k = 0; k < 2; ++k) dst[n][k] = *(const LAS bf16x8*)(lds + PG8_SB(b, h) + boff + n * 2048 + k * 1024); } while (0)
; #define PG8_MMA(ai, bj, At, Bt) do { __builtin_amdgcn_s_setprio(1); _Pragma("unroll") for (int m = 0; m < 4; ++m) _Pragma("unroll") for (int n = 0; n < 2; ++n) _Pragma("unroll") for (int k = 0; k < 2; ++k) \
;         acc[ai][bj][m][n] = __builtin_amdgcn_mfma_f32_16x16x32_bf16(Bt[n][k], At[m][k], acc[ai][bj][m][n], 0, 0, 0); __builtin_amdgcn_s_setprio(0); } while (0)
; #define PG8_WAIT_V(n) asm volatile("s_waitcnt vmcnt(" #n ")" ::: "memory")
; #define PG8_WAIT_L(n) asm volatile("s_waitcnt lgkmcnt(" #n ")" ::: "memory")
; #define PG8_BAR __builtin_amdgcn_s_barrier()
; #define PG8_SCHED __builtin_amdgcn_sched_barrier(0)
; template <class Epi, class Sched>
; __device__ __forceinline__ void gemm_phase(LAS unsigned char* lds, const Gemm g, const Sched& S, const Epi& E) {
;     ...
;         for (int t = 0; t < nt; t += 2) {
;             const bool last = (t == nt - 2);
;             const char* a1 = cA + (size_t)(t + 1) * kstep;
;             const char* a2 = last ? nA : cA + (size_t)(t + 2) * kstep; const char* b2 = last ? nB : cB + (size_t)(t + 2) * kstep;
;             const char* a3 = a2 + kstep; const char* b3 = b2 + kstep;
;             PG8_LDB(B0, 0, 0); PG8_LDB(B1, 0, 1); PG8_SCHED; PG8_LDA(At, 0, 0); PG8_STAGE(PG8_SA(1, 1), a1 + hstepA, voffA);
;             PG8_WAIT_V(8); PG8_WAIT_L(0); PG8_BAR; PG8_MMA(0, 0, At, B0); PG8_MMA(0, 1, At, B1); PG8_BAR; PG8_SCHED;
;             PG8_LDA(At, 0, 1); PG8_STAGE(PG8_SB(0, 0), b2, voffB); PG8_STAGE(PG8_SB(0, 1), b2 + hstepB, voffB); PG8_STAGE(PG8_SA(0, 0), a2, voffA);
;             PG8_WAIT_V(8); PG8_WAIT_L(0); PG8_BAR; PG8_MMA(1, 0, At, B0); PG8_MMA(1, 1, At, B1); PG8_BAR; PG8_SCHED;
.LBB0_598:
	s_add_i32 vcc_lo, s20, 2
	s_add_u32 s90, s18, 0x80
	s_addc_u32 s21, s19, 0
	s_add_i32 s92, 0, 0x10000
	s_cmp_eq_u32 s43, s20
	s_cselect_b32 s21, s37, s21
	s_cselect_b32 s20, s36, s90
	s_cselect_b32 s91, s71, s87
	s_cselect_b32 s90, s70, s86
	s_add_i32 s93, 0, 0x14000
	s_add_i32 m0, s35, 0xc000
	s_nop 0
	global_load_lds_dwordx4 v138, s[18:19]
	s_add_i32 m0, s35, 0xe000
	s_nop 0
	global_load_lds_dwordx4 v140, s[18:19]
	ds_read_b128 v[142:145], v255
	ds_read_b128 v[150:153], v255 offset:1024
	ds_read_b128 v[154:157], v255 offset:2048
	ds_read_b128 v[158:161], v255 offset:3072
	ds_read_b128 v[162:165], v255 offset:16384
	ds_read_b128 v[166:169], v255 offset:17408
	ds_read_b128 v[170:173], v255 offset:18432
	ds_read_b128 v[190:193], v255 offset:19456
	ds_read_b128 v[194:197], v148
	ds_read_b128 v[198:201], v148 offset:1024
	ds_read_b128 v[202:205], v148 offset:2048
	ds_read_b128 v[206:209], v148 offset:3072
	ds_read_b128 v[218:221], v148 offset:4096
	ds_read_b128 v[222:225], v148 offset:5120
	ds_read_b128 v[226:229], v148 offset:6144
	ds_read_b128 v[230:233], v148 offset:7168
	s_waitcnt vmcnt(8)
	s_waitcnt lgkmcnt(0)
	s_barrier
	s_waitcnt lgkmcnt(0)
	v_mfma_f32_16x16x32_bf16 v[114:117], v[142:145], v[194:197], v[114:117]
	v_mfma_f32_16x16x32_bf16 v[118:121], v[154:157], v[194:197], v[118:121]
	v_mfma_f32_16x16x32_bf16 v[94:97], v[142:145], v[202:205], v[94:97]
	v_mfma_f32_16x16x32_bf16 v[98:101], v[154:157], v[202:205], v[98:101]
	v_mfma_f32_16x16x32_bf16 v[62:65], v[142:145], v[218:221], v[62:65]
	v_mfma_f32_16x16x32_bf16 v[66:69], v[154:157], v[218:221], v[66:69]
	v_mfma_f32_16x16x32_bf16 v[22:25], v[142:145], v[226:229], v[22:25]
	v_mfma_f32_16x16x32_bf16 v[34:37], v[154:157], v[226:229], v[34:37]
	v_mfma_f32_16x16x32_bf16 v[114:117], v[150:153], v[198:201], v[114:117]
	v_mfma_f32_16x16x32_bf16 v[118:121], v[158:161], v[198:201], v[118:121]
	v_mfma_f32_16x16x32_bf16 v[94:97], v[150:153], v[206:209], v[94:97]
	v_mfma_f32_16x16x32_bf16 v[98:101], v[158:161], v[206:209], v[98:101]
	v_mfma_f32_16x16x32_bf16 v[62:65], v[150:153], v[222:225], v[62:65]
	v_mfma_f32_16x16x32_bf16 v[66:69], v[158:161], v[222:225], v[66:69]
	v_mfma_f32_16x16x32_bf16 v[22:25], v[150:153], v[230:233], v[22:25]
	v_mfma_f32_16x16x32_bf16 v[34:37], v[158:161], v[230:233], v[34:37]
	v_mfma_f32_16x16x32_bf16 v[122:125], v[162:165], v[194:197], v[122:125]
	v_mfma_f32_16x16x32_bf16 v[126:129], v[170:173], v[194:197], v[126:129]
	v_mfma_f32_16x16x32_bf16 v[102:105], v[162:165], v[202:205], v[102:105]
	v_mfma_f32_16x16x32_bf16 v[106:109], v[170:173], v[202:205], v[106:109]
	v_mfma_f32_16x16x32_bf16 v[70:73], v[162:165], v[218:221], v[70:73]
	v_mfma_f32_16x16x32_bf16 v[78:81], v[170:173], v[218:221], v[78:81]
	v_mfma_f32_16x16x32_bf16 v[38:41], v[162:165], v[226:229], v[38:41]
	v_mfma_f32_16x16x32_bf16 v[46:49], v[170:173], v[226:229], v[46:49]
	v_mfma_f32_16x16x32_bf16 v[122:125], v[166:169], v[198:201], v[122:125]
	v_mfma_f32_16x16x32_bf16 v[126:129], v[190:193], v[198:201], v[126:129]
	v_mfma_f32_16x16x32_bf16 v[102:105], v[166:169], v[206:209], v[102:105]
	v_mfma_f32_16x16x32_bf16 v[106:109], v[190:193], v[206:209], v[106:109]
	v_mfma_f32_16x16x32_bf16 v[70:73], v[166:169], v[222:225], v[70:73]
	v_mfma_f32_16x16x32_bf16 v[78:81], v[190:193], v[222:225], v[78:81]
	v_mfma_f32_16x16x32_bf16 v[38:41], v[166:169], v[230:233], v[38:41]
	v_mfma_f32_16x16x32_bf16 v[46:49], v[190:193], v[230:233], v[46:49]
	s_barrier
	s_add_i32 s92, s92, s34
	s_add_u32 s98, s90, 0x80
	s_addc_u32 s99, s91, 0
	s_add_u32 s100, s20, 0x80
	s_addc_u32 s101, s21, 0
	s_mov_b32 m0, s92
	s_nop 0
	global_load_lds_dwordx4 v132, s[90:91]
	s_add_i32 m0, s92, 0x2000
	s_add_i32 s92, s93, s34
	global_load_lds_dwordx4 v136, s[90:91]
	s_add_u32 s90, s90, s29
	s_addc_u32 s91, s91, 0
	s_mov_b32 m0, s92
	s_nop 0
	global_load_lds_dwordx4 v132, s[90:91]
	s_add_i32 m0, s92, 0x2000
	s_nop 0
	global_load_lds_dwordx4 v136, s[90:91]
	s_mov_b32 m0, s35
	s_nop 0
	global_load_lds_dwordx4 v130, s[20:21]
	s_mov_b32 m0, s8
	s_nop 0
	global_load_lds_dwordx4 v134, s[20:21]
	ds_read_b128 v[194:197], v148 offset:16384
	ds_read_b128 v[198:201], v148 offset:17408
	ds_read_b128 v[202:205], v148 offset:18432
	ds_read_b128 v[206:209], v148 offset:19456
	ds_read_b128 v[218:221], v148 offset:20480
	ds_read_b128 v[222:225], v148 offset:21504
	ds_read_b128 v[226:229], v148 offset:22528
	ds_read_b128 v[230:233], v148 offset:23552
	s_waitcnt vmcnt(8)
	s_waitcnt lgkmcnt(0)
	s_barrier
	s_waitcnt lgkmcnt(0)
	v_mfma_f32_16x16x32_bf16 v[14:17], v[142:145], v[194:197], v[14:17]
	v_mfma_f32_16x16x32_bf16 v[26:29], v[154:157], v[194:197], v[26:29]
	v_mfma_f32_16x16x32_bf16 v[74:77], v[142:145], v[202:205], v[74:77]
	v_mfma_f32_16x16x32_bf16 v[82:85], v[154:157], v[202:205], v[82:85]
	v_mfma_f32_16x16x32_bf16 v[42:45], v[142:145], v[218:221], v[42:45]
	v_mfma_f32_16x16x32_bf16 v[50:53], v[154:157], v[218:221], v[50:53]
	v_mfma_f32_16x16x32_bf16 v[2:5], v[142:145], v[226:229], v[2:5]
	v_mfma_f32_16x16x32_bf16 v[6:9], v[154:157], v[226:229], v[6:9]
	v_mfma_f32_16x16x32_bf16 v[14:17], v[150:153], v[198:201], v[14:17]
	v_mfma_f32_16x16x32_bf16 v[26:29], v[158:161], v[198:201], v[26:29]
	v_mfma_f32_16x16x32_bf16 v[74:77], v[150:153], v[206:209], v[74:77]
	v_mfma_f32_16x16x32_bf16 v[82:85], v[158:161], v[206:209], v[82:85]
	v_mfma_f32_16x16x32_bf16 v[42:45], v[150:153], v[222:225], v[42:45]
	v_mfma_f32_16x16x32_bf16 v[50:53], v[158:161], v[222:225], v[50:53]
	v_mfma_f32_16x16x32_bf16 v[2:5], v[150:153], v[230:233], v[2:5]
	v_mfma_f32_16x16x32_bf16 v[6:9], v[158:161], v[230:233], v[6:9]
	v_mfma_f32_16x16x32_bf16 v[30:33], v[162:165], v[194:197], v[30:33]
	v_mfma_f32_16x16x32_bf16 v[110:113], v[170:173], v[194:197], v[110:113]
	v_mfma_f32_16x16x32_bf16 v[86:89], v[162:165], v[202:205], v[86:89]
	v_mfma_f32_16x16x32_bf16 v[90:93], v[170:173], v[202:205], v[90:93]
	v_mfma_f32_16x16x32_bf16 v[54:57], v[162:165], v[218:221], v[54:57]
	v_mfma_f32_16x16x32_bf16 v[58:61], v[170:173], v[218:221], v[58:61]
	v_mfma_f32_16x16x32_bf16 v[10:13], v[162:165], v[226:229], v[10:13]
	v_mfma_f32_16x16x32_bf16 v[18:21], v[170:173], v[226:229], v[18:21]
	v_mfma_f32_16x16x32_bf16 v[30:33], v[166:169], v[198:201], v[30:33]
	v_mfma_f32_16x16x32_bf16 v[110:113], v[190:193], v[198:201], v[110:113]
	v_mfma_f32_16x16x32_bf16 v[86:89], v[166:169], v[206:209], v[86:89]
	v_mfma_f32_16x16x32_bf16 v[90:93], v[190:193], v[206:209], v[90:93]
	v_mfma_f32_16x16x32_bf16 v[54:57], v[166:169], v[222:225], v[54:57]
	v_mfma_f32_16x16x32_bf16 v[58:61], v[190:193], v[222:225], v[58:61]
	v_mfma_f32_16x16x32_bf16 v[10:13], v[166:169], v[230:233], v[10:13]
	v_mfma_f32_16x16x32_bf16 v[18:21], v[190:193], v[230:233], v[18:21]
	s_barrier
; #define PG8_STAGE(bufoff, gbase, voff) do { _Pragma("unroll") for (int _i = 0; _i < 2; ++_i) \
;         __builtin_amdgcn_global_load_lds((const unsigned*)((const char*)(gbase) + (voff)[_i]), (LAS unsigned*)(lds + (bufoff) + ldsw + _i * 8192), 16, 0, 0); } while (0)
; #define PG8_LDA(dst, b, h) do { _Pragma("unroll") for (int m = 0; m < 4; ++m) _Pragma("unroll") for (int k = 0; k < 2; ++k) dst[m][k] = *(const LAS bf16x8*)(lds + PG8_SA(b, h) + aoff + m * 2048 + k * 1024); } while (0)
; #define PG8_LDB(dst, b, h) do { _Pragma("unroll") for (int n = 0; n < 2; ++n) _Pragma("unroll") for (int k = 0; k < 2; ++k) dst[n][k] = *(const LAS bf16x8*)(lds + PG8_SB(b, h) + boff + n * 2048 + k * 1024); } while (0)
; #define PG8_MMA(ai, bj, At, Bt) do { __builtin_amdgcn_s_setprio(1); _Pragma("unroll") for (int m = 0; m < 4; ++m) _Pragma("unroll") for (int n = 0; n < 2; ++n) _Pragma("unroll") for (int k = 0; k < 2; ++k) \
;         acc[ai][bj][m][n] = __builtin_amdgcn_mfma_f32_16x16x32_bf16(Bt[n][k], At[m][k], acc[ai][bj][m][n], 0, 0, 0); __builtin_amdgcn_s_setprio(0); } while (0)
; #define PG8_WAIT_V(n) asm volatile("s_waitcnt vmcnt(" #n ")" ::: "memory")
; #define PG8_WAIT_L(n) asm volatile("s_waitcnt lgkmcnt(" #n ")" ::: "memory")
; #define PG8_BAR __builtin_amdgcn_s_barrier()
; #define PG8_SCHED __builtin_amdgcn_sched_barrier(0)
; template <class Epi, class Sched>
; __device__ __forceinline__ void gemm_phase(LAS unsigned char* lds, const Gemm g, const Sched& S, const Epi& E) {
;     ...
;             PG8_LDB(B0, 1, 0); PG8_LDB(B1, 1, 1); PG8_SCHED; PG8_LDA(At, 1, 0); PG8_STAGE(PG8_SA(0, 1), a2 + hstepA, voffA);
;             PG8_WAIT_V(8); PG8_WAIT_L(0); PG8_BAR; PG8_MMA(0, 0, At, B0); PG8_MMA(0, 1, At, B1); PG8_BAR; PG8_SCHED;
;             PG8_LDA(At, 1, 1); PG8_STAGE(PG8_SB(1, 0), b3, voffB); PG8_STAGE(PG8_SB(1, 1), b3 + hstepB, voffB); PG8_STAGE(PG8_SA(1, 0), a3, voffA);
;             PG8_WAIT_V(8); PG8_WAIT_L(0); PG8_BAR; PG8_MMA(1, 0, At, B0); PG8_MMA(1, 1, At, B1); PG8_BAR; PG8_SCHED;
;         }
;         if (wr == 0) PG8_BAR;
	s_add_u32 s20, s20, s80
	s_addc_u32 s21, s21, 0
	s_mov_b32 m0, s9
	s_nop 0
	global_load_lds_dwordx4 v130, s[20:21]
	s_mov_b32 m0, s40
	s_nop 0
	global_load_lds_dwordx4 v134, s[20:21]
	ds_read_b128 v[142:145], v255 offset:32768
	ds_read_b128 v[150:153], v255 offset:33792
	ds_read_b128 v[154:157], v255 offset:34816
	ds_read_b128 v[158:161], v255 offset:35840
	ds_read_b128 v[162:165], v255 offset:49152
	ds_read_b128 v[166:169], v255 offset:50176
	ds_read_b128 v[170:173], v255 offset:51200
	ds_read_b128 v[190:193], v255 offset:52224
	ds_read_b128 v[194:197], v148 offset:32768
	ds_read_b128 v[198:201], v148 offset:33792
	ds_read_b128 v[202:205], v148 offset:34816
	ds_read_b128 v[206:209], v148 offset:35840
	ds_read_b128 v[218:221], v148 offset:36864
	ds_read_b128 v[222:225], v148 offset:37888
	ds_read_b128 v[226:229], v148 offset:38912
	ds_read_b128 v[230:233], v148 offset:39936
	s_waitcnt vmcnt(8)
	s_waitcnt lgkmcnt(0)
	s_barrier
	s_waitcnt lgkmcnt(0)
	v_mfma_f32_16x16x32_bf16 v[114:117], v[142:145], v[194:197], v[114:117]
	v_mfma_f32_16x16x32_bf16 v[118:121], v[154:157], v[194:197], v[118:121]
	v_mfma_f32_16x16x32_bf16 v[94:97], v[142:145], v[202:205], v[94:97]
	v_mfma_f32_16x16x32_bf16 v[98:101], v[154:157], v[202:205], v[98:101]
	v_mfma_f32_16x16x32_bf16 v[62:65], v[142:145], v[218:221], v[62:65]
	v_mfma_f32_16x16x32_bf16 v[66:69], v[154:157], v[218:221], v[66:69]
	v_mfma_f32_16x16x32_bf16 v[22:25], v[142:145], v[226:229], v[22:25]
	v_mfma_f32_16x16x32_bf16 v[34:37], v[154:157], v[226:229], v[34:37]
	v_mfma_f32_16x16x32_bf16 v[114:117], v[150:153], v[198:201], v[114:117]
	v_mfma_f32_16x16x32_bf16 v[118:121], v[158:161], v[198:201], v[118:121]
	v_mfma_f32_16x16x32_bf16 v[94:97], v[150:153], v[206:209], v[94:97]
	v_mfma_f32_16x16x32_bf16 v[98:101], v[158:161], v[206:209], v[98:101]
	v_mfma_f32_16x16x32_bf16 v[62:65], v[150:153], v[222:225], v[62:65]
	v_mfma_f32_16x16x32_bf16 v[66:69], v[158:161], v[222:225], v[66:69]
	v_mfma_f32_16x16x32_bf16 v[22:25], v[150:153], v[230:233], v[22:25]
	v_mfma_f32_16x16x32_bf16 v[34:37], v[158:161], v[230:233], v[34:37]
	v_mfma_f32_16x16x32_bf16 v[122:125], v[162:165], v[194:197], v[122:125]
	v_mfma_f32_16x16x32_bf16 v[126:129], v[170:173], v[194:197], v[126:129]
	v_mfma_f32_16x16x32_bf16 v[102:105], v[162:165], v[202:205], v[102:105]
	v_mfma_f32_16x16x32_bf16 v[106:109], v[170:173], v[202:205], v[106:109]
	v_mfma_f32_16x16x32_bf16 v[70:73], v[162:165], v[218:221], v[70:73]
	v_mfma_f32_16x16x32_bf16 v[78:81], v[170:173], v[218:221], v[78:81]
	v_mfma_f32_16x16x32_bf16 v[38:41], v[162:165], v[226:229], v[38:41]
	v_mfma_f32_16x16x32_bf16 v[46:49], v[170:173], v[226:229], v[46:49]
	v_mfma_f32_16x16x32_bf16 v[122:125], v[166:169], v[198:201], v[122:125]
	v_mfma_f32_16x16x32_bf16 v[126:129], v[190:193], v[198:201], v[126:129]
	v_mfma_f32_16x16x32_bf16 v[102:105], v[166:169], v[206:209], v[102:105]
	v_mfma_f32_16x16x32_bf16 v[106:109], v[190:193], v[206:209], v[106:109]
	v_mfma_f32_16x16x32_bf16 v[70:73], v[166:169], v[222:225], v[70:73]
	v_mfma_f32_16x16x32_bf16 v[78:81], v[190:193], v[222:225], v[78:81]
	v_mfma_f32_16x16x32_bf16 v[38:41], v[166:169], v[230:233], v[38:41]
	v_mfma_f32_16x16x32_bf16 v[46:49], v[190:193], v[230:233], v[46:49]
	s_barrier
	s_add_i32 s20, s34, 0x18000
	s_mov_b32 m0, s20
	s_nop 0
	global_load_lds_dwordx4 v132, s[98:99]
	s_add_i32 m0, s20, 0x2000
	s_add_i32 s20, s34, 0x1c000
	global_load_lds_dwordx4 v136, s[98:99]
	s_add_u32 s98, s98, s29
	s_addc_u32 s99, s99, 0
	s_mov_b32 m0, s20
	s_nop 0
	global_load_lds_dwordx4 v132, s[98:99]
	s_add_i32 m0, s20, 0x2000
	s_nop 0
	global_load_lds_dwordx4 v136, s[98:99]
	s_mov_b32 m0, s41
	s_nop 0
	global_load_lds_dwordx4 v130, s[100:101]
	s_mov_b32 m0, s42
	s_nop 0
	global_load_lds_dwordx4 v134, s[100:101]
	ds_read_b128 v[194:197], v148 offset:49152
	ds_read_b128 v[198:201], v148 offset:50176
	ds_read_b128 v[202:205], v148 offset:51200
	ds_read_b128 v[206:209], v148 offset:52224
	ds_read_b128 v[218:221], v148 offset:53248
	ds_read_b128 v[222:225], v148 offset:54272
	ds_read_b128 v[226:229], v148 offset:55296
	ds_read_b128 v[230:233], v148 offset:56320
	s_waitcnt vmcnt(8)
	s_waitcnt lgkmcnt(0)
	s_barrier
	s_waitcnt lgkmcnt(0)
	v_mfma_f32_16x16x32_bf16 v[14:17], v[142:145], v[194:197], v[14:17]
	v_mfma_f32_16x16x32_bf16 v[26:29], v[154:157], v[194:197], v[26:29]
	v_mfma_f32_16x16x32_bf16 v[74:77], v[142:145], v[202:205], v[74:77]
	v_mfma_f32_16x16x32_bf16 v[82:85], v[154:157], v[202:205], v[82:85]
	v_mfma_f32_16x16x32_bf16 v[42:45], v[142:145], v[218:221], v[42:45]
	v_mfma_f32_16x16x32_bf16 v[50:53], v[154:157], v[218:221], v[50:53]
	v_mfma_f32_16x16x32_bf16 v[2:5], v[142:145], v[226:229], v[2:5]
	v_mfma_f32_16x16x32_bf16 v[6:9], v[154:157], v[226:229], v[6:9]
	v_mfma_f32_16x16x32_bf16 v[14:17], v[150:153], v[198:201], v[14:17]
	v_mfma_f32_16x16x32_bf16 v[26:29], v[158:161], v[198:201], v[26:29]
	v_mfma_f32_16x16x32_bf16 v[74:77], v[150:153], v[206:209], v[74:77]
	v_mfma_f32_16x16x32_bf16 v[82:85], v[158:161], v[206:209], v[82:85]
	v_mfma_f32_16x16x32_bf16 v[42:45], v[150:153], v[222:225], v[42:45]
	v_mfma_f32_16x16x32_bf16 v[50:53], v[158:161], v[222:225], v[50:53]
	v_mfma_f32_16x16x32_bf16 v[2:5], v[150:153], v[230:233], v[2:5]
	v_mfma_f32_16x16x32_bf16 v[6:9], v[158:161], v[230:233], v[6:9]
	v_mfma_f32_16x16x32_bf16 v[30:33], v[162:165], v[194:197], v[30:33]
	v_mfma_f32_16x16x32_bf16 v[110:113], v[170:173], v[194:197], v[110:113]
	v_mfma_f32_16x16x32_bf16 v[86:89], v[162:165], v[202:205], v[86:89]
	v_mfma_f32_16x16x32_bf16 v[90:93], v[170:173], v[202:205], v[90:93]
	v_mfma_f32_16x16x32_bf16 v[54:57], v[162:165], v[218:221], v[54:57]
	v_mfma_f32_16x16x32_bf16 v[58:61], v[170:173], v[218:221], v[58:61]
	v_mfma_f32_16x16x32_bf16 v[10:13], v[162:165], v[226:229], v[10:13]
	v_mfma_f32_16x16x32_bf16 v[18:21], v[170:173], v[226:229], v[18:21]
	v_mfma_f32_16x16x32_bf16 v[30:33], v[166:169], v[198:201], v[30:33]
	v_mfma_f32_16x16x32_bf16 v[110:113], v[190:193], v[198:201], v[110:113]
	v_mfma_f32_16x16x32_bf16 v[86:89], v[166:169], v[206:209], v[86:89]
	v_mfma_f32_16x16x32_bf16 v[90:93], v[190:193], v[206:209], v[90:93]
	v_mfma_f32_16x16x32_bf16 v[54:57], v[166:169], v[222:225], v[54:57]
	v_mfma_f32_16x16x32_bf16 v[58:61], v[190:193], v[222:225], v[58:61]
	v_mfma_f32_16x16x32_bf16 v[10:13], v[166:169], v[230:233], v[10:13]
	v_mfma_f32_16x16x32_bf16 v[18:21], v[190:193], v[230:233], v[18:21]
	s_add_u32 s18, s18, 0x100
	s_addc_u32 s19, s19, 0
	s_add_u32 s86, s86, 0x100
	s_addc_u32 s87, s87, 0
	s_cmp_ge_u32 vcc_lo, s48
	s_mov_b32 s20, vcc_lo
	s_barrier
	s_cbranch_scc0 .LBB0_598
	s_and_b64 vcc, exec, s[84:85]
	s_cbranch_vccz .LBB0_601
	s_barrier

; #define PG8_STAGE(bufoff, gbase, voff) do { _Pragma("unroll") for (int _i = 0; _i < 2; ++_i) \
;         __builtin_amdgcn_global_load_lds((const unsigned*)((const char*)(gbase) + (voff)[_i]), (LAS unsigned*)(lds + (bufoff) + ldsw + _i * 8192), 16, 0, 0); } while (0)
; #define PG8_LDA(dst, b, h) do { _Pragma("unroll") for (int m = 0; m < 4; ++m) _Pragma("unroll") for (int k = 0; k < 2; ++k) dst[m][k] = *(const LAS bf16x8*)(lds + PG8_SA(b, h) + aoff + m * 2048 + k * 1024); } while (0)
; #define PG8_LDB(dst, b, h) do { _Pragma("unroll") for (int n = 0; n < 2; ++n) _Pragma("unroll") for (int k = 0; k < 2; ++k) dst[n][k] = *(const LAS bf16x8*)(lds + PG8_SB(b, h) + boff + n * 2048 + k * 1024); } while (0)
; #define PG8_MMA(ai, bj, At, Bt) do { __builtin_amdgcn_s_setprio(1); _Pragma("unroll") for (int m = 0; m < 4; ++m) _Pragma("unroll") for (int n = 0; n < 2; ++n) _Pragma("unroll") for (int k = 0; k < 2; ++k) \
;         acc[ai][bj][m][n] = __builtin_amdgcn_mfma_f32_16x16x32_bf16(Bt[n][k], At[m][k], acc[ai][bj][m][n], 0, 0, 0); __builtin_amdgcn_s_setprio(0); } while (0)
; #define PG8_WAIT_V(n) asm volatile("s_waitcnt vmcnt(" #n ")" ::: "memory")
; #define PG8_WAIT_L(n) asm volatile("s_waitcnt lgkmcnt(" #n ")" ::: "memory")
; #define PG8_BAR __builtin_amdgcn_s_barrier()
; #define PG8_SCHED __builtin_amdgcn_sched_barrier(0)
; template <class Epi, class Sched>
; __device__ __forceinline__ void gemm_phase(LAS unsigned char* lds, const Gemm g, const Sched& S, const Epi& E) {
;     ...
;         for (int t = 0; t < nt; t += 2) {
;             const bool last = (t == nt - 2);
;             const char* a1 = cA + (size_t)(t + 1) * kstep;
;             const char* a2 = last ? nA : cA + (size_t)(t + 2) * kstep; const char* b2 = last ? nB : cB + (size_t)(t + 2) * kstep;
;             const char* a3 = a2 + kstep; const char* b3 = b2 + kstep;
;             PG8_LDB(B0, 0, 0); PG8_LDB(B1, 0, 1); PG8_SCHED; PG8_LDA(At, 0, 0); PG8_STAGE(PG8_SA(1, 1), a1 + hstepA, voffA);
;             PG8_WAIT_V(8); PG8_WAIT_L(0); PG8_BAR; PG8_MMA(0, 0, At, B0); PG8_MMA(0, 1, At, B1); PG8_BAR; PG8_SCHED;
;             PG8_LDA(At, 0, 1); PG8_STAGE(PG8_SB(0, 0), b2, voffB); PG8_STAGE(PG8_SB(0, 1), b2 + hstepB, voffB); PG8_STAGE(PG8_SA(0, 0), a2, voffA);
;             PG8_WAIT_V(8); PG8_WAIT_L(0); PG8_BAR; PG8_MMA(1, 0, At, B0); PG8_MMA(1, 1, At, B1); PG8_BAR; PG8_SCHED;
.LBB0_640:
	s_add_i32 s87, s20, 2
	s_add_u32 s88, s18, 0x80
	s_addc_u32 s21, s19, 0
	s_add_i32 s90, 0, 0x10000
	s_cmp_eq_u32 s43, s20
	s_cselect_b32 s21, s69, s21
	s_cselect_b32 s20, s68, s88
	s_cselect_b32 s89, s81, s83
	s_cselect_b32 s88, s80, s82
	s_add_i32 s91, 0, 0x14000
	s_add_i32 m0, s30, 0xc000
	s_nop 0
	global_load_lds_dwordx4 v138, s[18:19]
	s_add_i32 m0, s30, 0xe000
	s_nop 0
	global_load_lds_dwordx4 v140, s[18:19]
	ds_read_b128 v[146:149], v255
	ds_read_b128 v[150:153], v255 offset:1024
	ds_read_b128 v[154:157], v255 offset:2048
	ds_read_b128 v[158:161], v255 offset:3072
	ds_read_b128 v[162:165], v255 offset:16384
	ds_read_b128 v[166:169], v255 offset:17408
	ds_read_b128 v[170:173], v255 offset:18432
	ds_read_b128 v[190:193], v255 offset:19456
	ds_read_b128 v[194:197], v144
	ds_read_b128 v[198:201], v144 offset:1024
	ds_read_b128 v[202:205], v144 offset:2048
	ds_read_b128 v[206:209], v144 offset:3072
	ds_read_b128 v[218:221], v144 offset:4096
	ds_read_b128 v[222:225], v144 offset:5120
	ds_read_b128 v[226:229], v144 offset:6144
	ds_read_b128 v[230:233], v144 offset:7168
	s_waitcnt vmcnt(8)
	s_waitcnt lgkmcnt(0)
	s_barrier
	s_waitcnt lgkmcnt(0)
	v_mfma_f32_16x16x32_bf16 v[2:5], v[146:149], v[194:197], v[2:5]
	v_mfma_f32_16x16x32_bf16 v[6:9], v[154:157], v[194:197], v[6:9]
	v_mfma_f32_16x16x32_bf16 v[10:13], v[146:149], v[202:205], v[10:13]
	v_mfma_f32_16x16x32_bf16 v[14:17], v[154:157], v[202:205], v[14:17]
	v_mfma_f32_16x16x32_bf16 v[26:29], v[146:149], v[218:221], v[26:29]
	v_mfma_f32_16x16x32_bf16 v[30:33], v[154:157], v[218:221], v[30:33]
	v_mfma_f32_16x16x32_bf16 v[42:45], v[146:149], v[226:229], v[42:45]
	v_mfma_f32_16x16x32_bf16 v[46:49], v[154:157], v[226:229], v[46:49]
	v_mfma_f32_16x16x32_bf16 v[2:5], v[150:153], v[198:201], v[2:5]
	v_mfma_f32_16x16x32_bf16 v[6:9], v[158:161], v[198:201], v[6:9]
	v_mfma_f32_16x16x32_bf16 v[10:13], v[150:153], v[206:209], v[10:13]
	v_mfma_f32_16x16x32_bf16 v[14:17], v[158:161], v[206:209], v[14:17]
	v_mfma_f32_16x16x32_bf16 v[26:29], v[150:153], v[222:225], v[26:29]
	v_mfma_f32_16x16x32_bf16 v[30:33], v[158:161], v[222:225], v[30:33]
	v_mfma_f32_16x16x32_bf16 v[42:45], v[150:153], v[230:233], v[42:45]
	v_mfma_f32_16x16x32_bf16 v[46:49], v[158:161], v[230:233], v[46:49]
	v_mfma_f32_16x16x32_bf16 v[18:21], v[162:165], v[194:197], v[18:21]
	v_mfma_f32_16x16x32_bf16 v[22:25], v[170:173], v[194:197], v[22:25]
	v_mfma_f32_16x16x32_bf16 v[34:37], v[162:165], v[202:205], v[34:37]
	v_mfma_f32_16x16x32_bf16 v[38:41], v[170:173], v[202:205], v[38:41]
	v_mfma_f32_16x16x32_bf16 v[50:53], v[162:165], v[218:221], v[50:53]
	v_mfma_f32_16x16x32_bf16 v[54:57], v[170:173], v[218:221], v[54:57]
	v_mfma_f32_16x16x32_bf16 v[58:61], v[162:165], v[226:229], v[58:61]
	v_mfma_f32_16x16x32_bf16 v[66:69], v[170:173], v[226:229], v[66:69]
	v_mfma_f32_16x16x32_bf16 v[18:21], v[166:169], v[198:201], v[18:21]
	v_mfma_f32_16x16x32_bf16 v[22:25], v[190:193], v[198:201], v[22:25]
	v_mfma_f32_16x16x32_bf16 v[34:37], v[166:169], v[206:209], v[34:37]
	v_mfma_f32_16x16x32_bf16 v[38:41], v[190:193], v[206:209], v[38:41]
	v_mfma_f32_16x16x32_bf16 v[50:53], v[166:169], v[222:225], v[50:53]
	v_mfma_f32_16x16x32_bf16 v[54:57], v[190:193], v[222:225], v[54:57]
	v_mfma_f32_16x16x32_bf16 v[58:61], v[166:169], v[230:233], v[58:61]
	v_mfma_f32_16x16x32_bf16 v[66:69], v[190:193], v[230:233], v[66:69]
	s_barrier
	s_add_i32 s90, s90, s29
	s_add_u32 s98, s88, 0x80
	s_addc_u32 s99, s89, 0
	s_add_u32 s100, s20, 0x80
	s_addc_u32 s101, s21, 0
	s_mov_b32 m0, s90
	s_nop 0
	global_load_lds_dwordx4 v132, s[88:89]
	s_add_i32 m0, s90, 0x2000
	s_add_i32 s90, s91, s29
	global_load_lds_dwordx4 v136, s[88:89]
	s_add_u32 s88, s88, s8
	s_addc_u32 s89, s89, 0
	s_mov_b32 m0, s90
	s_nop 0
	global_load_lds_dwordx4 v132, s[88:89]
	s_add_i32 m0, s90, 0x2000
	s_nop 0
	global_load_lds_dwordx4 v136, s[88:89]
	s_mov_b32 m0, s30
	s_nop 0
	global_load_lds_dwordx4 v130, s[20:21]
	s_mov_b32 m0, s31
	s_nop 0
	global_load_lds_dwordx4 v134, s[20:21]
	ds_read_b128 v[194:197], v144 offset:16384
	ds_read_b128 v[198:201], v144 offset:17408
	ds_read_b128 v[202:205], v144 offset:18432
	ds_read_b128 v[206:209], v144 offset:19456
	ds_read_b128 v[218:221], v144 offset:20480
	ds_read_b128 v[222:225], v144 offset:21504
	ds_read_b128 v[226:229], v144 offset:22528
	ds_read_b128 v[230:233], v144 offset:23552
	s_waitcnt vmcnt(8)
	s_waitcnt lgkmcnt(0)
	s_barrier
	s_waitcnt lgkmcnt(0)
	v_mfma_f32_16x16x32_bf16 v[62:65], v[146:149], v[194:197], v[62:65]
	v_mfma_f32_16x16x32_bf16 v[70:73], v[154:157], v[194:197], v[70:73]
	v_mfma_f32_16x16x32_bf16 v[78:81], v[146:149], v[202:205], v[78:81]
	v_mfma_f32_16x16x32_bf16 v[82:85], v[154:157], v[202:205], v[82:85]
	v_mfma_f32_16x16x32_bf16 v[90:93], v[146:149], v[218:221], v[90:93]
	v_mfma_f32_16x16x32_bf16 v[94:97], v[154:157], v[218:221], v[94:97]
	v_mfma_f32_16x16x32_bf16 v[106:109], v[146:149], v[226:229], v[106:109]
	v_mfma_f32_16x16x32_bf16 v[110:113], v[154:157], v[226:229], v[110:113]
	v_mfma_f32_16x16x32_bf16 v[62:65], v[150:153], v[198:201], v[62:65]
	v_mfma_f32_16x16x32_bf16 v[70:73], v[158:161], v[198:201], v[70:73]
	v_mfma_f32_16x16x32_bf16 v[78:81], v[150:153], v[206:209], v[78:81]
	v_mfma_f32_16x16x32_bf16 v[82:85], v[158:161], v[206:209], v[82:85]
	v_mfma_f32_16x16x32_bf16 v[90:93], v[150:153], v[222:225], v[90:93]
	v_mfma_f32_16x16x32_bf16 v[94:97], v[158:161], v[222:225], v[94:97]
	v_mfma_f32_16x16x32_bf16 v[106:109], v[150:153], v[230:233], v[106:109]
	v_mfma_f32_16x16x32_bf16 v[110:113], v[158:161], v[230:233], v[110:113]
	v_mfma_f32_16x16x32_bf16 v[74:77], v[162:165], v[194:197], v[74:77]
	v_mfma_f32_16x16x32_bf16 v[86:89], v[170:173], v[194:197], v[86:89]
	v_mfma_f32_16x16x32_bf16 v[98:101], v[162:165], v[202:205], v[98:101]
	v_mfma_f32_16x16x32_bf16 v[102:105], v[170:173], v[202:205], v[102:105]
	v_mfma_f32_16x16x32_bf16 v[114:117], v[162:165], v[218:221], v[114:117]
	v_mfma_f32_16x16x32_bf16 v[118:121], v[170:173], v[218:221], v[118:121]
	v_mfma_f32_16x16x32_bf16 v[122:125], v[162:165], v[226:229], v[122:125]
	v_mfma_f32_16x16x32_bf16 v[126:129], v[170:173], v[226:229], v[126:129]
	v_mfma_f32_16x16x32_bf16 v[74:77], v[166:169], v[198:201], v[74:77]
	v_mfma_f32_16x16x32_bf16 v[86:89], v[190:193], v[198:201], v[86:89]
	v_mfma_f32_16x16x32_bf16 v[98:101], v[166:169], v[206:209], v[98:101]
	v_mfma_f32_16x16x32_bf16 v[102:105], v[190:193], v[206:209], v[102:105]
	v_mfma_f32_16x16x32_bf16 v[114:117], v[166:169], v[222:225], v[114:117]
	v_mfma_f32_16x16x32_bf16 v[118:121], v[190:193], v[222:225], v[118:121]
	v_mfma_f32_16x16x32_bf16 v[122:125], v[166:169], v[230:233], v[122:125]
	v_mfma_f32_16x16x32_bf16 v[126:129], v[190:193], v[230:233], v[126:129]
	s_barrier
; #define PG8_STAGE(bufoff, gbase, voff) do { _Pragma("unroll") for (int _i = 0; _i < 2; ++_i) \
;         __builtin_amdgcn_global_load_lds((const unsigned*)((const char*)(gbase) + (voff)[_i]), (LAS unsigned*)(lds + (bufoff) + ldsw + _i * 8192), 16, 0, 0); } while (0)
; #define PG8_LDA(dst, b, h) do { _Pragma("unroll") for (int m = 0; m < 4; ++m) _Pragma("unroll") for (int k = 0; k < 2; ++k) dst[m][k] = *(const LAS bf16x8*)(lds + PG8_SA(b, h) + aoff + m * 2048 + k * 1024); } while (0)
; #define PG8_LDB(dst, b, h) do { _Pragma("unroll") for (int n = 0; n < 2; ++n) _Pragma("unroll") for (int k = 0; k < 2; ++k) dst[n][k] = *(const LAS bf16x8*)(lds + PG8_SB(b, h) + boff + n * 2048 + k * 1024); } while (0)
; #define PG8_MMA(ai, bj, At, Bt) do { __builtin_amdgcn_s_setprio(1); _Pragma("unroll") for (int m = 0; m < 4; ++m) _Pragma("unroll") for (int n = 0; n < 2; ++n) _Pragma("unroll") for (int k = 0; k < 2; ++k) \
;         acc[ai][bj][m][n] = __builtin_amdgcn_mfma_f32_16x16x32_bf16(Bt[n][k], At[m][k], acc[ai][bj][m][n], 0, 0, 0); __builtin_amdgcn_s_setprio(0); } while (0)
; #define PG8_WAIT_V(n) asm volatile("s_waitcnt vmcnt(" #n ")" ::: "memory")
; #define PG8_WAIT_L(n) asm volatile("s_waitcnt lgkmcnt(" #n ")" ::: "memory")
; #define PG8_BAR __builtin_amdgcn_s_barrier()
; #define PG8_SCHED __builtin_amdgcn_sched_barrier(0)
; template <class Epi, class Sched>
; __device__ __forceinline__ void gemm_phase(LAS unsigned char* lds, const Gemm g, const Sched& S, const Epi& E) {
;     ...
;             PG8_LDB(B0, 1, 0); PG8_LDB(B1, 1, 1); PG8_SCHED; PG8_LDA(At, 1, 0); PG8_STAGE(PG8_SA(0, 1), a2 + hstepA, voffA);
;             PG8_WAIT_V(8); PG8_WAIT_L(0); PG8_BAR; PG8_MMA(0, 0, At, B0); PG8_MMA(0, 1, At, B1); PG8_BAR; PG8_SCHED;
;             PG8_LDA(At, 1, 1); PG8_STAGE(PG8_SB(1, 0), b3, voffB); PG8_STAGE(PG8_SB(1, 1), b3 + hstepB, voffB); PG8_STAGE(PG8_SA(1, 0), a3, voffA);
;             PG8_WAIT_V(8); PG8_WAIT_L(0); PG8_BAR; PG8_MMA(1, 0, At, B0); PG8_MMA(1, 1, At, B1); PG8_BAR; PG8_SCHED;
;         }
;         if (wr == 0) PG8_BAR;
	s_add_u32 s20, s20, s54
	s_addc_u32 s21, s21, 0
	s_mov_b32 m0, s34
	s_nop 0
	global_load_lds_dwordx4 v130, s[20:21]
	s_mov_b32 m0, s35
	s_nop 0
	global_load_lds_dwordx4 v134, s[20:21]
	ds_read_b128 v[146:149], v255 offset:32768
	ds_read_b128 v[150:153], v255 offset:33792
	ds_read_b128 v[154:157], v255 offset:34816
	ds_read_b128 v[158:161], v255 offset:35840
	ds_read_b128 v[162:165], v255 offset:49152
	ds_read_b128 v[166:169], v255 offset:50176
	ds_read_b128 v[170:173], v255 offset:51200
	ds_read_b128 v[190:193], v255 offset:52224
	ds_read_b128 v[194:197], v144 offset:32768
	ds_read_b128 v[198:201], v144 offset:33792
	ds_read_b128 v[202:205], v144 offset:34816
	ds_read_b128 v[206:209], v144 offset:35840
	ds_read_b128 v[218:221], v144 offset:36864
	ds_read_b128 v[222:225], v144 offset:37888
	ds_read_b128 v[226:229], v144 offset:38912
	ds_read_b128 v[230:233], v144 offset:39936
	s_waitcnt vmcnt(8)
	s_waitcnt lgkmcnt(0)
	s_barrier
	s_waitcnt lgkmcnt(0)
	v_mfma_f32_16x16x32_bf16 v[2:5], v[146:149], v[194:197], v[2:5]
	v_mfma_f32_16x16x32_bf16 v[6:9], v[154:157], v[194:197], v[6:9]
	v_mfma_f32_16x16x32_bf16 v[10:13], v[146:149], v[202:205], v[10:13]
	v_mfma_f32_16x16x32_bf16 v[14:17], v[154:157], v[202:205], v[14:17]
	v_mfma_f32_16x16x32_bf16 v[26:29], v[146:149], v[218:221], v[26:29]
	v_mfma_f32_16x16x32_bf16 v[30:33], v[154:157], v[218:221], v[30:33]
	v_mfma_f32_16x16x32_bf16 v[42:45], v[146:149], v[226:229], v[42:45]
	v_mfma_f32_16x16x32_bf16 v[46:49], v[154:157], v[226:229], v[46:49]
	v_mfma_f32_16x16x32_bf16 v[2:5], v[150:153], v[198:201], v[2:5]
	v_mfma_f32_16x16x32_bf16 v[6:9], v[158:161], v[198:201], v[6:9]
	v_mfma_f32_16x16x32_bf16 v[10:13], v[150:153], v[206:209], v[10:13]
	v_mfma_f32_16x16x32_bf16 v[14:17], v[158:161], v[206:209], v[14:17]
	v_mfma_f32_16x16x32_bf16 v[26:29], v[150:153], v[222:225], v[26:29]
	v_mfma_f32_16x16x32_bf16 v[30:33], v[158:161], v[222:225], v[30:33]
	v_mfma_f32_16x16x32_bf16 v[42:45], v[150:153], v[230:233], v[42:45]
	v_mfma_f32_16x16x32_bf16 v[46:49], v[158:161], v[230:233], v[46:49]
	v_mfma_f32_16x16x32_bf16 v[18:21], v[162:165], v[194:197], v[18:21]
	v_mfma_f32_16x16x32_bf16 v[22:25], v[170:173], v[194:197], v[22:25]
	v_mfma_f32_16x16x32_bf16 v[34:37], v[162:165], v[202:205], v[34:37]
	v_mfma_f32_16x16x32_bf16 v[38:41], v[170:173], v[202:205], v[38:41]
	v_mfma_f32_16x16x32_bf16 v[50:53], v[162:165], v[218:221], v[50:53]
	v_mfma_f32_16x16x32_bf16 v[54:57], v[170:173], v[218:221], v[54:57]
	v_mfma_f32_16x16x32_bf16 v[58:61], v[162:165], v[226:229], v[58:61]
	v_mfma_f32_16x16x32_bf16 v[66:69], v[170:173], v[226:229], v[66:69]
	v_mfma_f32_16x16x32_bf16 v[18:21], v[166:169], v[198:201], v[18:21]
	v_mfma_f32_16x16x32_bf16 v[22:25], v[190:193], v[198:201], v[22:25]
	v_mfma_f32_16x16x32_bf16 v[34:37], v[166:169], v[206:209], v[34:37]
	v_mfma_f32_16x16x32_bf16 v[38:41], v[190:193], v[206:209], v[38:41]
	v_mfma_f32_16x16x32_bf16 v[50:53], v[166:169], v[222:225], v[50:53]
	v_mfma_f32_16x16x32_bf16 v[54:57], v[190:193], v[222:225], v[54:57]
	v_mfma_f32_16x16x32_bf16 v[58:61], v[166:169], v[230:233], v[58:61]
	v_mfma_f32_16x16x32_bf16 v[66:69], v[190:193], v[230:233], v[66:69]
	s_barrier
	s_add_i32 s20, s29, 0x18000
	s_mov_b32 m0, s20
	s_nop 0
	global_load_lds_dwordx4 v132, s[98:99]
	s_add_i32 m0, s20, 0x2000
	s_add_i32 s20, s29, 0x1c000
	global_load_lds_dwordx4 v136, s[98:99]
	s_add_u32 s98, s98, s8
	s_addc_u32 s99, s99, 0
	s_mov_b32 m0, s20
	s_nop 0
	global_load_lds_dwordx4 v132, s[98:99]
	s_add_i32 m0, s20, 0x2000
	s_nop 0
	global_load_lds_dwordx4 v136, s[98:99]
	s_mov_b32 m0, s40
	s_nop 0
	global_load_lds_dwordx4 v130, s[100:101]
	s_mov_b32 m0, s41
	s_nop 0
	global_load_lds_dwordx4 v134, s[100:101]
	ds_read_b128 v[194:197], v144 offset:49152
	ds_read_b128 v[198:201], v144 offset:50176
	ds_read_b128 v[202:205], v144 offset:51200
	ds_read_b128 v[206:209], v144 offset:52224
	ds_read_b128 v[218:221], v144 offset:53248
	ds_read_b128 v[222:225], v144 offset:54272
	ds_read_b128 v[226:229], v144 offset:55296
	ds_read_b128 v[230:233], v144 offset:56320
	s_waitcnt vmcnt(8)
	s_waitcnt lgkmcnt(0)
	s_barrier
	s_waitcnt lgkmcnt(0)
	v_mfma_f32_16x16x32_bf16 v[62:65], v[146:149], v[194:197], v[62:65]
	v_mfma_f32_16x16x32_bf16 v[70:73], v[154:157], v[194:197], v[70:73]
	v_mfma_f32_16x16x32_bf16 v[78:81], v[146:149], v[202:205], v[78:81]
	v_mfma_f32_16x16x32_bf16 v[82:85], v[154:157], v[202:205], v[82:85]
	v_mfma_f32_16x16x32_bf16 v[90:93], v[146:149], v[218:221], v[90:93]
	v_mfma_f32_16x16x32_bf16 v[94:97], v[154:157], v[218:221], v[94:97]
	v_mfma_f32_16x16x32_bf16 v[106:109], v[146:149], v[226:229], v[106:109]
	v_mfma_f32_16x16x32_bf16 v[110:113], v[154:157], v[226:229], v[110:113]
	v_mfma_f32_16x16x32_bf16 v[62:65], v[150:153], v[198:201], v[62:65]
	v_mfma_f32_16x16x32_bf16 v[70:73], v[158:161], v[198:201], v[70:73]
	v_mfma_f32_16x16x32_bf16 v[78:81], v[150:153], v[206:209], v[78:81]
	v_mfma_f32_16x16x32_bf16 v[82:85], v[158:161], v[206:209], v[82:85]
	v_mfma_f32_16x16x32_bf16 v[90:93], v[150:153], v[222:225], v[90:93]
	v_mfma_f32_16x16x32_bf16 v[94:97], v[158:161], v[222:225], v[94:97]
	v_mfma_f32_16x16x32_bf16 v[106:109], v[150:153], v[230:233], v[106:109]
	v_mfma_f32_16x16x32_bf16 v[110:113], v[158:161], v[230:233], v[110:113]
	v_mfma_f32_16x16x32_bf16 v[74:77], v[162:165], v[194:197], v[74:77]
	v_mfma_f32_16x16x32_bf16 v[86:89], v[170:173], v[194:197], v[86:89]
	v_mfma_f32_16x16x32_bf16 v[98:101], v[162:165], v[202:205], v[98:101]
	v_mfma_f32_16x16x32_bf16 v[102:105], v[170:173], v[202:205], v[102:105]
	v_mfma_f32_16x16x32_bf16 v[114:117], v[162:165], v[218:221], v[114:117]
	v_mfma_f32_16x16x32_bf16 v[118:121], v[170:173], v[218:221], v[118:121]
	v_mfma_f32_16x16x32_bf16 v[122:125], v[162:165], v[226:229], v[122:125]
	v_mfma_f32_16x16x32_bf16 v[126:129], v[170:173], v[226:229], v[126:129]
	v_mfma_f32_16x16x32_bf16 v[74:77], v[166:169], v[198:201], v[74:77]
	v_mfma_f32_16x16x32_bf16 v[86:89], v[190:193], v[198:201], v[86:89]
	v_mfma_f32_16x16x32_bf16 v[98:101], v[166:169], v[206:209], v[98:101]
	v_mfma_f32_16x16x32_bf16 v[102:105], v[190:193], v[206:209], v[102:105]
	v_mfma_f32_16x16x32_bf16 v[114:117], v[166:169], v[222:225], v[114:117]
	v_mfma_f32_16x16x32_bf16 v[118:121], v[190:193], v[222:225], v[118:121]
	v_mfma_f32_16x16x32_bf16 v[122:125], v[166:169], v[230:233], v[122:125]
	v_mfma_f32_16x16x32_bf16 v[126:129], v[190:193], v[230:233], v[126:129]
	s_add_u32 s18, s18, 0x100
	s_addc_u32 s19, s19, 0
	s_add_u32 s82, s82, 0x100
	s_addc_u32 s83, s83, 0
	s_cmp_ge_u32 s87, s42
	s_mov_b32 s20, s87
	s_barrier
	s_cbranch_scc0 .LBB0_640
	s_and_b64 vcc, exec, s[70:71]
	s_cbranch_vccz .LBB0_643
	s_barrier
